# removed 40 redundant back-to-back s_setprio 0 / s_setprio 1 pairs between the two 16-MFMA halves of each GEMM MFMA block (fewer issue slots between MFMAs)
# baseline (speedup 1.0000x reference)
; #define G_STAGE(bufoff, gbase, voff) do { _Pragma("unroll") for (int _i = 0; _i < 2; ++_i) \
;         __builtin_amdgcn_global_load_lds((const unsigned*)((const char*)(gbase) + (voff)[_i]), (LAS unsigned*)(lds + (bufoff) + ldsw + _i * 8192), 16, 0, 0); } while (0)
; #define G_LDA(dst, b, h) do { _Pragma("unroll") for (int m = 0; m < 4; ++m) _Pragma("unroll") for (int k = 0; k < 2; ++k) dst[m][k] = *(const LAS bf16x8*)(lds + G_SA(b, h) + aoff + m * 2048 + k * 1024); } while (0)
; #define G_LDB(dst, b, h) do { _Pragma("unroll") for (int n = 0; n < 2; ++n) _Pragma("unroll") for (int k = 0; k < 2; ++k) dst[n][k] = *(const LAS bf16x8*)(lds + G_SB(b, h) + boff + n * 2048 + k * 1024); } while (0)
; #define G_MMA(ai, bj, At, Bt_) do { __builtin_amdgcn_s_setprio(1); _Pragma("unroll") for (int m = 0; m < 4; ++m) _Pragma("unroll") for (int n = 0; n < 2; ++n) _Pragma("unroll") for (int k = 0; k < 2; ++k) \
;         acc[ai][bj][m][n] = __builtin_amdgcn_mfma_f32_16x16x32_bf16(Bt_[n][k], At[m][k], acc[ai][bj][m][n], 0, 0, 0); __builtin_amdgcn_s_setprio(0); } while (0)
; #define G_WAIT_V(n) asm volatile("s_waitcnt vmcnt(" #n ")" ::: "memory")
; template <int NSTORE, class TF, class F>
; DEVI void gemm_run(const bf16_t* __restrict__ A, int lda, const bf16_t* __restrict__ Bt, int ldb, int K, bf16_t* shm, TF&& tile, F&& emit) {
;     ...
;     for (;;) {
;         const bool has_next = tile(ui + 1, nrow, ncol);
;         const char* nA = has_next ? (const char*)A + (size_t)nrow * lda * 2 : cA; const char* nB = has_next ? (const char*)Bt + (size_t)ncol * ldb * 2 : cB;
;         for (int t = 0; t < nt; t += 2) {
;             const bool last = (t == nt - 2);
;             const char* a1 = cA + (size_t)(t + 1) * kstep;
;             const char* a2 = last ? nA : cA + (size_t)(t + 2) * kstep; const char* b2 = last ? nB : cB + (size_t)(t + 2) * kstep;
;             const char* a3 = a2 + kstep; const char* b3 = b2 + kstep;
;             G_LDB(B0, 0, 0); G_LDB(B1, 0, 1); G_SCHED; G_LDA(At, 0, 0); G_STAGE(G_SA(1, 1), a1 + hstepA, voffA);
;             G_WAIT_V(8); G_WAIT_L(0); G_BAR; G_MMA(0, 0, At, B0); G_MMA(0, 1, At, B1); G_BAR; G_SCHED;
;             G_LDA(At, 0, 1); G_STAGE(G_SB(0, 0), b2, voffB); G_STAGE(G_SB(0, 1), b2 + hstepB, voffB); G_STAGE(G_SA(0, 0), a2, voffA);
;             G_WAIT_V(8); G_WAIT_L(0); G_BAR; G_MMA(1, 0, At, B0); G_MMA(1, 1, At, B1); G_BAR; G_SCHED;
.LBB0_338:
	v_or_b32_e32 v187, 0x10000, v10
	v_add_u32_e32 v223, 0x10800, v10
	v_or_b32_e32 v225, 0x14000, v10
	v_add_u32_e32 v227, 0x14800, v10
	s_ashr_i32 s39, s38, 31
	v_add_u32_e32 v222, 0x10400, v10
	ds_read_b128 v[12:15], v187
	ds_read_b128 v[16:19], v222
	v_add_u32_e32 v224, 0x10c00, v10
	ds_read_b128 v[20:23], v223
	ds_read_b128 v[24:27], v224
	v_add_u32_e32 v226, 0x14400, v10
	ds_read_b128 v[28:31], v225
	ds_read_b128 v[32:35], v226
	v_add_u32_e32 v228, 0x14c00, v10
	ds_read_b128 v[36:39], v227
	ds_read_b128 v[40:43], v228
	s_lshl_b64 s[28:29], s[38:39], 9
	v_readlane_b32 s36, v253, 38
	v_readlane_b32 s37, v253, 39
	s_add_u32 s42, s36, s28
	s_addc_u32 s43, s37, s29
	s_and_b64 s[28:29], s[44:45], exec
	s_cselect_b32 s45, s43, s69
	s_cselect_b32 s44, s42, s68
	s_add_u32 s28, s46, 0x70080
	s_addc_u32 s29, s47, 0
	s_mov_b32 m0, s71
	v_lshl_add_u64 v[76:77], s[28:29], 0, v[6:7]
	s_add_i32 s39, s9, 0xe000
	ds_read_b128 v[44:47], v9
	ds_read_b128 v[48:51], v9 offset:1024
	ds_read_b128 v[52:55], v9 offset:2048
	ds_read_b128 v[56:59], v9 offset:3072
	ds_read_b128 v[60:63], v9 offset:4096
	ds_read_b128 v[64:67], v9 offset:5120
	ds_read_b128 v[68:71], v9 offset:6144
	ds_read_b128 v[72:75], v9 offset:7168
	global_load_lds_dwordx4 v[76:77], off
	v_lshl_add_u64 v[76:77], s[28:29], 0, v[4:5]
	s_mov_b32 m0, s39
	s_nop 0
	global_load_lds_dwordx4 v[76:77], off
	s_waitcnt vmcnt(8)
	s_waitcnt lgkmcnt(0)
	s_barrier
	s_setprio 1
	s_waitcnt lgkmcnt(0)
	v_mfma_f32_16x16x32_bf16 v[76:79], v[12:15], v[44:47], 0
	v_mfma_f32_16x16x32_bf16 v[80:83], v[20:23], v[44:47], 0
	v_mfma_f32_16x16x32_bf16 v[84:87], v[12:15], v[52:55], 0
	v_mfma_f32_16x16x32_bf16 v[88:91], v[20:23], v[52:55], 0
	v_mfma_f32_16x16x32_bf16 v[92:95], v[12:15], v[60:63], 0
	v_mfma_f32_16x16x32_bf16 v[96:99], v[20:23], v[60:63], 0
	v_mfma_f32_16x16x32_bf16 v[100:103], v[12:15], v[68:71], 0
	v_mfma_f32_16x16x32_bf16 v[104:107], v[20:23], v[68:71], 0
	v_mfma_f32_16x16x32_bf16 v[76:79], v[16:19], v[48:51], v[76:79]
	v_mfma_f32_16x16x32_bf16 v[80:83], v[24:27], v[48:51], v[80:83]
	v_mfma_f32_16x16x32_bf16 v[84:87], v[16:19], v[56:59], v[84:87]
	v_mfma_f32_16x16x32_bf16 v[88:91], v[24:27], v[56:59], v[88:91]
	v_mfma_f32_16x16x32_bf16 v[92:95], v[16:19], v[64:67], v[92:95]
	v_mfma_f32_16x16x32_bf16 v[96:99], v[24:27], v[64:67], v[96:99]
	v_mfma_f32_16x16x32_bf16 v[100:103], v[16:19], v[72:75], v[100:103]
	v_mfma_f32_16x16x32_bf16 v[104:107], v[24:27], v[72:75], v[104:107]
	v_mfma_f32_16x16x32_bf16 v[108:111], v[28:31], v[44:47], 0
	v_mfma_f32_16x16x32_bf16 v[44:47], v[36:39], v[44:47], 0
	v_mfma_f32_16x16x32_bf16 v[108:111], v[32:35], v[48:51], v[108:111]
	v_mfma_f32_16x16x32_bf16 v[44:47], v[40:43], v[48:51], v[44:47]
	v_mfma_f32_16x16x32_bf16 v[48:51], v[28:31], v[52:55], 0
	v_mfma_f32_16x16x32_bf16 v[52:55], v[36:39], v[52:55], 0
	v_mfma_f32_16x16x32_bf16 v[48:51], v[32:35], v[56:59], v[48:51]
	v_mfma_f32_16x16x32_bf16 v[52:55], v[40:43], v[56:59], v[52:55]
	v_mfma_f32_16x16x32_bf16 v[56:59], v[28:31], v[60:63], 0
	v_mfma_f32_16x16x32_bf16 v[60:63], v[36:39], v[60:63], 0
	v_mfma_f32_16x16x32_bf16 v[56:59], v[32:35], v[64:67], v[56:59]
	v_mfma_f32_16x16x32_bf16 v[60:63], v[40:43], v[64:67], v[60:63]
	v_mfma_f32_16x16x32_bf16 v[64:67], v[28:31], v[68:71], 0
	v_mfma_f32_16x16x32_bf16 v[68:71], v[36:39], v[68:71], 0
	v_mfma_f32_16x16x32_bf16 v[64:67], v[32:35], v[72:75], v[64:67]
	v_mfma_f32_16x16x32_bf16 v[68:71], v[40:43], v[72:75], v[68:71]
	s_setprio 0
	s_barrier
	v_lshl_add_u64 v[212:213], s[68:69], 0, v[0:1]
	s_mov_b32 m0, s14
	v_lshl_add_u64 v[140:141], v[212:213], 0, s[4:5]
	v_lshl_add_u64 v[214:215], s[68:69], 0, v[2:3]
	s_add_u32 s28, s68, 0x10100
	ds_read_b128 v[72:75], v9 offset:16384
	ds_read_b128 v[112:115], v9 offset:17408
	ds_read_b128 v[116:119], v9 offset:18432
	ds_read_b128 v[120:123], v9 offset:19456
	ds_read_b128 v[124:127], v9 offset:20480
	ds_read_b128 v[128:131], v9 offset:21504
	ds_read_b128 v[132:135], v9 offset:22528
	ds_read_b128 v[136:139], v9 offset:23552
	global_load_lds_dwordx4 v[140:141], off
	v_lshl_add_u64 v[140:141], v[214:215], 0, s[4:5]
	s_mov_b32 m0, s15
	s_addc_u32 s29, s69, 0
	global_load_lds_dwordx4 v[140:141], off
	v_lshl_add_u64 v[140:141], s[28:29], 0, v[0:1]
	s_mov_b32 m0, s16
	v_lshl_add_u64 v[216:217], s[46:47], 0, v[6:7]
	global_load_lds_dwordx4 v[140:141], off
	v_lshl_add_u64 v[140:141], s[28:29], 0, v[2:3]
	s_mov_b32 m0, s17
	v_lshl_add_u64 v[218:219], s[46:47], 0, v[4:5]
	global_load_lds_dwordx4 v[140:141], off
	v_lshl_add_u64 v[140:141], v[216:217], 0, s[4:5]
	s_mov_b32 m0, s9
	s_nop 0
	global_load_lds_dwordx4 v[140:141], off
	v_lshl_add_u64 v[140:141], v[218:219], 0, s[4:5]
	s_mov_b32 m0, s18
	s_nop 0
	global_load_lds_dwordx4 v[140:141], off
	s_waitcnt vmcnt(8)
	s_waitcnt lgkmcnt(0)
	s_barrier
; #define G_STAGE(bufoff, gbase, voff) do { _Pragma("unroll") for (int _i = 0; _i < 2; ++_i) \
;         __builtin_amdgcn_global_load_lds((const unsigned*)((const char*)(gbase) + (voff)[_i]), (LAS unsigned*)(lds + (bufoff) + ldsw + _i * 8192), 16, 0, 0); } while (0)
; #define G_LDA(dst, b, h) do { _Pragma("unroll") for (int m = 0; m < 4; ++m) _Pragma("unroll") for (int k = 0; k < 2; ++k) dst[m][k] = *(const LAS bf16x8*)(lds + G_SA(b, h) + aoff + m * 2048 + k * 1024); } while (0)
; #define G_LDB(dst, b, h) do { _Pragma("unroll") for (int n = 0; n < 2; ++n) _Pragma("unroll") for (int k = 0; k < 2; ++k) dst[n][k] = *(const LAS bf16x8*)(lds + G_SB(b, h) + boff + n * 2048 + k * 1024); } while (0)
; #define G_MMA(ai, bj, At, Bt_) do { __builtin_amdgcn_s_setprio(1); _Pragma("unroll") for (int m = 0; m < 4; ++m) _Pragma("unroll") for (int n = 0; n < 2; ++n) _Pragma("unroll") for (int k = 0; k < 2; ++k) \
;         acc[ai][bj][m][n] = __builtin_amdgcn_mfma_f32_16x16x32_bf16(Bt_[n][k], At[m][k], acc[ai][bj][m][n], 0, 0, 0); __builtin_amdgcn_s_setprio(0); } while (0)
; #define G_WAIT_V(n) asm volatile("s_waitcnt vmcnt(" #n ")" ::: "memory")
; #define G_WAIT_L(n) asm volatile("s_waitcnt lgkmcnt(" #n ")" ::: "memory")
; #define G_BAR __builtin_amdgcn_s_barrier()
; #define G_SCHED __builtin_amdgcn_sched_barrier(0)
; template <int NSTORE, class TF, class F>
; DEVI void gemm_run(const bf16_t* __restrict__ A, int lda, const bf16_t* __restrict__ Bt, int ldb, int K, bf16_t* shm, TF&& tile, F&& emit) {
;     ...
;             G_WAIT_V(8); G_WAIT_L(0); G_BAR; G_MMA(1, 0, At, B0); G_MMA(1, 1, At, B1); G_BAR; G_SCHED;
;             G_LDB(B0, 1, 0); G_LDB(B1, 1, 1); G_SCHED; G_LDA(At, 1, 0); G_STAGE(G_SA(0, 1), a2 + hstepA, voffA);
;             G_WAIT_V(8); G_WAIT_L(0); G_BAR; G_MMA(0, 0, At, B0); G_MMA(0, 1, At, B1); G_BAR; G_SCHED;
	s_setprio 1
	s_waitcnt lgkmcnt(0)
	v_mfma_f32_16x16x32_bf16 v[140:143], v[12:15], v[72:75], 0
	v_mfma_f32_16x16x32_bf16 v[148:151], v[12:15], v[116:119], 0
	v_mfma_f32_16x16x32_bf16 v[156:159], v[12:15], v[124:127], 0
	v_mfma_f32_16x16x32_bf16 v[12:15], v[12:15], v[132:135], 0
	v_mfma_f32_16x16x32_bf16 v[140:143], v[16:19], v[112:115], v[140:143]
	v_mfma_f32_16x16x32_bf16 v[144:147], v[20:23], v[72:75], 0
	v_mfma_f32_16x16x32_bf16 v[148:151], v[16:19], v[120:123], v[148:151]
	v_mfma_f32_16x16x32_bf16 v[152:155], v[20:23], v[116:119], 0
	v_mfma_f32_16x16x32_bf16 v[156:159], v[16:19], v[128:131], v[156:159]
	v_mfma_f32_16x16x32_bf16 v[160:163], v[20:23], v[124:127], 0
	v_mfma_f32_16x16x32_bf16 v[12:15], v[16:19], v[136:139], v[12:15]
	v_mfma_f32_16x16x32_bf16 v[16:19], v[20:23], v[132:135], 0
	v_mfma_f32_16x16x32_bf16 v[144:147], v[24:27], v[112:115], v[144:147]
	v_mfma_f32_16x16x32_bf16 v[152:155], v[24:27], v[120:123], v[152:155]
	v_mfma_f32_16x16x32_bf16 v[160:163], v[24:27], v[128:131], v[160:163]
	v_mfma_f32_16x16x32_bf16 v[16:19], v[24:27], v[136:139], v[16:19]
	v_mfma_f32_16x16x32_bf16 v[20:23], v[28:31], v[72:75], 0
	v_mfma_f32_16x16x32_bf16 v[24:27], v[36:39], v[72:75], 0
	v_mfma_f32_16x16x32_bf16 v[20:23], v[32:35], v[112:115], v[20:23]
	v_mfma_f32_16x16x32_bf16 v[24:27], v[40:43], v[112:115], v[24:27]
	v_mfma_f32_16x16x32_bf16 v[72:75], v[28:31], v[116:119], 0
	v_mfma_f32_16x16x32_bf16 v[112:115], v[36:39], v[116:119], 0
	v_mfma_f32_16x16x32_bf16 v[116:119], v[28:31], v[124:127], 0
	v_mfma_f32_16x16x32_bf16 v[28:31], v[28:31], v[132:135], 0
	v_mfma_f32_16x16x32_bf16 v[72:75], v[32:35], v[120:123], v[72:75]
	v_mfma_f32_16x16x32_bf16 v[112:115], v[40:43], v[120:123], v[112:115]
	v_mfma_f32_16x16x32_bf16 v[116:119], v[32:35], v[128:131], v[116:119]
	v_mfma_f32_16x16x32_bf16 v[120:123], v[36:39], v[124:127], 0
	v_mfma_f32_16x16x32_bf16 v[28:31], v[32:35], v[136:139], v[28:31]
	v_mfma_f32_16x16x32_bf16 v[32:35], v[36:39], v[132:135], 0
	v_mfma_f32_16x16x32_bf16 v[120:123], v[40:43], v[128:131], v[120:123]
	v_mfma_f32_16x16x32_bf16 v[32:35], v[40:43], v[136:139], v[32:35]
	s_setprio 0
	s_barrier
	v_or_b32_e32 v229, 0x18000, v10
	v_add_u32_e32 v231, 0x18800, v10
	v_or_b32_e32 v233, 0x1c000, v10
	v_add_u32_e32 v235, 0x1c800, v10
	v_add_u32_e32 v230, 0x18400, v10
	ds_read_b128 v[36:39], v229
	ds_read_b128 v[40:43], v230
	v_add_u32_e32 v232, 0x18c00, v10
	ds_read_b128 v[124:127], v231
	ds_read_b128 v[128:131], v232
	v_add_u32_e32 v234, 0x1c400, v10
	ds_read_b128 v[132:135], v233
	ds_read_b128 v[136:139], v234
	v_add_u32_e32 v236, 0x1cc00, v10
	ds_read_b128 v[164:167], v235
	ds_read_b128 v[168:171], v236
	s_add_u32 s28, s46, 0x70100
	s_addc_u32 s29, s47, 0
	s_mov_b32 m0, s19
	v_lshl_add_u64 v[220:221], s[28:29], 0, v[6:7]
	ds_read_b128 v[176:179], v9 offset:32768
	ds_read_b128 v[182:185], v9 offset:33792
	ds_read_b128 v[188:191], v9 offset:34816
	ds_read_b128 v[192:195], v9 offset:35840
	ds_read_b128 v[196:199], v9 offset:36864
	ds_read_b128 v[200:203], v9 offset:37888
	ds_read_b128 v[204:207], v9 offset:38912
	ds_read_b128 v[208:211], v9 offset:39936
	global_load_lds_dwordx4 v[220:221], off
	v_lshl_add_u64 v[220:221], s[28:29], 0, v[4:5]
	s_mov_b32 m0, s26
	s_nop 0
	global_load_lds_dwordx4 v[220:221], off
	s_waitcnt vmcnt(8)
	s_waitcnt lgkmcnt(0)
	s_barrier
	s_setprio 1
	s_waitcnt lgkmcnt(0)
	v_mfma_f32_16x16x32_bf16 v[76:79], v[36:39], v[176:179], v[76:79]
	v_mfma_f32_16x16x32_bf16 v[80:83], v[124:127], v[176:179], v[80:83]
	v_mfma_f32_16x16x32_bf16 v[84:87], v[36:39], v[188:191], v[84:87]
	v_mfma_f32_16x16x32_bf16 v[88:91], v[124:127], v[188:191], v[88:91]
	v_mfma_f32_16x16x32_bf16 v[92:95], v[36:39], v[196:199], v[92:95]
	v_mfma_f32_16x16x32_bf16 v[96:99], v[124:127], v[196:199], v[96:99]
	v_mfma_f32_16x16x32_bf16 v[100:103], v[36:39], v[204:207], v[100:103]
	v_mfma_f32_16x16x32_bf16 v[104:107], v[124:127], v[204:207], v[104:107]
	v_mfma_f32_16x16x32_bf16 v[76:79], v[40:43], v[182:185], v[76:79]
	v_mfma_f32_16x16x32_bf16 v[80:83], v[128:131], v[182:185], v[80:83]
	v_mfma_f32_16x16x32_bf16 v[84:87], v[40:43], v[192:195], v[84:87]
	v_mfma_f32_16x16x32_bf16 v[88:91], v[128:131], v[192:195], v[88:91]
	v_mfma_f32_16x16x32_bf16 v[92:95], v[40:43], v[200:203], v[92:95]
	v_mfma_f32_16x16x32_bf16 v[96:99], v[128:131], v[200:203], v[96:99]
	v_mfma_f32_16x16x32_bf16 v[100:103], v[40:43], v[208:211], v[100:103]
	v_mfma_f32_16x16x32_bf16 v[104:107], v[128:131], v[208:211], v[104:107]
	v_mfma_f32_16x16x32_bf16 v[108:111], v[132:135], v[176:179], v[108:111]
	v_mfma_f32_16x16x32_bf16 v[44:47], v[164:167], v[176:179], v[44:47]
	v_mfma_f32_16x16x32_bf16 v[48:51], v[132:135], v[188:191], v[48:51]
	v_mfma_f32_16x16x32_bf16 v[52:55], v[164:167], v[188:191], v[52:55]
	v_mfma_f32_16x16x32_bf16 v[56:59], v[132:135], v[196:199], v[56:59]
	v_mfma_f32_16x16x32_bf16 v[60:63], v[164:167], v[196:199], v[60:63]
	v_mfma_f32_16x16x32_bf16 v[64:67], v[132:135], v[204:207], v[64:67]
	v_mfma_f32_16x16x32_bf16 v[68:71], v[164:167], v[204:207], v[68:71]
	v_mfma_f32_16x16x32_bf16 v[108:111], v[136:139], v[182:185], v[108:111]
	v_mfma_f32_16x16x32_bf16 v[44:47], v[168:171], v[182:185], v[44:47]
	v_mfma_f32_16x16x32_bf16 v[48:51], v[136:139], v[192:195], v[48:51]
	v_mfma_f32_16x16x32_bf16 v[52:55], v[168:171], v[192:195], v[52:55]
	v_mfma_f32_16x16x32_bf16 v[56:59], v[136:139], v[200:203], v[56:59]
	v_mfma_f32_16x16x32_bf16 v[60:63], v[168:171], v[200:203], v[60:63]
	v_mfma_f32_16x16x32_bf16 v[64:67], v[136:139], v[208:211], v[64:67]
	v_mfma_f32_16x16x32_bf16 v[68:71], v[168:171], v[208:211], v[68:71]
	s_setprio 0
	s_barrier
; #define G_STAGE(bufoff, gbase, voff) do { _Pragma("unroll") for (int _i = 0; _i < 2; ++_i) \
;         __builtin_amdgcn_global_load_lds((const unsigned*)((const char*)(gbase) + (voff)[_i]), (LAS unsigned*)(lds + (bufoff) + ldsw + _i * 8192), 16, 0, 0); } while (0)
; #define G_LDA(dst, b, h) do { _Pragma("unroll") for (int m = 0; m < 4; ++m) _Pragma("unroll") for (int k = 0; k < 2; ++k) dst[m][k] = *(const LAS bf16x8*)(lds + G_SA(b, h) + aoff + m * 2048 + k * 1024); } while (0)
; #define G_LDB(dst, b, h) do { _Pragma("unroll") for (int n = 0; n < 2; ++n) _Pragma("unroll") for (int k = 0; k < 2; ++k) dst[n][k] = *(const LAS bf16x8*)(lds + G_SB(b, h) + boff + n * 2048 + k * 1024); } while (0)
; #define G_MMA(ai, bj, At, Bt_) do { __builtin_amdgcn_s_setprio(1); _Pragma("unroll") for (int m = 0; m < 4; ++m) _Pragma("unroll") for (int n = 0; n < 2; ++n) _Pragma("unroll") for (int k = 0; k < 2; ++k) \
;         acc[ai][bj][m][n] = __builtin_amdgcn_mfma_f32_16x16x32_bf16(Bt_[n][k], At[m][k], acc[ai][bj][m][n], 0, 0, 0); __builtin_amdgcn_s_setprio(0); } while (0)
; #define G_WAIT_V(n) asm volatile("s_waitcnt vmcnt(" #n ")" ::: "memory")
; #define G_WAIT_L(n) asm volatile("s_waitcnt lgkmcnt(" #n ")" ::: "memory")
; #define G_BAR __builtin_amdgcn_s_barrier()
; #define G_SCHED __builtin_amdgcn_sched_barrier(0)
; template <int NSTORE, class TF, class F>
; DEVI void gemm_run(const bf16_t* __restrict__ A, int lda, const bf16_t* __restrict__ Bt, int ldb, int K, bf16_t* shm, TF&& tile, F&& emit) {
;     ...
;             G_LDB(B0, 0, 0); G_LDB(B1, 0, 1); G_SCHED; G_LDA(At, 0, 0); G_STAGE(G_SA(1, 1), a1 + hstepA, voffA);
;             G_WAIT_V(8); G_WAIT_L(0); G_BAR; G_MMA(0, 0, At, B0); G_MMA(0, 1, At, B1); G_BAR; G_SCHED;
;     ...
;             G_LDA(At, 1, 1); G_STAGE(G_SB(1, 0), b3, voffB); G_STAGE(G_SB(1, 1), b3 + hstepB, voffB); G_STAGE(G_SA(1, 0), a3, voffA);
;             G_WAIT_V(8); G_WAIT_L(0); G_BAR; G_MMA(1, 0, At, B0); G_MMA(1, 1, At, B1); G_BAR; G_SCHED;
	s_mov_b64 s[36:37], 0x180
	s_mov_b32 m0, s27
	v_lshl_add_u64 v[212:213], v[212:213], 0, s[36:37]
	s_add_u32 s28, s68, 0x10180
	ds_read_b128 v[176:179], v9 offset:49152
	ds_read_b128 v[182:185], v9 offset:50176
	ds_read_b128 v[188:191], v9 offset:51200
	ds_read_b128 v[192:195], v9 offset:52224
	ds_read_b128 v[196:199], v9 offset:53248
	ds_read_b128 v[200:203], v9 offset:54272
	ds_read_b128 v[204:207], v9 offset:55296
	ds_read_b128 v[208:211], v9 offset:56320
	global_load_lds_dwordx4 v[212:213], off
	v_lshl_add_u64 v[212:213], v[214:215], 0, s[36:37]
	s_mov_b32 m0, s48
	s_addc_u32 s29, s69, 0
	global_load_lds_dwordx4 v[212:213], off
	v_lshl_add_u64 v[212:213], s[28:29], 0, v[0:1]
	s_mov_b32 m0, s3
	s_nop 0
	global_load_lds_dwordx4 v[212:213], off
	v_lshl_add_u64 v[212:213], s[28:29], 0, v[2:3]
	s_mov_b32 m0, s33
	s_nop 0
	global_load_lds_dwordx4 v[212:213], off
	v_lshl_add_u64 v[212:213], v[216:217], 0, s[36:37]
	s_mov_b32 m0, s49
	s_nop 0
	global_load_lds_dwordx4 v[212:213], off
	v_lshl_add_u64 v[212:213], v[218:219], 0, s[36:37]
	s_mov_b32 m0, s70
	s_nop 0
	global_load_lds_dwordx4 v[212:213], off
	s_waitcnt vmcnt(8)
	s_waitcnt lgkmcnt(0)
	s_barrier
	s_setprio 1
	s_waitcnt lgkmcnt(0)
	v_mfma_f32_16x16x32_bf16 v[140:143], v[36:39], v[176:179], v[140:143]
	v_mfma_f32_16x16x32_bf16 v[144:147], v[124:127], v[176:179], v[144:147]
	v_mfma_f32_16x16x32_bf16 v[148:151], v[36:39], v[188:191], v[148:151]
	v_mfma_f32_16x16x32_bf16 v[152:155], v[124:127], v[188:191], v[152:155]
	v_mfma_f32_16x16x32_bf16 v[156:159], v[36:39], v[196:199], v[156:159]
	v_mfma_f32_16x16x32_bf16 v[160:163], v[124:127], v[196:199], v[160:163]
	v_mfma_f32_16x16x32_bf16 v[12:15], v[36:39], v[204:207], v[12:15]
	v_mfma_f32_16x16x32_bf16 v[16:19], v[124:127], v[204:207], v[16:19]
	v_mfma_f32_16x16x32_bf16 v[140:143], v[40:43], v[182:185], v[140:143]
	v_mfma_f32_16x16x32_bf16 v[144:147], v[128:131], v[182:185], v[144:147]
	v_mfma_f32_16x16x32_bf16 v[148:151], v[40:43], v[192:195], v[148:151]
	v_mfma_f32_16x16x32_bf16 v[152:155], v[128:131], v[192:195], v[152:155]
	v_mfma_f32_16x16x32_bf16 v[156:159], v[40:43], v[200:203], v[156:159]
	v_mfma_f32_16x16x32_bf16 v[160:163], v[128:131], v[200:203], v[160:163]
	v_mfma_f32_16x16x32_bf16 v[12:15], v[40:43], v[208:211], v[12:15]
	v_mfma_f32_16x16x32_bf16 v[16:19], v[128:131], v[208:211], v[16:19]
	v_mfma_f32_16x16x32_bf16 v[20:23], v[132:135], v[176:179], v[20:23]
	v_mfma_f32_16x16x32_bf16 v[24:27], v[164:167], v[176:179], v[24:27]
	v_mfma_f32_16x16x32_bf16 v[36:39], v[132:135], v[188:191], v[72:75]
	v_mfma_f32_16x16x32_bf16 v[40:43], v[164:167], v[188:191], v[112:115]
	v_mfma_f32_16x16x32_bf16 v[72:75], v[132:135], v[196:199], v[116:119]
	v_mfma_f32_16x16x32_bf16 v[112:115], v[164:167], v[196:199], v[120:123]
	v_mfma_f32_16x16x32_bf16 v[28:31], v[132:135], v[204:207], v[28:31]
	v_mfma_f32_16x16x32_bf16 v[32:35], v[164:167], v[204:207], v[32:35]
	v_mfma_f32_16x16x32_bf16 v[20:23], v[136:139], v[182:185], v[20:23]
	v_mfma_f32_16x16x32_bf16 v[24:27], v[168:171], v[182:185], v[24:27]
	v_mfma_f32_16x16x32_bf16 v[36:39], v[136:139], v[192:195], v[36:39]
	v_mfma_f32_16x16x32_bf16 v[40:43], v[168:171], v[192:195], v[40:43]
	v_mfma_f32_16x16x32_bf16 v[72:75], v[136:139], v[200:203], v[72:75]
	v_mfma_f32_16x16x32_bf16 v[112:115], v[168:171], v[200:203], v[112:115]
	v_mfma_f32_16x16x32_bf16 v[28:31], v[136:139], v[208:211], v[28:31]
	v_mfma_f32_16x16x32_bf16 v[32:35], v[168:171], v[208:211], v[32:35]
	s_setprio 0
	s_barrier
	ds_read_b128 v[116:119], v187
	ds_read_b128 v[120:123], v222
	ds_read_b128 v[124:127], v223
	ds_read_b128 v[128:131], v224
	ds_read_b128 v[132:135], v225
	ds_read_b128 v[136:139], v226
	ds_read_b128 v[164:167], v227
	ds_read_b128 v[168:171], v228
	s_add_u32 s28, s46, 0x70180
	s_addc_u32 s29, s47, 0
	s_mov_b32 m0, s71
	v_lshl_add_u64 v[212:213], s[28:29], 0, v[6:7]
	ds_read_b128 v[176:179], v9
	ds_read_b128 v[182:185], v9 offset:1024
	ds_read_b128 v[188:191], v9 offset:2048
	ds_read_b128 v[192:195], v9 offset:3072
	ds_read_b128 v[196:199], v9 offset:4096
	ds_read_b128 v[200:203], v9 offset:5120
	ds_read_b128 v[204:207], v9 offset:6144
	ds_read_b128 v[208:211], v9 offset:7168
	global_load_lds_dwordx4 v[212:213], off
	v_lshl_add_u64 v[212:213], s[28:29], 0, v[4:5]
	s_mov_b32 m0, s39
	s_nop 0
	global_load_lds_dwordx4 v[212:213], off
	s_waitcnt vmcnt(8)
	s_waitcnt lgkmcnt(0)
	s_barrier
	s_setprio 1
	s_waitcnt lgkmcnt(0)
	v_mfma_f32_16x16x32_bf16 v[76:79], v[116:119], v[176:179], v[76:79]
	v_mfma_f32_16x16x32_bf16 v[80:83], v[124:127], v[176:179], v[80:83]
	v_mfma_f32_16x16x32_bf16 v[84:87], v[116:119], v[188:191], v[84:87]
	v_mfma_f32_16x16x32_bf16 v[88:91], v[124:127], v[188:191], v[88:91]
	v_mfma_f32_16x16x32_bf16 v[92:95], v[116:119], v[196:199], v[92:95]
	v_mfma_f32_16x16x32_bf16 v[96:99], v[124:127], v[196:199], v[96:99]
	v_mfma_f32_16x16x32_bf16 v[100:103], v[116:119], v[204:207], v[100:103]
	v_mfma_f32_16x16x32_bf16 v[104:107], v[124:127], v[204:207], v[104:107]
	v_mfma_f32_16x16x32_bf16 v[76:79], v[120:123], v[182:185], v[76:79]
	v_mfma_f32_16x16x32_bf16 v[80:83], v[128:131], v[182:185], v[80:83]
	v_mfma_f32_16x16x32_bf16 v[84:87], v[120:123], v[192:195], v[84:87]
	v_mfma_f32_16x16x32_bf16 v[88:91], v[128:131], v[192:195], v[88:91]
	v_mfma_f32_16x16x32_bf16 v[92:95], v[120:123], v[200:203], v[92:95]
	v_mfma_f32_16x16x32_bf16 v[96:99], v[128:131], v[200:203], v[96:99]
	v_mfma_f32_16x16x32_bf16 v[100:103], v[120:123], v[208:211], v[100:103]
	v_mfma_f32_16x16x32_bf16 v[104:107], v[128:131], v[208:211], v[104:107]
	v_mfma_f32_16x16x32_bf16 v[108:111], v[132:135], v[176:179], v[108:111]
	v_mfma_f32_16x16x32_bf16 v[44:47], v[164:167], v[176:179], v[44:47]
	v_mfma_f32_16x16x32_bf16 v[48:51], v[132:135], v[188:191], v[48:51]
	v_mfma_f32_16x16x32_bf16 v[52:55], v[164:167], v[188:191], v[52:55]
	v_mfma_f32_16x16x32_bf16 v[56:59], v[132:135], v[196:199], v[56:59]
	v_mfma_f32_16x16x32_bf16 v[60:63], v[164:167], v[196:199], v[60:63]
	v_mfma_f32_16x16x32_bf16 v[64:67], v[132:135], v[204:207], v[64:67]
	v_mfma_f32_16x16x32_bf16 v[68:71], v[164:167], v[204:207], v[68:71]
	v_mfma_f32_16x16x32_bf16 v[108:111], v[136:139], v[182:185], v[108:111]
	v_mfma_f32_16x16x32_bf16 v[44:47], v[168:171], v[182:185], v[44:47]
	v_mfma_f32_16x16x32_bf16 v[48:51], v[136:139], v[192:195], v[48:51]
	v_mfma_f32_16x16x32_bf16 v[52:55], v[168:171], v[192:195], v[52:55]
	v_mfma_f32_16x16x32_bf16 v[56:59], v[136:139], v[200:203], v[56:59]
	v_mfma_f32_16x16x32_bf16 v[60:63], v[168:171], v[200:203], v[60:63]
	v_mfma_f32_16x16x32_bf16 v[64:67], v[136:139], v[208:211], v[64:67]
	v_mfma_f32_16x16x32_bf16 v[68:71], v[168:171], v[208:211], v[68:71]
	s_setprio 0
	s_barrier
; #define G_STAGE(bufoff, gbase, voff) do { _Pragma("unroll") for (int _i = 0; _i < 2; ++_i) \
;         __builtin_amdgcn_global_load_lds((const unsigned*)((const char*)(gbase) + (voff)[_i]), (LAS unsigned*)(lds + (bufoff) + ldsw + _i * 8192), 16, 0, 0); } while (0)
; #define G_LDA(dst, b, h) do { _Pragma("unroll") for (int m = 0; m < 4; ++m) _Pragma("unroll") for (int k = 0; k < 2; ++k) dst[m][k] = *(const LAS bf16x8*)(lds + G_SA(b, h) + aoff + m * 2048 + k * 1024); } while (0)
; #define G_LDB(dst, b, h) do { _Pragma("unroll") for (int n = 0; n < 2; ++n) _Pragma("unroll") for (int k = 0; k < 2; ++k) dst[n][k] = *(const LAS bf16x8*)(lds + G_SB(b, h) + boff + n * 2048 + k * 1024); } while (0)
; #define G_MMA(ai, bj, At, Bt_) do { __builtin_amdgcn_s_setprio(1); _Pragma("unroll") for (int m = 0; m < 4; ++m) _Pragma("unroll") for (int n = 0; n < 2; ++n) _Pragma("unroll") for (int k = 0; k < 2; ++k) \
;         acc[ai][bj][m][n] = __builtin_amdgcn_mfma_f32_16x16x32_bf16(Bt_[n][k], At[m][k], acc[ai][bj][m][n], 0, 0, 0); __builtin_amdgcn_s_setprio(0); } while (0)
; #define G_WAIT_V(n) asm volatile("s_waitcnt vmcnt(" #n ")" ::: "memory")
; #define G_WAIT_L(n) asm volatile("s_waitcnt lgkmcnt(" #n ")" ::: "memory")
; #define G_BAR __builtin_amdgcn_s_barrier()
; #define G_SCHED __builtin_amdgcn_sched_barrier(0)
; template <int NSTORE, class TF, class F>
; DEVI void gemm_run(const bf16_t* __restrict__ A, int lda, const bf16_t* __restrict__ Bt, int ldb, int K, bf16_t* shm, TF&& tile, F&& emit) {
;     ...
;             G_LDA(At, 0, 1); G_STAGE(G_SB(0, 0), b2, voffB); G_STAGE(G_SB(0, 1), b2 + hstepB, voffB); G_STAGE(G_SA(0, 0), a2, voffA);
;             G_WAIT_V(8); G_WAIT_L(0); G_BAR; G_MMA(1, 0, At, B0); G_MMA(1, 1, At, B1); G_BAR; G_SCHED;
;             G_LDB(B0, 1, 0); G_LDB(B1, 1, 1); G_SCHED; G_LDA(At, 1, 0); G_STAGE(G_SA(0, 1), a2 + hstepA, voffA);
;             G_WAIT_V(8); G_WAIT_L(0); G_BAR; G_MMA(0, 0, At, B0); G_MMA(0, 1, At, B1); G_BAR; G_SCHED;
	s_mov_b32 m0, s14
	v_lshl_add_u64 v[212:213], s[44:45], 0, v[0:1]
	s_add_u32 s28, s44, 0x10000
	ds_read_b128 v[176:179], v9 offset:16384
	ds_read_b128 v[182:185], v9 offset:17408
	ds_read_b128 v[188:191], v9 offset:18432
	ds_read_b128 v[192:195], v9 offset:19456
	ds_read_b128 v[196:199], v9 offset:20480
	ds_read_b128 v[200:203], v9 offset:21504
	ds_read_b128 v[204:207], v9 offset:22528
	ds_read_b128 v[208:211], v9 offset:23552
	global_load_lds_dwordx4 v[212:213], off
	v_lshl_add_u64 v[214:215], s[44:45], 0, v[2:3]
	s_mov_b32 m0, s15
	s_addc_u32 s29, s45, 0
	global_load_lds_dwordx4 v[214:215], off
	v_lshl_add_u64 v[216:217], s[28:29], 0, v[0:1]
	s_mov_b32 m0, s16
	v_lshl_add_u64 v[218:219], s[40:41], 0, v[4:5]
	global_load_lds_dwordx4 v[216:217], off
	v_lshl_add_u64 v[216:217], s[28:29], 0, v[2:3]
	s_mov_b32 m0, s17
	s_nop 0
	global_load_lds_dwordx4 v[216:217], off
	v_lshl_add_u64 v[216:217], s[40:41], 0, v[6:7]
	s_mov_b32 m0, s9
	s_nop 0
	global_load_lds_dwordx4 v[216:217], off
	s_mov_b32 m0, s18
	s_nop 0
	global_load_lds_dwordx4 v[218:219], off
	s_waitcnt vmcnt(8)
	s_waitcnt lgkmcnt(0)
	s_barrier
	s_setprio 1
	s_waitcnt lgkmcnt(0)
	v_mfma_f32_16x16x32_bf16 v[140:143], v[116:119], v[176:179], v[140:143]
	v_mfma_f32_16x16x32_bf16 v[144:147], v[124:127], v[176:179], v[144:147]
	v_mfma_f32_16x16x32_bf16 v[148:151], v[116:119], v[188:191], v[148:151]
	v_mfma_f32_16x16x32_bf16 v[152:155], v[124:127], v[188:191], v[152:155]
	v_mfma_f32_16x16x32_bf16 v[156:159], v[116:119], v[196:199], v[156:159]
	v_mfma_f32_16x16x32_bf16 v[160:163], v[124:127], v[196:199], v[160:163]
	v_mfma_f32_16x16x32_bf16 v[12:15], v[116:119], v[204:207], v[12:15]
	v_mfma_f32_16x16x32_bf16 v[16:19], v[124:127], v[204:207], v[16:19]
	v_mfma_f32_16x16x32_bf16 v[140:143], v[120:123], v[182:185], v[140:143]
	v_mfma_f32_16x16x32_bf16 v[144:147], v[128:131], v[182:185], v[144:147]
	v_mfma_f32_16x16x32_bf16 v[148:151], v[120:123], v[192:195], v[148:151]
	v_mfma_f32_16x16x32_bf16 v[152:155], v[128:131], v[192:195], v[152:155]
	v_mfma_f32_16x16x32_bf16 v[156:159], v[120:123], v[200:203], v[156:159]
	v_mfma_f32_16x16x32_bf16 v[160:163], v[128:131], v[200:203], v[160:163]
	v_mfma_f32_16x16x32_bf16 v[12:15], v[120:123], v[208:211], v[12:15]
	v_mfma_f32_16x16x32_bf16 v[16:19], v[128:131], v[208:211], v[16:19]
	v_mfma_f32_16x16x32_bf16 v[20:23], v[132:135], v[176:179], v[20:23]
	v_mfma_f32_16x16x32_bf16 v[24:27], v[164:167], v[176:179], v[24:27]
	v_mfma_f32_16x16x32_bf16 v[36:39], v[132:135], v[188:191], v[36:39]
	v_mfma_f32_16x16x32_bf16 v[40:43], v[164:167], v[188:191], v[40:43]
	v_mfma_f32_16x16x32_bf16 v[72:75], v[132:135], v[196:199], v[72:75]
	v_mfma_f32_16x16x32_bf16 v[112:115], v[164:167], v[196:199], v[112:115]
	v_mfma_f32_16x16x32_bf16 v[28:31], v[132:135], v[204:207], v[28:31]
	v_mfma_f32_16x16x32_bf16 v[32:35], v[164:167], v[204:207], v[32:35]
	v_mfma_f32_16x16x32_bf16 v[20:23], v[136:139], v[182:185], v[20:23]
	v_mfma_f32_16x16x32_bf16 v[24:27], v[168:171], v[182:185], v[24:27]
	v_mfma_f32_16x16x32_bf16 v[36:39], v[136:139], v[192:195], v[36:39]
	v_mfma_f32_16x16x32_bf16 v[40:43], v[168:171], v[192:195], v[40:43]
	v_mfma_f32_16x16x32_bf16 v[72:75], v[136:139], v[200:203], v[72:75]
	v_mfma_f32_16x16x32_bf16 v[112:115], v[168:171], v[200:203], v[112:115]
	v_mfma_f32_16x16x32_bf16 v[28:31], v[136:139], v[208:211], v[28:31]
	v_mfma_f32_16x16x32_bf16 v[32:35], v[168:171], v[208:211], v[32:35]
	s_setprio 0
	s_barrier
	ds_read_b128 v[116:119], v229
	ds_read_b128 v[120:123], v230
	ds_read_b128 v[124:127], v231
	ds_read_b128 v[128:131], v232
	ds_read_b128 v[132:135], v233
	ds_read_b128 v[136:139], v234
	ds_read_b128 v[164:167], v235
	ds_read_b128 v[168:171], v236
	s_add_u32 s28, s40, 0x70000
	s_addc_u32 s29, s41, 0
	s_mov_b32 m0, s19
	v_lshl_add_u64 v[220:221], s[28:29], 0, v[6:7]
	ds_read_b128 v[176:179], v9 offset:32768
	ds_read_b128 v[182:185], v9 offset:33792
	ds_read_b128 v[188:191], v9 offset:34816
	ds_read_b128 v[192:195], v9 offset:35840
	ds_read_b128 v[196:199], v9 offset:36864
	ds_read_b128 v[200:203], v9 offset:37888
	ds_read_b128 v[204:207], v9 offset:38912
	ds_read_b128 v[208:211], v9 offset:39936
	global_load_lds_dwordx4 v[220:221], off
	v_lshl_add_u64 v[220:221], s[28:29], 0, v[4:5]
	s_mov_b32 m0, s26
	s_nop 0
	global_load_lds_dwordx4 v[220:221], off
	s_waitcnt vmcnt(8)
	s_waitcnt lgkmcnt(0)
	s_barrier
	s_setprio 1
	s_waitcnt lgkmcnt(0)
	v_mfma_f32_16x16x32_bf16 v[76:79], v[116:119], v[176:179], v[76:79]
	v_mfma_f32_16x16x32_bf16 v[80:83], v[124:127], v[176:179], v[80:83]
	v_mfma_f32_16x16x32_bf16 v[84:87], v[116:119], v[188:191], v[84:87]
	v_mfma_f32_16x16x32_bf16 v[88:91], v[124:127], v[188:191], v[88:91]
	v_mfma_f32_16x16x32_bf16 v[92:95], v[116:119], v[196:199], v[92:95]
	v_mfma_f32_16x16x32_bf16 v[96:99], v[124:127], v[196:199], v[96:99]
	v_mfma_f32_16x16x32_bf16 v[100:103], v[116:119], v[204:207], v[100:103]
	v_mfma_f32_16x16x32_bf16 v[104:107], v[124:127], v[204:207], v[104:107]
	v_mfma_f32_16x16x32_bf16 v[76:79], v[120:123], v[182:185], v[76:79]
	v_mfma_f32_16x16x32_bf16 v[80:83], v[128:131], v[182:185], v[80:83]
	v_mfma_f32_16x16x32_bf16 v[84:87], v[120:123], v[192:195], v[84:87]
	v_mfma_f32_16x16x32_bf16 v[88:91], v[128:131], v[192:195], v[88:91]
	v_mfma_f32_16x16x32_bf16 v[92:95], v[120:123], v[200:203], v[92:95]
	v_mfma_f32_16x16x32_bf16 v[96:99], v[128:131], v[200:203], v[96:99]
	v_mfma_f32_16x16x32_bf16 v[100:103], v[120:123], v[208:211], v[100:103]
	v_mfma_f32_16x16x32_bf16 v[104:107], v[128:131], v[208:211], v[104:107]
	v_mfma_f32_16x16x32_bf16 v[108:111], v[132:135], v[176:179], v[108:111]
	v_mfma_f32_16x16x32_bf16 v[44:47], v[164:167], v[176:179], v[44:47]
	v_mfma_f32_16x16x32_bf16 v[48:51], v[132:135], v[188:191], v[48:51]
	v_mfma_f32_16x16x32_bf16 v[52:55], v[164:167], v[188:191], v[52:55]
	v_mfma_f32_16x16x32_bf16 v[56:59], v[132:135], v[196:199], v[56:59]
	v_mfma_f32_16x16x32_bf16 v[60:63], v[164:167], v[196:199], v[60:63]
	v_mfma_f32_16x16x32_bf16 v[64:67], v[132:135], v[204:207], v[64:67]
	v_mfma_f32_16x16x32_bf16 v[68:71], v[164:167], v[204:207], v[68:71]
	v_mfma_f32_16x16x32_bf16 v[108:111], v[136:139], v[182:185], v[108:111]
	v_mfma_f32_16x16x32_bf16 v[44:47], v[168:171], v[182:185], v[44:47]
	v_mfma_f32_16x16x32_bf16 v[48:51], v[136:139], v[192:195], v[48:51]
	v_mfma_f32_16x16x32_bf16 v[52:55], v[168:171], v[192:195], v[52:55]
	v_mfma_f32_16x16x32_bf16 v[56:59], v[136:139], v[200:203], v[56:59]
	v_mfma_f32_16x16x32_bf16 v[60:63], v[168:171], v[200:203], v[60:63]
	v_mfma_f32_16x16x32_bf16 v[64:67], v[136:139], v[208:211], v[64:67]
	v_mfma_f32_16x16x32_bf16 v[68:71], v[168:171], v[208:211], v[68:71]
	s_setprio 0
	s_barrier
; #define G_STAGE(bufoff, gbase, voff) do { _Pragma("unroll") for (int _i = 0; _i < 2; ++_i) \
;         __builtin_amdgcn_global_load_lds((const unsigned*)((const char*)(gbase) + (voff)[_i]), (LAS unsigned*)(lds + (bufoff) + ldsw + _i * 8192), 16, 0, 0); } while (0)
; #define G_LDA(dst, b, h) do { _Pragma("unroll") for (int m = 0; m < 4; ++m) _Pragma("unroll") for (int k = 0; k < 2; ++k) dst[m][k] = *(const LAS bf16x8*)(lds + G_SA(b, h) + aoff + m * 2048 + k * 1024); } while (0)
; #define G_MMA(ai, bj, At, Bt_) do { __builtin_amdgcn_s_setprio(1); _Pragma("unroll") for (int m = 0; m < 4; ++m) _Pragma("unroll") for (int n = 0; n < 2; ++n) _Pragma("unroll") for (int k = 0; k < 2; ++k) \
;         acc[ai][bj][m][n] = __builtin_amdgcn_mfma_f32_16x16x32_bf16(Bt_[n][k], At[m][k], acc[ai][bj][m][n], 0, 0, 0); __builtin_amdgcn_s_setprio(0); } while (0)
; #define G_WAIT_V(n) asm volatile("s_waitcnt vmcnt(" #n ")" ::: "memory")
; #define G_WAIT_L(n) asm volatile("s_waitcnt lgkmcnt(" #n ")" ::: "memory")
; #define G_BAR __builtin_amdgcn_s_barrier()
; #define G_SCHED __builtin_amdgcn_sched_barrier(0)
; template <int NSTORE, class TF, class F>
; DEVI void gemm_run(const bf16_t* __restrict__ A, int lda, const bf16_t* __restrict__ Bt, int ldb, int K, bf16_t* shm, TF&& tile, F&& emit) {
;     ...
;             G_LDA(At, 1, 1); G_STAGE(G_SB(1, 0), b3, voffB); G_STAGE(G_SB(1, 1), b3 + hstepB, voffB); G_STAGE(G_SA(1, 0), a3, voffA);
;             G_WAIT_V(8); G_WAIT_L(0); G_BAR; G_MMA(1, 0, At, B0); G_MMA(1, 1, At, B1); G_BAR; G_SCHED;
	s_mov_b32 m0, s27
	v_lshl_add_u64 v[212:213], v[212:213], 0, s[30:31]
	s_add_u32 s28, s44, 0x10080
	ds_read_b128 v[176:179], v9 offset:49152
	ds_read_b128 v[182:185], v9 offset:50176
	ds_read_b128 v[188:191], v9 offset:51200
	ds_read_b128 v[192:195], v9 offset:52224
	ds_read_b128 v[196:199], v9 offset:53248
	ds_read_b128 v[200:203], v9 offset:54272
	ds_read_b128 v[204:207], v9 offset:55296
	ds_read_b128 v[208:211], v9 offset:56320
	global_load_lds_dwordx4 v[212:213], off
	v_lshl_add_u64 v[212:213], v[214:215], 0, s[30:31]
	s_mov_b32 m0, s48
	s_addc_u32 s29, s45, 0
	global_load_lds_dwordx4 v[212:213], off
	v_lshl_add_u64 v[212:213], s[28:29], 0, v[0:1]
	s_mov_b32 m0, s3
	s_nop 0
	global_load_lds_dwordx4 v[212:213], off
	v_lshl_add_u64 v[212:213], s[28:29], 0, v[2:3]
	s_mov_b32 m0, s33
	s_nop 0
	global_load_lds_dwordx4 v[212:213], off
	v_lshl_add_u64 v[212:213], v[216:217], 0, s[30:31]
	s_mov_b32 m0, s49
	s_nop 0
	global_load_lds_dwordx4 v[212:213], off
	v_lshl_add_u64 v[212:213], v[218:219], 0, s[30:31]
	s_mov_b32 m0, s70
	s_nop 0
	global_load_lds_dwordx4 v[212:213], off
	s_waitcnt vmcnt(8)
	s_waitcnt lgkmcnt(0)
	s_barrier
	s_setprio 1
	s_waitcnt lgkmcnt(0)
	v_mfma_f32_16x16x32_bf16 v[140:143], v[116:119], v[176:179], v[140:143]
	v_mfma_f32_16x16x32_bf16 v[144:147], v[124:127], v[176:179], v[144:147]
	v_mfma_f32_16x16x32_bf16 v[148:151], v[116:119], v[188:191], v[148:151]
	v_mfma_f32_16x16x32_bf16 v[152:155], v[124:127], v[188:191], v[152:155]
	v_mfma_f32_16x16x32_bf16 v[156:159], v[116:119], v[196:199], v[156:159]
	v_mfma_f32_16x16x32_bf16 v[160:163], v[124:127], v[196:199], v[160:163]
	v_mfma_f32_16x16x32_bf16 v[12:15], v[116:119], v[204:207], v[12:15]
	v_mfma_f32_16x16x32_bf16 v[16:19], v[124:127], v[204:207], v[16:19]
	v_mfma_f32_16x16x32_bf16 v[140:143], v[120:123], v[182:185], v[140:143]
	v_mfma_f32_16x16x32_bf16 v[144:147], v[128:131], v[182:185], v[144:147]
	v_mfma_f32_16x16x32_bf16 v[148:151], v[120:123], v[192:195], v[148:151]
	v_mfma_f32_16x16x32_bf16 v[152:155], v[128:131], v[192:195], v[152:155]
	v_mfma_f32_16x16x32_bf16 v[156:159], v[120:123], v[200:203], v[156:159]
	v_mfma_f32_16x16x32_bf16 v[160:163], v[128:131], v[200:203], v[160:163]
	v_mfma_f32_16x16x32_bf16 v[12:15], v[120:123], v[208:211], v[12:15]
	v_mfma_f32_16x16x32_bf16 v[16:19], v[128:131], v[208:211], v[16:19]
	v_mfma_f32_16x16x32_bf16 v[20:23], v[132:135], v[176:179], v[20:23]
	v_mfma_f32_16x16x32_bf16 v[24:27], v[164:167], v[176:179], v[24:27]
	v_mfma_f32_16x16x32_bf16 v[36:39], v[132:135], v[188:191], v[36:39]
	v_mfma_f32_16x16x32_bf16 v[40:43], v[164:167], v[188:191], v[40:43]
	v_mfma_f32_16x16x32_bf16 v[72:75], v[132:135], v[196:199], v[72:75]
	v_mfma_f32_16x16x32_bf16 v[112:115], v[164:167], v[196:199], v[112:115]
	v_mfma_f32_16x16x32_bf16 v[28:31], v[132:135], v[204:207], v[28:31]
	v_mfma_f32_16x16x32_bf16 v[32:35], v[164:167], v[204:207], v[32:35]
	v_mfma_f32_16x16x32_bf16 v[20:23], v[136:139], v[182:185], v[20:23]
	v_mfma_f32_16x16x32_bf16 v[24:27], v[168:171], v[182:185], v[24:27]
	v_mfma_f32_16x16x32_bf16 v[36:39], v[136:139], v[192:195], v[36:39]
	v_mfma_f32_16x16x32_bf16 v[40:43], v[168:171], v[192:195], v[40:43]
	v_mfma_f32_16x16x32_bf16 v[72:75], v[136:139], v[200:203], v[72:75]
	v_mfma_f32_16x16x32_bf16 v[112:115], v[168:171], v[200:203], v[112:115]
	v_mfma_f32_16x16x32_bf16 v[28:31], v[136:139], v[208:211], v[28:31]
	v_mfma_f32_16x16x32_bf16 v[32:35], v[168:171], v[208:211], v[32:35]
	s_setprio 0
	s_barrier
; #define G_BAR __builtin_amdgcn_s_barrier()
; template <int NSTORE, class TF, class F>
; DEVI void gemm_run(const bf16_t* __restrict__ A, int lda, const bf16_t* __restrict__ Bt, int ldb, int K, bf16_t* shm, TF&& tile, F&& emit) {
;     ...
;         if (NSTORE != 0 && wr == 0) G_BAR;
; #pragma unroll
;         for (int ai = 0; ai < 2; ++ai)
; #pragma unroll
;             for (int m = 0; m < 4; ++m)
; #pragma unroll
;                 for (int bj = 0; bj < 2; ++bj)
;                     emit(brow + ai * HALF + wr * 64 + m * 16 + fr, bcol + bj * HALF + wc * 32 + fq * 8, acc[ai][bj][m][0], acc[ai][bj][m][1]);
;         if (!has_next) break;
; #pragma unroll
;         for (int a = 0; a < 2; ++a)
; #pragma unroll
;             for (int b = 0; b < 2; ++b)
; #pragma unroll
;                 for (int m = 0; m < 4; ++m)
; #pragma unroll
;                     for (int n = 0; n < 2; ++n) acc[a][b][m][n] = (f32x4){0.f, 0.f, 0.f, 0.f};
;         brow = nrow; bcol = ncol; cA = nA; cB = nB; ++ui;
	v_add_u32_e32 v116, s74, v8
	v_add_u32_e32 v118, s75, v11
	v_ashrrev_i32_e32 v117, 31, v116
	v_readlane_b32 s28, v252, 10
	v_lshlrev_b64 v[120:121], 11, v[116:117]
	v_readlane_b32 s29, v252, 11
	v_ashrrev_i32_e32 v119, 31, v118
	v_lshlrev_b64 v[118:119], 1, v[118:119]
	v_lshl_add_u64 v[120:121], s[28:29], 0, v[120:121]
	v_lshl_add_u64 v[120:121], v[120:121], 0, v[118:119]
	v_cvt_pk_bf16_f32 v76, v76, v77
	v_cvt_pk_bf16_f32 v77, v78, v79
	v_cvt_pk_bf16_f32 v78, v80, v81
	v_cvt_pk_bf16_f32 v79, v82, v83
	global_store_dwordx4 v[120:121], v[76:79], off
	v_cvt_pk_bf16_f32 v20, v20, v21
	v_cvt_pk_bf16_f32 v21, v22, v23
	v_cvt_pk_bf16_f32 v78, v44, v45
	v_add_u32_e32 v44, 16, v116
	v_ashrrev_i32_e32 v45, 31, v44
	v_lshlrev_b64 v[44:45], 11, v[44:45]
	v_cvt_pk_bf16_f32 v76, v108, v109
	v_cvt_pk_bf16_f32 v77, v110, v111
	v_cvt_pk_bf16_f32 v79, v46, v47
	v_lshl_add_u64 v[44:45], s[28:29], 0, v[44:45]
	global_store_dwordx4 v[120:121], v[76:79], off offset:256
	v_cvt_pk_bf16_f32 v46, v88, v89
	v_cvt_pk_bf16_f32 v47, v90, v91
	v_lshl_add_u64 v[76:77], v[44:45], 0, v[118:119]
	v_cvt_pk_bf16_f32 v44, v84, v85
	v_cvt_pk_bf16_f32 v45, v86, v87
	global_store_dwordx4 v[76:77], v[44:47], off
	v_cvt_pk_bf16_f32 v22, v24, v25
	v_cvt_pk_bf16_f32 v23, v26, v27
	v_cvt_pk_bf16_f32 v44, v48, v49
	v_cvt_pk_bf16_f32 v45, v50, v51
	v_cvt_pk_bf16_f32 v46, v52, v53
	v_cvt_pk_bf16_f32 v47, v54, v55
	global_store_dwordx4 v[76:77], v[44:47], off offset:256
	v_cvt_pk_bf16_f32 v12, v12, v13
	v_cvt_pk_bf16_f32 v13, v14, v15
	v_add_u32_e32 v44, 32, v116
	v_ashrrev_i32_e32 v45, 31, v44
	v_lshlrev_b64 v[44:45], 11, v[44:45]
	v_lshl_add_u64 v[44:45], s[28:29], 0, v[44:45]
	v_lshl_add_u64 v[48:49], v[44:45], 0, v[118:119]
	v_cvt_pk_bf16_f32 v44, v92, v93
	v_cvt_pk_bf16_f32 v45, v94, v95
	v_cvt_pk_bf16_f32 v46, v96, v97
	v_cvt_pk_bf16_f32 v47, v98, v99
	global_store_dwordx4 v[48:49], v[44:47], off
	v_cvt_pk_bf16_f32 v14, v16, v17
	v_cvt_pk_bf16_f32 v15, v18, v19
	v_cvt_pk_bf16_f32 v44, v56, v57
	v_cvt_pk_bf16_f32 v45, v58, v59
	v_cvt_pk_bf16_f32 v46, v60, v61
	v_cvt_pk_bf16_f32 v47, v62, v63
	global_store_dwordx4 v[48:49], v[44:47], off offset:256
	s_andn2_b64 vcc, exec, s[0:1]
	s_mov_b32 s74, s73
	v_add_u32_e32 v44, 48, v116
	v_ashrrev_i32_e32 v45, 31, v44
	v_lshlrev_b64 v[44:45], 11, v[44:45]
	v_lshl_add_u64 v[44:45], s[28:29], 0, v[44:45]
	v_lshl_add_u64 v[48:49], v[44:45], 0, v[118:119]
	v_cvt_pk_bf16_f32 v44, v100, v101
	v_cvt_pk_bf16_f32 v45, v102, v103
	v_cvt_pk_bf16_f32 v46, v104, v105
	v_cvt_pk_bf16_f32 v47, v106, v107
	global_store_dwordx4 v[48:49], v[44:47], off
	s_mov_b32 s75, s38
	s_mov_b64 s[68:69], s[42:43]
	v_cvt_pk_bf16_f32 v44, v64, v65
	v_cvt_pk_bf16_f32 v45, v66, v67
	v_cvt_pk_bf16_f32 v46, v68, v69
	v_cvt_pk_bf16_f32 v47, v70, v71
	global_store_dwordx4 v[48:49], v[44:47], off offset:256
	s_mov_b64 s[46:47], s[40:41]
	s_nop 0
	v_add_u32_e32 v44, 0x80, v116
	v_ashrrev_i32_e32 v45, 31, v44
	v_lshlrev_b64 v[44:45], 11, v[44:45]
	v_lshl_add_u64 v[44:45], s[28:29], 0, v[44:45]
	v_lshl_add_u64 v[48:49], v[44:45], 0, v[118:119]
	global_store_dwordx4 v[48:49], v[20:23], off offset:256
	v_cvt_pk_bf16_f32 v44, v140, v141
	v_cvt_pk_bf16_f32 v45, v142, v143
	v_add_u32_e32 v20, 0x90, v116
	v_ashrrev_i32_e32 v21, 31, v20
	v_lshlrev_b64 v[20:21], 11, v[20:21]
	v_lshl_add_u64 v[20:21], s[28:29], 0, v[20:21]
	v_lshl_add_u64 v[24:25], v[20:21], 0, v[118:119]
	v_cvt_pk_bf16_f32 v20, v148, v149
	v_cvt_pk_bf16_f32 v21, v150, v151
	v_cvt_pk_bf16_f32 v22, v152, v153
	v_cvt_pk_bf16_f32 v23, v154, v155
	global_store_dwordx4 v[24:25], v[20:23], off
	v_cvt_pk_bf16_f32 v46, v144, v145
	v_cvt_pk_bf16_f32 v47, v146, v147
	v_cvt_pk_bf16_f32 v20, v36, v37
	v_cvt_pk_bf16_f32 v21, v38, v39
	v_cvt_pk_bf16_f32 v22, v40, v41
	v_cvt_pk_bf16_f32 v23, v42, v43
	global_store_dwordx4 v[24:25], v[20:23], off offset:256
	global_store_dwordx4 v[48:49], v[44:47], off
	s_nop 0
	v_add_u32_e32 v20, 0xa0, v116
	v_ashrrev_i32_e32 v21, 31, v20
	v_lshlrev_b64 v[20:21], 11, v[20:21]
	v_lshl_add_u64 v[20:21], s[28:29], 0, v[20:21]
	v_lshl_add_u64 v[24:25], v[20:21], 0, v[118:119]
	v_cvt_pk_bf16_f32 v20, v156, v157
	v_cvt_pk_bf16_f32 v21, v158, v159
	v_cvt_pk_bf16_f32 v22, v160, v161
	v_cvt_pk_bf16_f32 v23, v162, v163
	global_store_dwordx4 v[24:25], v[20:23], off
	s_nop 1
	v_cvt_pk_bf16_f32 v20, v72, v73
	v_cvt_pk_bf16_f32 v21, v74, v75
	v_cvt_pk_bf16_f32 v22, v112, v113
	v_cvt_pk_bf16_f32 v23, v114, v115
	global_store_dwordx4 v[24:25], v[20:23], off offset:256
	s_nop 1
	v_add_u32_e32 v20, 0xb0, v116
	v_ashrrev_i32_e32 v21, 31, v20
	v_lshlrev_b64 v[20:21], 11, v[20:21]
	v_lshl_add_u64 v[20:21], s[28:29], 0, v[20:21]
	v_lshl_add_u64 v[20:21], v[20:21], 0, v[118:119]
	global_store_dwordx4 v[20:21], v[12:15], off
	s_nop 1
	v_cvt_pk_bf16_f32 v12, v28, v29
	v_cvt_pk_bf16_f32 v13, v30, v31
	v_cvt_pk_bf16_f32 v14, v32, v33
	v_cvt_pk_bf16_f32 v15, v34, v35
	global_store_dwordx4 v[20:21], v[12:15], off offset:256
	s_cbranch_vccz .LBB0_343

; #define G_STAGE(bufoff, gbase, voff) do { _Pragma("unroll") for (int _i = 0; _i < 2; ++_i) \
;         __builtin_amdgcn_global_load_lds((const unsigned*)((const char*)(gbase) + (voff)[_i]), (LAS unsigned*)(lds + (bufoff) + ldsw + _i * 8192), 16, 0, 0); } while (0)
; #define G_LDA(dst, b, h) do { _Pragma("unroll") for (int m = 0; m < 4; ++m) _Pragma("unroll") for (int k = 0; k < 2; ++k) dst[m][k] = *(const LAS bf16x8*)(lds + G_SA(b, h) + aoff + m * 2048 + k * 1024); } while (0)
; #define G_LDB(dst, b, h) do { _Pragma("unroll") for (int n = 0; n < 2; ++n) _Pragma("unroll") for (int k = 0; k < 2; ++k) dst[n][k] = *(const LAS bf16x8*)(lds + G_SB(b, h) + boff + n * 2048 + k * 1024); } while (0)
; #define G_MMA(ai, bj, At, Bt_) do { __builtin_amdgcn_s_setprio(1); _Pragma("unroll") for (int m = 0; m < 4; ++m) _Pragma("unroll") for (int n = 0; n < 2; ++n) _Pragma("unroll") for (int k = 0; k < 2; ++k) \
;         acc[ai][bj][m][n] = __builtin_amdgcn_mfma_f32_16x16x32_bf16(Bt_[n][k], At[m][k], acc[ai][bj][m][n], 0, 0, 0); __builtin_amdgcn_s_setprio(0); } while (0)
; #define G_WAIT_V(n) asm volatile("s_waitcnt vmcnt(" #n ")" ::: "memory")
; template <int NSTORE, class TF, class F>
; DEVI void gemm_run(const bf16_t* __restrict__ A, int lda, const bf16_t* __restrict__ Bt, int ldb, int K, bf16_t* shm, TF&& tile, F&& emit) {
;     ...
;     for (;;) {
;         const bool has_next = tile(ui + 1, nrow, ncol);
;         const char* nA = has_next ? (const char*)A + (size_t)nrow * lda * 2 : cA; const char* nB = has_next ? (const char*)Bt + (size_t)ncol * ldb * 2 : cB;
;         for (int t = 0; t < nt; t += 2) {
;             const bool last = (t == nt - 2);
;             const char* a1 = cA + (size_t)(t + 1) * kstep;
;             const char* a2 = last ? nA : cA + (size_t)(t + 2) * kstep; const char* b2 = last ? nB : cB + (size_t)(t + 2) * kstep;
;             const char* a3 = a2 + kstep; const char* b3 = b2 + kstep;
;             G_LDB(B0, 0, 0); G_LDB(B1, 0, 1); G_SCHED; G_LDA(At, 0, 0); G_STAGE(G_SA(1, 1), a1 + hstepA, voffA);
;             G_WAIT_V(8); G_WAIT_L(0); G_BAR; G_MMA(0, 0, At, B0); G_MMA(0, 1, At, B1); G_BAR; G_SCHED;
;             G_LDA(At, 0, 1); G_STAGE(G_SB(0, 0), b2, voffB); G_STAGE(G_SB(0, 1), b2 + hstepB, voffB); G_STAGE(G_SA(0, 0), a2, voffA);
;             G_WAIT_V(8); G_WAIT_L(0); G_BAR; G_MMA(1, 0, At, B0); G_MMA(1, 1, At, B1); G_BAR; G_SCHED;
.LBB0_350:
	v_or_b32_e32 v20, 0x10000, v18
	v_add_u32_e32 v22, 0x10800, v18
	v_or_b32_e32 v24, 0x14000, v18
	v_add_u32_e32 v26, 0x14800, v18
	v_add_u32_e32 v21, 0x10400, v18
	ds_read_b128 v[28:31], v20
	ds_read_b128 v[32:35], v21
	v_add_u32_e32 v23, 0x10c00, v18
	ds_read_b128 v[36:39], v22
	ds_read_b128 v[40:43], v23
	v_add_u32_e32 v25, 0x14400, v18
	ds_read_b128 v[44:47], v24
	ds_read_b128 v[48:51], v25
	v_add_u32_e32 v27, 0x14c00, v18
	ds_read_b128 v[52:55], v26
	ds_read_b128 v[56:59], v27
	s_add_u32 s28, s42, 0x70080
	s_addc_u32 s29, s43, 0
	s_add_i32 s73, s8, 0xc000
	v_lshl_add_u64 v[84:85], s[28:29], 0, v[6:7]
	s_mov_b32 m0, s73
	s_add_i32 s72, s8, 0xe000
	ds_read_b128 v[8:11], v17
	ds_read_b128 v[12:15], v17 offset:1024
	ds_read_b128 v[60:63], v17 offset:2048
	ds_read_b128 v[64:67], v17 offset:3072
	ds_read_b128 v[68:71], v17 offset:4096
	ds_read_b128 v[72:75], v17 offset:5120
	ds_read_b128 v[76:79], v17 offset:6144
	ds_read_b128 v[80:83], v17 offset:7168
	global_load_lds_dwordx4 v[84:85], off
	v_lshl_add_u64 v[84:85], s[28:29], 0, v[4:5]
	s_mov_b32 m0, s72
	s_nop 0
	global_load_lds_dwordx4 v[84:85], off
	s_waitcnt vmcnt(8)
	s_waitcnt lgkmcnt(0)
	s_barrier
	s_setprio 1
	s_waitcnt lgkmcnt(0)
	v_mfma_f32_16x16x32_bf16 v[84:87], v[28:31], v[8:11], 0
	v_mfma_f32_16x16x32_bf16 v[88:91], v[36:39], v[8:11], 0
	v_mfma_f32_16x16x32_bf16 v[92:95], v[28:31], v[60:63], 0
	v_mfma_f32_16x16x32_bf16 v[96:99], v[36:39], v[60:63], 0
	v_mfma_f32_16x16x32_bf16 v[100:103], v[28:31], v[68:71], 0
	v_mfma_f32_16x16x32_bf16 v[104:107], v[36:39], v[68:71], 0
	v_mfma_f32_16x16x32_bf16 v[108:111], v[28:31], v[76:79], 0
	v_mfma_f32_16x16x32_bf16 v[112:115], v[36:39], v[76:79], 0
	v_mfma_f32_16x16x32_bf16 v[84:87], v[32:35], v[12:15], v[84:87]
	v_mfma_f32_16x16x32_bf16 v[88:91], v[40:43], v[12:15], v[88:91]
	v_mfma_f32_16x16x32_bf16 v[92:95], v[32:35], v[64:67], v[92:95]
	v_mfma_f32_16x16x32_bf16 v[96:99], v[40:43], v[64:67], v[96:99]
	v_mfma_f32_16x16x32_bf16 v[100:103], v[32:35], v[72:75], v[100:103]
	v_mfma_f32_16x16x32_bf16 v[104:107], v[40:43], v[72:75], v[104:107]
	v_mfma_f32_16x16x32_bf16 v[108:111], v[32:35], v[80:83], v[108:111]
	v_mfma_f32_16x16x32_bf16 v[112:115], v[40:43], v[80:83], v[112:115]
	v_mfma_f32_16x16x32_bf16 v[116:119], v[44:47], v[8:11], 0
	v_mfma_f32_16x16x32_bf16 v[8:11], v[52:55], v[8:11], 0
	v_mfma_f32_16x16x32_bf16 v[120:123], v[56:59], v[12:15], v[8:11]
	v_mfma_f32_16x16x32_bf16 v[8:11], v[44:47], v[60:63], 0
	v_mfma_f32_16x16x32_bf16 v[124:127], v[48:51], v[64:67], v[8:11]
	v_mfma_f32_16x16x32_bf16 v[8:11], v[52:55], v[60:63], 0
	v_mfma_f32_16x16x32_bf16 v[60:63], v[56:59], v[64:67], v[8:11]
	v_mfma_f32_16x16x32_bf16 v[8:11], v[44:47], v[68:71], 0
	v_mfma_f32_16x16x32_bf16 v[64:67], v[48:51], v[72:75], v[8:11]
	v_mfma_f32_16x16x32_bf16 v[8:11], v[52:55], v[68:71], 0
	v_mfma_f32_16x16x32_bf16 v[68:71], v[56:59], v[72:75], v[8:11]
	v_mfma_f32_16x16x32_bf16 v[8:11], v[44:47], v[76:79], 0
	v_mfma_f32_16x16x32_bf16 v[72:75], v[48:51], v[80:83], v[8:11]
	v_mfma_f32_16x16x32_bf16 v[8:11], v[52:55], v[76:79], 0
	v_mfma_f32_16x16x32_bf16 v[116:119], v[48:51], v[12:15], v[116:119]
	v_mfma_f32_16x16x32_bf16 v[76:79], v[56:59], v[80:83], v[8:11]
	s_setprio 0
	s_barrier
	s_nop 3
	v_lshl_add_u64 v[8:9], s[44:45], 0, v[0:1]
	s_mov_b32 m0, s9
	v_lshl_add_u64 v[10:11], v[8:9], 0, s[4:5]
	ds_read_b128 v[80:83], v17 offset:16384
	ds_read_b128 v[128:131], v17 offset:17408
	ds_read_b128 v[132:135], v17 offset:18432
	ds_read_b128 v[136:139], v17 offset:19456
	ds_read_b128 v[140:143], v17 offset:20480
	ds_read_b128 v[144:147], v17 offset:21504
	ds_read_b128 v[148:151], v17 offset:22528
	ds_read_b128 v[152:155], v17 offset:23552
	global_load_lds_dwordx4 v[10:11], off
	v_lshl_add_u64 v[10:11], s[44:45], 0, v[2:3]
	s_add_u32 s28, s44, 0x18100
	v_lshl_add_u64 v[12:13], v[10:11], 0, s[4:5]
	s_mov_b32 m0, s15
	s_addc_u32 s29, s45, 0
	global_load_lds_dwordx4 v[12:13], off
	v_lshl_add_u64 v[12:13], s[28:29], 0, v[0:1]
	s_mov_b32 m0, s16
	s_nop 0
	global_load_lds_dwordx4 v[12:13], off
	v_lshl_add_u64 v[12:13], s[28:29], 0, v[2:3]
	s_mov_b32 m0, s17
	s_nop 0
	global_load_lds_dwordx4 v[12:13], off
	v_lshl_add_u64 v[12:13], s[42:43], 0, v[6:7]
	v_lshl_add_u64 v[14:15], v[12:13], 0, s[4:5]
	s_mov_b32 m0, s8
	s_nop 0
	global_load_lds_dwordx4 v[14:15], off
	v_lshl_add_u64 v[14:15], s[42:43], 0, v[4:5]
	v_lshl_add_u64 v[156:157], v[14:15], 0, s[4:5]
	s_mov_b32 m0, s18
	s_nop 0
	global_load_lds_dwordx4 v[156:157], off
	s_waitcnt vmcnt(8)
	s_waitcnt lgkmcnt(0)
	s_barrier
	s_setprio 1
	s_waitcnt lgkmcnt(0)
	v_mfma_f32_16x16x32_bf16 v[156:159], v[28:31], v[80:83], 0
	v_mfma_f32_16x16x32_bf16 v[164:167], v[28:31], v[132:135], 0
	v_mfma_f32_16x16x32_bf16 v[176:179], v[28:31], v[140:143], 0
	v_mfma_f32_16x16x32_bf16 v[28:31], v[28:31], v[148:151], 0
	v_mfma_f32_16x16x32_bf16 v[160:163], v[36:39], v[80:83], 0
	v_mfma_f32_16x16x32_bf16 v[168:171], v[36:39], v[132:135], 0
	v_mfma_f32_16x16x32_bf16 v[182:185], v[36:39], v[140:143], 0
	v_mfma_f32_16x16x32_bf16 v[188:191], v[32:35], v[152:155], v[28:31]
	v_mfma_f32_16x16x32_bf16 v[28:31], v[36:39], v[148:151], 0
	v_mfma_f32_16x16x32_bf16 v[156:159], v[32:35], v[128:131], v[156:159]
	v_mfma_f32_16x16x32_bf16 v[160:163], v[40:43], v[128:131], v[160:163]
	v_mfma_f32_16x16x32_bf16 v[164:167], v[32:35], v[136:139], v[164:167]
	v_mfma_f32_16x16x32_bf16 v[168:171], v[40:43], v[136:139], v[168:171]
	v_mfma_f32_16x16x32_bf16 v[176:179], v[32:35], v[144:147], v[176:179]
	v_mfma_f32_16x16x32_bf16 v[182:185], v[40:43], v[144:147], v[182:185]
	v_mfma_f32_16x16x32_bf16 v[36:39], v[40:43], v[152:155], v[28:31]
	v_mfma_f32_16x16x32_bf16 v[28:31], v[44:47], v[80:83], 0
	v_mfma_f32_16x16x32_bf16 v[40:43], v[48:51], v[128:131], v[28:31]
	v_mfma_f32_16x16x32_bf16 v[28:31], v[52:55], v[80:83], 0
	v_mfma_f32_16x16x32_bf16 v[80:83], v[56:59], v[128:131], v[28:31]
	v_mfma_f32_16x16x32_bf16 v[28:31], v[44:47], v[132:135], 0
	v_mfma_f32_16x16x32_bf16 v[128:131], v[48:51], v[136:139], v[28:31]
	v_mfma_f32_16x16x32_bf16 v[28:31], v[52:55], v[132:135], 0
	v_mfma_f32_16x16x32_bf16 v[132:135], v[56:59], v[136:139], v[28:31]
	v_mfma_f32_16x16x32_bf16 v[28:31], v[44:47], v[140:143], 0
	v_mfma_f32_16x16x32_bf16 v[136:139], v[48:51], v[144:147], v[28:31]
	v_mfma_f32_16x16x32_bf16 v[28:31], v[52:55], v[140:143], 0
	v_mfma_f32_16x16x32_bf16 v[140:143], v[56:59], v[144:147], v[28:31]
	v_mfma_f32_16x16x32_bf16 v[28:31], v[44:47], v[148:151], 0
	v_mfma_f32_16x16x32_bf16 v[44:47], v[48:51], v[152:155], v[28:31]
	v_mfma_f32_16x16x32_bf16 v[28:31], v[52:55], v[148:151], 0
	v_mfma_f32_16x16x32_bf16 v[48:51], v[56:59], v[152:155], v[28:31]
	s_setprio 0
	s_barrier
; #define G_STAGE(bufoff, gbase, voff) do { _Pragma("unroll") for (int _i = 0; _i < 2; ++_i) \
;         __builtin_amdgcn_global_load_lds((const unsigned*)((const char*)(gbase) + (voff)[_i]), (LAS unsigned*)(lds + (bufoff) + ldsw + _i * 8192), 16, 0, 0); } while (0)
; #define G_LDA(dst, b, h) do { _Pragma("unroll") for (int m = 0; m < 4; ++m) _Pragma("unroll") for (int k = 0; k < 2; ++k) dst[m][k] = *(const LAS bf16x8*)(lds + G_SA(b, h) + aoff + m * 2048 + k * 1024); } while (0)
; #define G_LDB(dst, b, h) do { _Pragma("unroll") for (int n = 0; n < 2; ++n) _Pragma("unroll") for (int k = 0; k < 2; ++k) dst[n][k] = *(const LAS bf16x8*)(lds + G_SB(b, h) + boff + n * 2048 + k * 1024); } while (0)
; #define G_MMA(ai, bj, At, Bt_) do { __builtin_amdgcn_s_setprio(1); _Pragma("unroll") for (int m = 0; m < 4; ++m) _Pragma("unroll") for (int n = 0; n < 2; ++n) _Pragma("unroll") for (int k = 0; k < 2; ++k) \
;         acc[ai][bj][m][n] = __builtin_amdgcn_mfma_f32_16x16x32_bf16(Bt_[n][k], At[m][k], acc[ai][bj][m][n], 0, 0, 0); __builtin_amdgcn_s_setprio(0); } while (0)
; #define G_WAIT_V(n) asm volatile("s_waitcnt vmcnt(" #n ")" ::: "memory")
; #define G_WAIT_L(n) asm volatile("s_waitcnt lgkmcnt(" #n ")" ::: "memory")
; #define G_BAR __builtin_amdgcn_s_barrier()
; #define G_SCHED __builtin_amdgcn_sched_barrier(0)
; template <int NSTORE, class TF, class F>
; DEVI void gemm_run(const bf16_t* __restrict__ A, int lda, const bf16_t* __restrict__ Bt, int ldb, int K, bf16_t* shm, TF&& tile, F&& emit) {
;     ...
;             G_LDB(B0, 1, 0); G_LDB(B1, 1, 1); G_SCHED; G_LDA(At, 1, 0); G_STAGE(G_SA(0, 1), a2 + hstepA, voffA);
;             G_WAIT_V(8); G_WAIT_L(0); G_BAR; G_MMA(0, 0, At, B0); G_MMA(0, 1, At, B1); G_BAR; G_SCHED;
;             G_LDA(At, 1, 1); G_STAGE(G_SB(1, 0), b3, voffB); G_STAGE(G_SB(1, 1), b3 + hstepB, voffB); G_STAGE(G_SA(1, 0), a3, voffA);
	s_nop 4
	v_or_b32_e32 v28, 0x18000, v18
	v_add_u32_e32 v30, 0x18800, v18
	v_or_b32_e32 v32, 0x1c000, v18
	v_add_u32_e32 v34, 0x1c800, v18
	v_add_u32_e32 v29, 0x18400, v18
	ds_read_b128 v[52:55], v28
	ds_read_b128 v[56:59], v29
	v_add_u32_e32 v31, 0x18c00, v18
	ds_read_b128 v[144:147], v30
	ds_read_b128 v[148:151], v31
	v_add_u32_e32 v33, 0x1c400, v18
	ds_read_b128 v[152:155], v32
	ds_read_b128 v[192:195], v33
	v_add_u32_e32 v35, 0x1cc00, v18
	ds_read_b128 v[196:199], v34
	ds_read_b128 v[200:203], v35
	s_add_u32 s28, s42, 0x70100
	s_addc_u32 s29, s43, 0
	s_mov_b32 m0, s19
	v_lshl_add_u64 v[236:237], s[28:29], 0, v[6:7]
	ds_read_b128 v[204:207], v17 offset:32768
	ds_read_b128 v[208:211], v17 offset:33792
	ds_read_b128 v[212:215], v17 offset:34816
	ds_read_b128 v[216:219], v17 offset:35840
	ds_read_b128 v[220:223], v17 offset:36864
	ds_read_b128 v[224:227], v17 offset:37888
	ds_read_b128 v[228:231], v17 offset:38912
	ds_read_b128 v[232:235], v17 offset:39936
	global_load_lds_dwordx4 v[236:237], off
	v_lshl_add_u64 v[236:237], s[28:29], 0, v[4:5]
	s_mov_b32 m0, s26
	s_nop 0
	global_load_lds_dwordx4 v[236:237], off
	s_waitcnt vmcnt(8)
	s_waitcnt lgkmcnt(0)
	s_barrier
	s_setprio 1
	s_waitcnt lgkmcnt(0)
	v_mfma_f32_16x16x32_bf16 v[84:87], v[52:55], v[204:207], v[84:87]
	v_mfma_f32_16x16x32_bf16 v[88:91], v[144:147], v[204:207], v[88:91]
	v_mfma_f32_16x16x32_bf16 v[92:95], v[52:55], v[212:215], v[92:95]
	v_mfma_f32_16x16x32_bf16 v[96:99], v[144:147], v[212:215], v[96:99]
	v_mfma_f32_16x16x32_bf16 v[100:103], v[52:55], v[220:223], v[100:103]
	v_mfma_f32_16x16x32_bf16 v[104:107], v[144:147], v[220:223], v[104:107]
	v_mfma_f32_16x16x32_bf16 v[108:111], v[52:55], v[228:231], v[108:111]
	v_mfma_f32_16x16x32_bf16 v[112:115], v[144:147], v[228:231], v[112:115]
	v_mfma_f32_16x16x32_bf16 v[84:87], v[56:59], v[208:211], v[84:87]
	v_mfma_f32_16x16x32_bf16 v[88:91], v[148:151], v[208:211], v[88:91]
	v_mfma_f32_16x16x32_bf16 v[92:95], v[56:59], v[216:219], v[92:95]
	v_mfma_f32_16x16x32_bf16 v[96:99], v[148:151], v[216:219], v[96:99]
	v_mfma_f32_16x16x32_bf16 v[100:103], v[56:59], v[224:227], v[100:103]
	v_mfma_f32_16x16x32_bf16 v[104:107], v[148:151], v[224:227], v[104:107]
	v_mfma_f32_16x16x32_bf16 v[108:111], v[56:59], v[232:235], v[108:111]
	v_mfma_f32_16x16x32_bf16 v[112:115], v[148:151], v[232:235], v[112:115]
	v_mfma_f32_16x16x32_bf16 v[116:119], v[152:155], v[204:207], v[116:119]
	v_mfma_f32_16x16x32_bf16 v[120:123], v[196:199], v[204:207], v[120:123]
	v_mfma_f32_16x16x32_bf16 v[124:127], v[152:155], v[212:215], v[124:127]
	v_mfma_f32_16x16x32_bf16 v[60:63], v[196:199], v[212:215], v[60:63]
	v_mfma_f32_16x16x32_bf16 v[64:67], v[152:155], v[220:223], v[64:67]
	v_mfma_f32_16x16x32_bf16 v[68:71], v[196:199], v[220:223], v[68:71]
	v_mfma_f32_16x16x32_bf16 v[72:75], v[152:155], v[228:231], v[72:75]
	v_mfma_f32_16x16x32_bf16 v[76:79], v[196:199], v[228:231], v[76:79]
	v_mfma_f32_16x16x32_bf16 v[116:119], v[192:195], v[208:211], v[116:119]
	v_mfma_f32_16x16x32_bf16 v[120:123], v[200:203], v[208:211], v[120:123]
	v_mfma_f32_16x16x32_bf16 v[124:127], v[192:195], v[216:219], v[124:127]
	v_mfma_f32_16x16x32_bf16 v[60:63], v[200:203], v[216:219], v[60:63]
	v_mfma_f32_16x16x32_bf16 v[64:67], v[192:195], v[224:227], v[64:67]
	v_mfma_f32_16x16x32_bf16 v[68:71], v[200:203], v[224:227], v[68:71]
	v_mfma_f32_16x16x32_bf16 v[72:75], v[192:195], v[232:235], v[72:75]
	v_mfma_f32_16x16x32_bf16 v[76:79], v[200:203], v[232:235], v[76:79]
	s_setprio 0
	s_barrier
	s_mov_b64 s[36:37], 0x180
	s_mov_b32 m0, s27
	v_lshl_add_u64 v[236:237], v[8:9], 0, s[36:37]
	s_add_u32 s28, s44, 0x18180
	ds_read_b128 v[204:207], v17 offset:49152
	ds_read_b128 v[208:211], v17 offset:50176
	ds_read_b128 v[212:215], v17 offset:51200
	ds_read_b128 v[216:219], v17 offset:52224
	ds_read_b128 v[220:223], v17 offset:53248
	ds_read_b128 v[224:227], v17 offset:54272
	ds_read_b128 v[228:231], v17 offset:55296
	ds_read_b128 v[232:235], v17 offset:56320
	global_load_lds_dwordx4 v[236:237], off
	v_lshl_add_u64 v[236:237], v[10:11], 0, s[36:37]
	s_mov_b32 m0, s46
	s_addc_u32 s29, s45, 0
	global_load_lds_dwordx4 v[236:237], off
	v_lshl_add_u64 v[236:237], s[28:29], 0, v[0:1]
	s_mov_b32 m0, s49
	s_nop 0
	global_load_lds_dwordx4 v[236:237], off
	v_lshl_add_u64 v[236:237], s[28:29], 0, v[2:3]
	s_mov_b32 m0, s68
	s_nop 0
	global_load_lds_dwordx4 v[236:237], off
	v_lshl_add_u64 v[236:237], v[12:13], 0, s[36:37]
	s_mov_b32 m0, s47
	s_nop 0
	global_load_lds_dwordx4 v[236:237], off
	v_lshl_add_u64 v[236:237], v[14:15], 0, s[36:37]
	s_mov_b32 m0, s48
	s_nop 0
	global_load_lds_dwordx4 v[236:237], off
	s_waitcnt vmcnt(8)
	s_waitcnt lgkmcnt(0)
	s_barrier
; #define G_STAGE(bufoff, gbase, voff) do { _Pragma("unroll") for (int _i = 0; _i < 2; ++_i) \
;         __builtin_amdgcn_global_load_lds((const unsigned*)((const char*)(gbase) + (voff)[_i]), (LAS unsigned*)(lds + (bufoff) + ldsw + _i * 8192), 16, 0, 0); } while (0)
; #define G_LDA(dst, b, h) do { _Pragma("unroll") for (int m = 0; m < 4; ++m) _Pragma("unroll") for (int k = 0; k < 2; ++k) dst[m][k] = *(const LAS bf16x8*)(lds + G_SA(b, h) + aoff + m * 2048 + k * 1024); } while (0)
; #define G_LDB(dst, b, h) do { _Pragma("unroll") for (int n = 0; n < 2; ++n) _Pragma("unroll") for (int k = 0; k < 2; ++k) dst[n][k] = *(const LAS bf16x8*)(lds + G_SB(b, h) + boff + n * 2048 + k * 1024); } while (0)
; #define G_MMA(ai, bj, At, Bt_) do { __builtin_amdgcn_s_setprio(1); _Pragma("unroll") for (int m = 0; m < 4; ++m) _Pragma("unroll") for (int n = 0; n < 2; ++n) _Pragma("unroll") for (int k = 0; k < 2; ++k) \
;         acc[ai][bj][m][n] = __builtin_amdgcn_mfma_f32_16x16x32_bf16(Bt_[n][k], At[m][k], acc[ai][bj][m][n], 0, 0, 0); __builtin_amdgcn_s_setprio(0); } while (0)
; #define G_WAIT_V(n) asm volatile("s_waitcnt vmcnt(" #n ")" ::: "memory")
; #define G_WAIT_L(n) asm volatile("s_waitcnt lgkmcnt(" #n ")" ::: "memory")
; #define G_BAR __builtin_amdgcn_s_barrier()
; #define G_SCHED __builtin_amdgcn_sched_barrier(0)
; template <int NSTORE, class TF, class F>
; DEVI void gemm_run(const bf16_t* __restrict__ A, int lda, const bf16_t* __restrict__ Bt, int ldb, int K, bf16_t* shm, TF&& tile, F&& emit) {
;     ...
;             G_LDB(B0, 0, 0); G_LDB(B1, 0, 1); G_SCHED; G_LDA(At, 0, 0); G_STAGE(G_SA(1, 1), a1 + hstepA, voffA);
;             G_WAIT_V(8); G_WAIT_L(0); G_BAR; G_MMA(0, 0, At, B0); G_MMA(0, 1, At, B1); G_BAR; G_SCHED;
;     ...
;             G_WAIT_V(8); G_WAIT_L(0); G_BAR; G_MMA(1, 0, At, B0); G_MMA(1, 1, At, B1); G_BAR; G_SCHED;
	s_setprio 1
	s_waitcnt lgkmcnt(0)
	v_mfma_f32_16x16x32_bf16 v[156:159], v[52:55], v[204:207], v[156:159]
	v_mfma_f32_16x16x32_bf16 v[160:163], v[144:147], v[204:207], v[160:163]
	v_mfma_f32_16x16x32_bf16 v[164:167], v[52:55], v[212:215], v[164:167]
	v_mfma_f32_16x16x32_bf16 v[168:171], v[144:147], v[212:215], v[168:171]
	v_mfma_f32_16x16x32_bf16 v[176:179], v[52:55], v[220:223], v[176:179]
	v_mfma_f32_16x16x32_bf16 v[182:185], v[144:147], v[220:223], v[182:185]
	v_mfma_f32_16x16x32_bf16 v[52:55], v[52:55], v[228:231], v[188:191]
	v_mfma_f32_16x16x32_bf16 v[36:39], v[144:147], v[228:231], v[36:39]
	v_mfma_f32_16x16x32_bf16 v[156:159], v[56:59], v[208:211], v[156:159]
	v_mfma_f32_16x16x32_bf16 v[160:163], v[148:151], v[208:211], v[160:163]
	v_mfma_f32_16x16x32_bf16 v[164:167], v[56:59], v[216:219], v[164:167]
	v_mfma_f32_16x16x32_bf16 v[168:171], v[148:151], v[216:219], v[168:171]
	v_mfma_f32_16x16x32_bf16 v[176:179], v[56:59], v[224:227], v[176:179]
	v_mfma_f32_16x16x32_bf16 v[182:185], v[148:151], v[224:227], v[182:185]
	v_mfma_f32_16x16x32_bf16 v[52:55], v[56:59], v[232:235], v[52:55]
	v_mfma_f32_16x16x32_bf16 v[36:39], v[148:151], v[232:235], v[36:39]
	v_mfma_f32_16x16x32_bf16 v[40:43], v[152:155], v[204:207], v[40:43]
	v_mfma_f32_16x16x32_bf16 v[56:59], v[196:199], v[204:207], v[80:83]
	v_mfma_f32_16x16x32_bf16 v[80:83], v[152:155], v[212:215], v[128:131]
	v_mfma_f32_16x16x32_bf16 v[128:131], v[196:199], v[212:215], v[132:135]
	v_mfma_f32_16x16x32_bf16 v[132:135], v[152:155], v[220:223], v[136:139]
	v_mfma_f32_16x16x32_bf16 v[136:139], v[196:199], v[220:223], v[140:143]
	v_mfma_f32_16x16x32_bf16 v[44:47], v[152:155], v[228:231], v[44:47]
	v_mfma_f32_16x16x32_bf16 v[48:51], v[196:199], v[228:231], v[48:51]
	v_mfma_f32_16x16x32_bf16 v[40:43], v[192:195], v[208:211], v[40:43]
	v_mfma_f32_16x16x32_bf16 v[56:59], v[200:203], v[208:211], v[56:59]
	v_mfma_f32_16x16x32_bf16 v[80:83], v[192:195], v[216:219], v[80:83]
	v_mfma_f32_16x16x32_bf16 v[128:131], v[200:203], v[216:219], v[128:131]
	v_mfma_f32_16x16x32_bf16 v[132:135], v[192:195], v[224:227], v[132:135]
	v_mfma_f32_16x16x32_bf16 v[136:139], v[200:203], v[224:227], v[136:139]
	v_mfma_f32_16x16x32_bf16 v[44:47], v[192:195], v[232:235], v[44:47]
	v_mfma_f32_16x16x32_bf16 v[48:51], v[200:203], v[232:235], v[48:51]
	s_setprio 0
	s_barrier
	ds_read_b128 v[140:143], v20
	ds_read_b128 v[144:147], v21
	ds_read_b128 v[148:151], v22
	ds_read_b128 v[152:155], v23
	ds_read_b128 v[188:191], v24
	ds_read_b128 v[192:195], v25
	ds_read_b128 v[196:199], v26
	ds_read_b128 v[200:203], v27
	s_add_u32 s28, s42, 0x70180
	s_addc_u32 s29, s43, 0
	s_mov_b32 m0, s73
	v_lshl_add_u64 v[236:237], s[28:29], 0, v[6:7]
	ds_read_b128 v[204:207], v17
	ds_read_b128 v[208:211], v17 offset:1024
	ds_read_b128 v[212:215], v17 offset:2048
	ds_read_b128 v[216:219], v17 offset:3072
	ds_read_b128 v[220:223], v17 offset:4096
	ds_read_b128 v[224:227], v17 offset:5120
	ds_read_b128 v[228:231], v17 offset:6144
	ds_read_b128 v[232:235], v17 offset:7168
	global_load_lds_dwordx4 v[236:237], off
	v_lshl_add_u64 v[236:237], s[28:29], 0, v[4:5]
	s_mov_b32 m0, s72
	s_nop 0
	global_load_lds_dwordx4 v[236:237], off
	s_waitcnt vmcnt(8)
	s_waitcnt lgkmcnt(0)
	s_barrier
	s_setprio 1
	s_waitcnt lgkmcnt(0)
	v_mfma_f32_16x16x32_bf16 v[84:87], v[140:143], v[204:207], v[84:87]
	v_mfma_f32_16x16x32_bf16 v[88:91], v[148:151], v[204:207], v[88:91]
	v_mfma_f32_16x16x32_bf16 v[92:95], v[140:143], v[212:215], v[92:95]
	v_mfma_f32_16x16x32_bf16 v[96:99], v[148:151], v[212:215], v[96:99]
	v_mfma_f32_16x16x32_bf16 v[100:103], v[140:143], v[220:223], v[100:103]
	v_mfma_f32_16x16x32_bf16 v[104:107], v[148:151], v[220:223], v[104:107]
	v_mfma_f32_16x16x32_bf16 v[108:111], v[140:143], v[228:231], v[108:111]
	v_mfma_f32_16x16x32_bf16 v[112:115], v[148:151], v[228:231], v[112:115]
	v_mfma_f32_16x16x32_bf16 v[84:87], v[144:147], v[208:211], v[84:87]
	v_mfma_f32_16x16x32_bf16 v[88:91], v[152:155], v[208:211], v[88:91]
	v_mfma_f32_16x16x32_bf16 v[92:95], v[144:147], v[216:219], v[92:95]
	v_mfma_f32_16x16x32_bf16 v[96:99], v[152:155], v[216:219], v[96:99]
	v_mfma_f32_16x16x32_bf16 v[100:103], v[144:147], v[224:227], v[100:103]
	v_mfma_f32_16x16x32_bf16 v[104:107], v[152:155], v[224:227], v[104:107]
	v_mfma_f32_16x16x32_bf16 v[108:111], v[144:147], v[232:235], v[108:111]
	v_mfma_f32_16x16x32_bf16 v[112:115], v[152:155], v[232:235], v[112:115]
	v_mfma_f32_16x16x32_bf16 v[116:119], v[188:191], v[204:207], v[116:119]
	v_mfma_f32_16x16x32_bf16 v[120:123], v[196:199], v[204:207], v[120:123]
	v_mfma_f32_16x16x32_bf16 v[124:127], v[188:191], v[212:215], v[124:127]
	v_mfma_f32_16x16x32_bf16 v[60:63], v[196:199], v[212:215], v[60:63]
	v_mfma_f32_16x16x32_bf16 v[64:67], v[188:191], v[220:223], v[64:67]
	v_mfma_f32_16x16x32_bf16 v[68:71], v[196:199], v[220:223], v[68:71]
	v_mfma_f32_16x16x32_bf16 v[72:75], v[188:191], v[228:231], v[72:75]
	v_mfma_f32_16x16x32_bf16 v[76:79], v[196:199], v[228:231], v[76:79]
	v_mfma_f32_16x16x32_bf16 v[116:119], v[192:195], v[208:211], v[116:119]
	v_mfma_f32_16x16x32_bf16 v[120:123], v[200:203], v[208:211], v[120:123]
	v_mfma_f32_16x16x32_bf16 v[124:127], v[192:195], v[216:219], v[124:127]
	v_mfma_f32_16x16x32_bf16 v[60:63], v[200:203], v[216:219], v[60:63]
	v_mfma_f32_16x16x32_bf16 v[64:67], v[192:195], v[224:227], v[64:67]
	v_mfma_f32_16x16x32_bf16 v[68:71], v[200:203], v[224:227], v[68:71]
	v_mfma_f32_16x16x32_bf16 v[72:75], v[192:195], v[232:235], v[72:75]
	v_mfma_f32_16x16x32_bf16 v[76:79], v[200:203], v[232:235], v[76:79]
	s_setprio 0
	s_barrier
; #define G_STAGE(bufoff, gbase, voff) do { _Pragma("unroll") for (int _i = 0; _i < 2; ++_i) \
;         __builtin_amdgcn_global_load_lds((const unsigned*)((const char*)(gbase) + (voff)[_i]), (LAS unsigned*)(lds + (bufoff) + ldsw + _i * 8192), 16, 0, 0); } while (0)
; #define G_LDA(dst, b, h) do { _Pragma("unroll") for (int m = 0; m < 4; ++m) _Pragma("unroll") for (int k = 0; k < 2; ++k) dst[m][k] = *(const LAS bf16x8*)(lds + G_SA(b, h) + aoff + m * 2048 + k * 1024); } while (0)
; #define G_LDB(dst, b, h) do { _Pragma("unroll") for (int n = 0; n < 2; ++n) _Pragma("unroll") for (int k = 0; k < 2; ++k) dst[n][k] = *(const LAS bf16x8*)(lds + G_SB(b, h) + boff + n * 2048 + k * 1024); } while (0)
; #define G_MMA(ai, bj, At, Bt_) do { __builtin_amdgcn_s_setprio(1); _Pragma("unroll") for (int m = 0; m < 4; ++m) _Pragma("unroll") for (int n = 0; n < 2; ++n) _Pragma("unroll") for (int k = 0; k < 2; ++k) \
;         acc[ai][bj][m][n] = __builtin_amdgcn_mfma_f32_16x16x32_bf16(Bt_[n][k], At[m][k], acc[ai][bj][m][n], 0, 0, 0); __builtin_amdgcn_s_setprio(0); } while (0)
; #define G_WAIT_V(n) asm volatile("s_waitcnt vmcnt(" #n ")" ::: "memory")
; #define G_WAIT_L(n) asm volatile("s_waitcnt lgkmcnt(" #n ")" ::: "memory")
; #define G_BAR __builtin_amdgcn_s_barrier()
; #define G_SCHED __builtin_amdgcn_sched_barrier(0)
; template <int NSTORE, class TF, class F>
; DEVI void gemm_run(const bf16_t* __restrict__ A, int lda, const bf16_t* __restrict__ Bt, int ldb, int K, bf16_t* shm, TF&& tile, F&& emit) {
;     ...
;             G_LDA(At, 0, 1); G_STAGE(G_SB(0, 0), b2, voffB); G_STAGE(G_SB(0, 1), b2 + hstepB, voffB); G_STAGE(G_SA(0, 0), a2, voffA);
;             G_WAIT_V(8); G_WAIT_L(0); G_BAR; G_MMA(1, 0, At, B0); G_MMA(1, 1, At, B1); G_BAR; G_SCHED;
;             G_LDB(B0, 1, 0); G_LDB(B1, 1, 1); G_SCHED; G_LDA(At, 1, 0); G_STAGE(G_SA(0, 1), a2 + hstepA, voffA);
;             G_WAIT_V(8); G_WAIT_L(0); G_BAR; G_MMA(0, 0, At, B0); G_MMA(0, 1, At, B1); G_BAR; G_SCHED;
	s_mov_b64 s[36:37], 0x200
	s_mov_b32 m0, s9
	v_lshl_add_u64 v[236:237], v[8:9], 0, s[36:37]
	s_add_u32 s28, s44, 0x18200
	ds_read_b128 v[204:207], v17 offset:16384
	ds_read_b128 v[208:211], v17 offset:17408
	ds_read_b128 v[212:215], v17 offset:18432
	ds_read_b128 v[216:219], v17 offset:19456
	ds_read_b128 v[220:223], v17 offset:20480
	ds_read_b128 v[224:227], v17 offset:21504
	ds_read_b128 v[228:231], v17 offset:22528
	ds_read_b128 v[232:235], v17 offset:23552
	global_load_lds_dwordx4 v[236:237], off
	v_lshl_add_u64 v[236:237], v[10:11], 0, s[36:37]
	s_mov_b32 m0, s15
	s_addc_u32 s29, s45, 0
	global_load_lds_dwordx4 v[236:237], off
	v_lshl_add_u64 v[236:237], s[28:29], 0, v[0:1]
	s_mov_b32 m0, s16
	s_nop 0
	global_load_lds_dwordx4 v[236:237], off
	v_lshl_add_u64 v[236:237], s[28:29], 0, v[2:3]
	s_mov_b32 m0, s17
	s_nop 0
	global_load_lds_dwordx4 v[236:237], off
	v_lshl_add_u64 v[236:237], v[12:13], 0, s[36:37]
	s_mov_b32 m0, s8
	s_nop 0
	global_load_lds_dwordx4 v[236:237], off
	v_lshl_add_u64 v[236:237], v[14:15], 0, s[36:37]
	s_mov_b32 m0, s18
	s_nop 0
	global_load_lds_dwordx4 v[236:237], off
	s_waitcnt vmcnt(8)
	s_waitcnt lgkmcnt(0)
	s_barrier
	s_setprio 1
	s_waitcnt lgkmcnt(0)
	v_mfma_f32_16x16x32_bf16 v[156:159], v[140:143], v[204:207], v[156:159]
	v_mfma_f32_16x16x32_bf16 v[160:163], v[148:151], v[204:207], v[160:163]
	v_mfma_f32_16x16x32_bf16 v[164:167], v[140:143], v[212:215], v[164:167]
	v_mfma_f32_16x16x32_bf16 v[168:171], v[148:151], v[212:215], v[168:171]
	v_mfma_f32_16x16x32_bf16 v[176:179], v[140:143], v[220:223], v[176:179]
	v_mfma_f32_16x16x32_bf16 v[182:185], v[148:151], v[220:223], v[182:185]
	v_mfma_f32_16x16x32_bf16 v[52:55], v[140:143], v[228:231], v[52:55]
	v_mfma_f32_16x16x32_bf16 v[36:39], v[148:151], v[228:231], v[36:39]
	v_mfma_f32_16x16x32_bf16 v[156:159], v[144:147], v[208:211], v[156:159]
	v_mfma_f32_16x16x32_bf16 v[160:163], v[152:155], v[208:211], v[160:163]
	v_mfma_f32_16x16x32_bf16 v[164:167], v[144:147], v[216:219], v[164:167]
	v_mfma_f32_16x16x32_bf16 v[168:171], v[152:155], v[216:219], v[168:171]
	v_mfma_f32_16x16x32_bf16 v[176:179], v[144:147], v[224:227], v[176:179]
	v_mfma_f32_16x16x32_bf16 v[182:185], v[152:155], v[224:227], v[182:185]
	v_mfma_f32_16x16x32_bf16 v[52:55], v[144:147], v[232:235], v[52:55]
	v_mfma_f32_16x16x32_bf16 v[36:39], v[152:155], v[232:235], v[36:39]
	v_mfma_f32_16x16x32_bf16 v[40:43], v[188:191], v[204:207], v[40:43]
	v_mfma_f32_16x16x32_bf16 v[56:59], v[196:199], v[204:207], v[56:59]
	v_mfma_f32_16x16x32_bf16 v[80:83], v[188:191], v[212:215], v[80:83]
	v_mfma_f32_16x16x32_bf16 v[128:131], v[196:199], v[212:215], v[128:131]
	v_mfma_f32_16x16x32_bf16 v[132:135], v[188:191], v[220:223], v[132:135]
	v_mfma_f32_16x16x32_bf16 v[136:139], v[196:199], v[220:223], v[136:139]
	v_mfma_f32_16x16x32_bf16 v[44:47], v[188:191], v[228:231], v[44:47]
	v_mfma_f32_16x16x32_bf16 v[48:51], v[196:199], v[228:231], v[48:51]
	v_mfma_f32_16x16x32_bf16 v[40:43], v[192:195], v[208:211], v[40:43]
	v_mfma_f32_16x16x32_bf16 v[56:59], v[200:203], v[208:211], v[56:59]
	v_mfma_f32_16x16x32_bf16 v[80:83], v[192:195], v[216:219], v[80:83]
	v_mfma_f32_16x16x32_bf16 v[128:131], v[200:203], v[216:219], v[128:131]
	v_mfma_f32_16x16x32_bf16 v[132:135], v[192:195], v[224:227], v[132:135]
	v_mfma_f32_16x16x32_bf16 v[136:139], v[200:203], v[224:227], v[136:139]
	v_mfma_f32_16x16x32_bf16 v[44:47], v[192:195], v[232:235], v[44:47]
	v_mfma_f32_16x16x32_bf16 v[48:51], v[200:203], v[232:235], v[48:51]
	s_setprio 0
	s_barrier
	ds_read_b128 v[140:143], v28
	ds_read_b128 v[144:147], v29
	ds_read_b128 v[148:151], v30
	ds_read_b128 v[152:155], v31
	ds_read_b128 v[188:191], v32
	ds_read_b128 v[192:195], v33
	ds_read_b128 v[196:199], v34
	ds_read_b128 v[200:203], v35
	s_add_u32 s28, s42, 0x70200
	s_addc_u32 s29, s43, 0
	s_mov_b32 m0, s19
	v_lshl_add_u64 v[236:237], s[28:29], 0, v[6:7]
	ds_read_b128 v[204:207], v17 offset:32768
	ds_read_b128 v[208:211], v17 offset:33792
	ds_read_b128 v[212:215], v17 offset:34816
	ds_read_b128 v[216:219], v17 offset:35840
	ds_read_b128 v[220:223], v17 offset:36864
	ds_read_b128 v[224:227], v17 offset:37888
	ds_read_b128 v[228:231], v17 offset:38912
	ds_read_b128 v[232:235], v17 offset:39936
	global_load_lds_dwordx4 v[236:237], off
	v_lshl_add_u64 v[236:237], s[28:29], 0, v[4:5]
	s_mov_b32 m0, s26
	s_nop 0
	global_load_lds_dwordx4 v[236:237], off
	s_waitcnt vmcnt(8)
	s_waitcnt lgkmcnt(0)
	s_barrier
	s_setprio 1
	s_waitcnt lgkmcnt(0)
	v_mfma_f32_16x16x32_bf16 v[84:87], v[140:143], v[204:207], v[84:87]
	v_mfma_f32_16x16x32_bf16 v[88:91], v[148:151], v[204:207], v[88:91]
	v_mfma_f32_16x16x32_bf16 v[92:95], v[140:143], v[212:215], v[92:95]
	v_mfma_f32_16x16x32_bf16 v[96:99], v[148:151], v[212:215], v[96:99]
	v_mfma_f32_16x16x32_bf16 v[100:103], v[140:143], v[220:223], v[100:103]
	v_mfma_f32_16x16x32_bf16 v[104:107], v[148:151], v[220:223], v[104:107]
	v_mfma_f32_16x16x32_bf16 v[108:111], v[140:143], v[228:231], v[108:111]
	v_mfma_f32_16x16x32_bf16 v[112:115], v[148:151], v[228:231], v[112:115]
	v_mfma_f32_16x16x32_bf16 v[84:87], v[144:147], v[208:211], v[84:87]
	v_mfma_f32_16x16x32_bf16 v[88:91], v[152:155], v[208:211], v[88:91]
	v_mfma_f32_16x16x32_bf16 v[92:95], v[144:147], v[216:219], v[92:95]
	v_mfma_f32_16x16x32_bf16 v[96:99], v[152:155], v[216:219], v[96:99]
	v_mfma_f32_16x16x32_bf16 v[100:103], v[144:147], v[224:227], v[100:103]
	v_mfma_f32_16x16x32_bf16 v[104:107], v[152:155], v[224:227], v[104:107]
	v_mfma_f32_16x16x32_bf16 v[108:111], v[144:147], v[232:235], v[108:111]
	v_mfma_f32_16x16x32_bf16 v[112:115], v[152:155], v[232:235], v[112:115]
	v_mfma_f32_16x16x32_bf16 v[116:119], v[188:191], v[204:207], v[116:119]
	v_mfma_f32_16x16x32_bf16 v[120:123], v[196:199], v[204:207], v[120:123]
	v_mfma_f32_16x16x32_bf16 v[124:127], v[188:191], v[212:215], v[124:127]
	v_mfma_f32_16x16x32_bf16 v[60:63], v[196:199], v[212:215], v[60:63]
	v_mfma_f32_16x16x32_bf16 v[64:67], v[188:191], v[220:223], v[64:67]
	v_mfma_f32_16x16x32_bf16 v[68:71], v[196:199], v[220:223], v[68:71]
	v_mfma_f32_16x16x32_bf16 v[72:75], v[188:191], v[228:231], v[72:75]
	v_mfma_f32_16x16x32_bf16 v[76:79], v[196:199], v[228:231], v[76:79]
	v_mfma_f32_16x16x32_bf16 v[116:119], v[192:195], v[208:211], v[116:119]
	v_mfma_f32_16x16x32_bf16 v[120:123], v[200:203], v[208:211], v[120:123]
	v_mfma_f32_16x16x32_bf16 v[124:127], v[192:195], v[216:219], v[124:127]
	v_mfma_f32_16x16x32_bf16 v[60:63], v[200:203], v[216:219], v[60:63]
	v_mfma_f32_16x16x32_bf16 v[64:67], v[192:195], v[224:227], v[64:67]
	v_mfma_f32_16x16x32_bf16 v[68:71], v[200:203], v[224:227], v[68:71]
	v_mfma_f32_16x16x32_bf16 v[72:75], v[192:195], v[232:235], v[72:75]
	v_mfma_f32_16x16x32_bf16 v[76:79], v[200:203], v[232:235], v[76:79]
	s_setprio 0
	s_barrier
; #define G_STAGE(bufoff, gbase, voff) do { _Pragma("unroll") for (int _i = 0; _i < 2; ++_i) \
;         __builtin_amdgcn_global_load_lds((const unsigned*)((const char*)(gbase) + (voff)[_i]), (LAS unsigned*)(lds + (bufoff) + ldsw + _i * 8192), 16, 0, 0); } while (0)
; #define G_LDA(dst, b, h) do { _Pragma("unroll") for (int m = 0; m < 4; ++m) _Pragma("unroll") for (int k = 0; k < 2; ++k) dst[m][k] = *(const LAS bf16x8*)(lds + G_SA(b, h) + aoff + m * 2048 + k * 1024); } while (0)
; #define G_LDB(dst, b, h) do { _Pragma("unroll") for (int n = 0; n < 2; ++n) _Pragma("unroll") for (int k = 0; k < 2; ++k) dst[n][k] = *(const LAS bf16x8*)(lds + G_SB(b, h) + boff + n * 2048 + k * 1024); } while (0)
; #define G_MMA(ai, bj, At, Bt_) do { __builtin_amdgcn_s_setprio(1); _Pragma("unroll") for (int m = 0; m < 4; ++m) _Pragma("unroll") for (int n = 0; n < 2; ++n) _Pragma("unroll") for (int k = 0; k < 2; ++k) \
;         acc[ai][bj][m][n] = __builtin_amdgcn_mfma_f32_16x16x32_bf16(Bt_[n][k], At[m][k], acc[ai][bj][m][n], 0, 0, 0); __builtin_amdgcn_s_setprio(0); } while (0)
; #define G_WAIT_V(n) asm volatile("s_waitcnt vmcnt(" #n ")" ::: "memory")
; #define G_WAIT_L(n) asm volatile("s_waitcnt lgkmcnt(" #n ")" ::: "memory")
; #define G_BAR __builtin_amdgcn_s_barrier()
; #define G_SCHED __builtin_amdgcn_sched_barrier(0)
; template <int NSTORE, class TF, class F>
; DEVI void gemm_run(const bf16_t* __restrict__ A, int lda, const bf16_t* __restrict__ Bt, int ldb, int K, bf16_t* shm, TF&& tile, F&& emit) {
;     ...
;             G_LDB(B0, 0, 0); G_LDB(B1, 0, 1); G_SCHED; G_LDA(At, 0, 0); G_STAGE(G_SA(1, 1), a1 + hstepA, voffA);
;             G_WAIT_V(8); G_WAIT_L(0); G_BAR; G_MMA(0, 0, At, B0); G_MMA(0, 1, At, B1); G_BAR; G_SCHED;
;     ...
;             G_LDA(At, 1, 1); G_STAGE(G_SB(1, 0), b3, voffB); G_STAGE(G_SB(1, 1), b3 + hstepB, voffB); G_STAGE(G_SA(1, 0), a3, voffA);
;             G_WAIT_V(8); G_WAIT_L(0); G_BAR; G_MMA(1, 0, At, B0); G_MMA(1, 1, At, B1); G_BAR; G_SCHED;
	s_mov_b64 s[36:37], 0x280
	s_mov_b32 m0, s27
	v_lshl_add_u64 v[8:9], v[8:9], 0, s[36:37]
	s_add_u32 s28, s44, 0x18280
	ds_read_b128 v[204:207], v17 offset:49152
	ds_read_b128 v[208:211], v17 offset:50176
	ds_read_b128 v[212:215], v17 offset:51200
	ds_read_b128 v[216:219], v17 offset:52224
	ds_read_b128 v[220:223], v17 offset:53248
	ds_read_b128 v[224:227], v17 offset:54272
	ds_read_b128 v[228:231], v17 offset:55296
	ds_read_b128 v[232:235], v17 offset:56320
	global_load_lds_dwordx4 v[8:9], off
	v_lshl_add_u64 v[8:9], v[10:11], 0, s[36:37]
	s_mov_b32 m0, s46
	s_addc_u32 s29, s45, 0
	global_load_lds_dwordx4 v[8:9], off
	v_lshl_add_u64 v[8:9], s[28:29], 0, v[0:1]
	s_mov_b32 m0, s49
	s_nop 0
	global_load_lds_dwordx4 v[8:9], off
	v_lshl_add_u64 v[8:9], s[28:29], 0, v[2:3]
	s_mov_b32 m0, s68
	s_nop 0
	global_load_lds_dwordx4 v[8:9], off
	v_lshl_add_u64 v[8:9], v[12:13], 0, s[36:37]
	s_mov_b32 m0, s47
	s_nop 0
	global_load_lds_dwordx4 v[8:9], off
	v_lshl_add_u64 v[8:9], v[14:15], 0, s[36:37]
	s_mov_b32 m0, s48
	s_nop 0
	global_load_lds_dwordx4 v[8:9], off
	s_waitcnt vmcnt(8)
	s_waitcnt lgkmcnt(0)
	s_barrier
	s_setprio 1
	s_waitcnt lgkmcnt(0)
	v_mfma_f32_16x16x32_bf16 v[8:11], v[140:143], v[204:207], v[156:159]
	v_mfma_f32_16x16x32_bf16 v[12:15], v[148:151], v[204:207], v[160:163]
	v_mfma_f32_16x16x32_bf16 v[156:159], v[140:143], v[212:215], v[164:167]
	v_mfma_f32_16x16x32_bf16 v[160:163], v[148:151], v[212:215], v[168:171]
	v_mfma_f32_16x16x32_bf16 v[164:167], v[140:143], v[220:223], v[176:179]
	v_mfma_f32_16x16x32_bf16 v[168:171], v[148:151], v[220:223], v[182:185]
	v_mfma_f32_16x16x32_bf16 v[52:55], v[140:143], v[228:231], v[52:55]
	v_mfma_f32_16x16x32_bf16 v[36:39], v[148:151], v[228:231], v[36:39]
	v_mfma_f32_16x16x32_bf16 v[8:11], v[144:147], v[208:211], v[8:11]
	v_mfma_f32_16x16x32_bf16 v[12:15], v[152:155], v[208:211], v[12:15]
	v_mfma_f32_16x16x32_bf16 v[156:159], v[144:147], v[216:219], v[156:159]
	v_mfma_f32_16x16x32_bf16 v[160:163], v[152:155], v[216:219], v[160:163]
	v_mfma_f32_16x16x32_bf16 v[164:167], v[144:147], v[224:227], v[164:167]
	v_mfma_f32_16x16x32_bf16 v[168:171], v[152:155], v[224:227], v[168:171]
	v_mfma_f32_16x16x32_bf16 v[52:55], v[144:147], v[232:235], v[52:55]
	v_mfma_f32_16x16x32_bf16 v[36:39], v[152:155], v[232:235], v[36:39]
	v_mfma_f32_16x16x32_bf16 v[40:43], v[188:191], v[204:207], v[40:43]
	v_mfma_f32_16x16x32_bf16 v[56:59], v[196:199], v[204:207], v[56:59]
	v_mfma_f32_16x16x32_bf16 v[80:83], v[188:191], v[212:215], v[80:83]
	v_mfma_f32_16x16x32_bf16 v[128:131], v[196:199], v[212:215], v[128:131]
	v_mfma_f32_16x16x32_bf16 v[132:135], v[188:191], v[220:223], v[132:135]
	v_mfma_f32_16x16x32_bf16 v[136:139], v[196:199], v[220:223], v[136:139]
	v_mfma_f32_16x16x32_bf16 v[44:47], v[188:191], v[228:231], v[44:47]
	v_mfma_f32_16x16x32_bf16 v[48:51], v[196:199], v[228:231], v[48:51]
	v_mfma_f32_16x16x32_bf16 v[40:43], v[192:195], v[208:211], v[40:43]
	v_mfma_f32_16x16x32_bf16 v[56:59], v[200:203], v[208:211], v[56:59]
	v_mfma_f32_16x16x32_bf16 v[80:83], v[192:195], v[216:219], v[80:83]
	v_mfma_f32_16x16x32_bf16 v[128:131], v[200:203], v[216:219], v[128:131]
	v_mfma_f32_16x16x32_bf16 v[132:135], v[192:195], v[224:227], v[132:135]
	v_mfma_f32_16x16x32_bf16 v[136:139], v[200:203], v[224:227], v[136:139]
	v_mfma_f32_16x16x32_bf16 v[44:47], v[192:195], v[232:235], v[44:47]
	v_mfma_f32_16x16x32_bf16 v[48:51], v[200:203], v[232:235], v[48:51]
	s_setprio 0
	s_barrier
	ds_read_b128 v[140:143], v20
	ds_read_b128 v[144:147], v21
	ds_read_b128 v[148:151], v22
	ds_read_b128 v[20:23], v23
	ds_read_b128 v[152:155], v24
	ds_read_b128 v[176:179], v25
	ds_read_b128 v[182:185], v26
	ds_read_b128 v[24:27], v27
	s_add_u32 s28, s42, 0x70280
	s_addc_u32 s29, s43, 0
	s_mov_b32 m0, s73
	v_lshl_add_u64 v[220:221], s[28:29], 0, v[6:7]
	ds_read_b128 v[188:191], v17
	ds_read_b128 v[192:195], v17 offset:1024
	ds_read_b128 v[196:199], v17 offset:2048
	ds_read_b128 v[200:203], v17 offset:3072
	ds_read_b128 v[204:207], v17 offset:4096
	ds_read_b128 v[208:211], v17 offset:5120
	ds_read_b128 v[212:215], v17 offset:6144
	ds_read_b128 v[216:219], v17 offset:7168
	global_load_lds_dwordx4 v[220:221], off
	v_lshl_add_u64 v[220:221], s[28:29], 0, v[4:5]
	s_mov_b32 m0, s72
	s_nop 0
	global_load_lds_dwordx4 v[220:221], off
	s_waitcnt vmcnt(8)
	s_waitcnt lgkmcnt(0)
	s_barrier
	s_setprio 1
	s_waitcnt lgkmcnt(0)
	v_mfma_f32_16x16x32_bf16 v[84:87], v[140:143], v[188:191], v[84:87]
	v_mfma_f32_16x16x32_bf16 v[88:91], v[148:151], v[188:191], v[88:91]
	v_mfma_f32_16x16x32_bf16 v[92:95], v[140:143], v[196:199], v[92:95]
	v_mfma_f32_16x16x32_bf16 v[96:99], v[148:151], v[196:199], v[96:99]
	v_mfma_f32_16x16x32_bf16 v[100:103], v[140:143], v[204:207], v[100:103]
	v_mfma_f32_16x16x32_bf16 v[104:107], v[148:151], v[204:207], v[104:107]
	v_mfma_f32_16x16x32_bf16 v[108:111], v[140:143], v[212:215], v[108:111]
	v_mfma_f32_16x16x32_bf16 v[112:115], v[148:151], v[212:215], v[112:115]
	v_mfma_f32_16x16x32_bf16 v[84:87], v[144:147], v[192:195], v[84:87]
	v_mfma_f32_16x16x32_bf16 v[88:91], v[20:23], v[192:195], v[88:91]
	v_mfma_f32_16x16x32_bf16 v[92:95], v[144:147], v[200:203], v[92:95]
	v_mfma_f32_16x16x32_bf16 v[96:99], v[20:23], v[200:203], v[96:99]
	v_mfma_f32_16x16x32_bf16 v[100:103], v[144:147], v[208:211], v[100:103]
	v_mfma_f32_16x16x32_bf16 v[104:107], v[20:23], v[208:211], v[104:107]
	v_mfma_f32_16x16x32_bf16 v[108:111], v[144:147], v[216:219], v[108:111]
	v_mfma_f32_16x16x32_bf16 v[112:115], v[20:23], v[216:219], v[112:115]
	v_mfma_f32_16x16x32_bf16 v[116:119], v[152:155], v[188:191], v[116:119]
	v_mfma_f32_16x16x32_bf16 v[120:123], v[182:185], v[188:191], v[120:123]
	v_mfma_f32_16x16x32_bf16 v[124:127], v[152:155], v[196:199], v[124:127]
	v_mfma_f32_16x16x32_bf16 v[60:63], v[182:185], v[196:199], v[60:63]
	v_mfma_f32_16x16x32_bf16 v[64:67], v[152:155], v[204:207], v[64:67]
	v_mfma_f32_16x16x32_bf16 v[68:71], v[182:185], v[204:207], v[68:71]
	v_mfma_f32_16x16x32_bf16 v[72:75], v[152:155], v[212:215], v[72:75]
	v_mfma_f32_16x16x32_bf16 v[76:79], v[182:185], v[212:215], v[76:79]
	v_mfma_f32_16x16x32_bf16 v[116:119], v[176:179], v[192:195], v[116:119]
	v_mfma_f32_16x16x32_bf16 v[120:123], v[24:27], v[192:195], v[120:123]
	v_mfma_f32_16x16x32_bf16 v[124:127], v[176:179], v[200:203], v[124:127]
	v_mfma_f32_16x16x32_bf16 v[60:63], v[24:27], v[200:203], v[60:63]
	v_mfma_f32_16x16x32_bf16 v[64:67], v[176:179], v[208:211], v[64:67]
	v_mfma_f32_16x16x32_bf16 v[68:71], v[24:27], v[208:211], v[68:71]
	v_mfma_f32_16x16x32_bf16 v[72:75], v[176:179], v[216:219], v[72:75]
	v_mfma_f32_16x16x32_bf16 v[76:79], v[24:27], v[216:219], v[76:79]
	s_setprio 0
	s_barrier
; #define G_STAGE(bufoff, gbase, voff) do { _Pragma("unroll") for (int _i = 0; _i < 2; ++_i) \
;         __builtin_amdgcn_global_load_lds((const unsigned*)((const char*)(gbase) + (voff)[_i]), (LAS unsigned*)(lds + (bufoff) + ldsw + _i * 8192), 16, 0, 0); } while (0)
; #define G_LDA(dst, b, h) do { _Pragma("unroll") for (int m = 0; m < 4; ++m) _Pragma("unroll") for (int k = 0; k < 2; ++k) dst[m][k] = *(const LAS bf16x8*)(lds + G_SA(b, h) + aoff + m * 2048 + k * 1024); } while (0)
; #define G_LDB(dst, b, h) do { _Pragma("unroll") for (int n = 0; n < 2; ++n) _Pragma("unroll") for (int k = 0; k < 2; ++k) dst[n][k] = *(const LAS bf16x8*)(lds + G_SB(b, h) + boff + n * 2048 + k * 1024); } while (0)
; #define G_MMA(ai, bj, At, Bt_) do { __builtin_amdgcn_s_setprio(1); _Pragma("unroll") for (int m = 0; m < 4; ++m) _Pragma("unroll") for (int n = 0; n < 2; ++n) _Pragma("unroll") for (int k = 0; k < 2; ++k) \
;         acc[ai][bj][m][n] = __builtin_amdgcn_mfma_f32_16x16x32_bf16(Bt_[n][k], At[m][k], acc[ai][bj][m][n], 0, 0, 0); __builtin_amdgcn_s_setprio(0); } while (0)
; #define G_WAIT_V(n) asm volatile("s_waitcnt vmcnt(" #n ")" ::: "memory")
; #define G_WAIT_L(n) asm volatile("s_waitcnt lgkmcnt(" #n ")" ::: "memory")
; #define G_BAR __builtin_amdgcn_s_barrier()
; #define G_SCHED __builtin_amdgcn_sched_barrier(0)
; template <int NSTORE, class TF, class F>
; DEVI void gemm_run(const bf16_t* __restrict__ A, int lda, const bf16_t* __restrict__ Bt, int ldb, int K, bf16_t* shm, TF&& tile, F&& emit) {
;     ...
;             G_LDA(At, 0, 1); G_STAGE(G_SB(0, 0), b2, voffB); G_STAGE(G_SB(0, 1), b2 + hstepB, voffB); G_STAGE(G_SA(0, 0), a2, voffA);
;             G_WAIT_V(8); G_WAIT_L(0); G_BAR; G_MMA(1, 0, At, B0); G_MMA(1, 1, At, B1); G_BAR; G_SCHED;
;             G_LDB(B0, 1, 0); G_LDB(B1, 1, 1); G_SCHED; G_LDA(At, 1, 0); G_STAGE(G_SA(0, 1), a2 + hstepA, voffA);
;             G_WAIT_V(8); G_WAIT_L(0); G_BAR; G_MMA(0, 0, At, B0); G_MMA(0, 1, At, B1); G_BAR; G_SCHED;
	s_mov_b32 m0, s9
	v_lshl_add_u64 v[220:221], s[0:1], 0, v[0:1]
	s_add_u32 s28, s0, 0x18000
	ds_read_b128 v[188:191], v17 offset:16384
	ds_read_b128 v[192:195], v17 offset:17408
	ds_read_b128 v[196:199], v17 offset:18432
	ds_read_b128 v[200:203], v17 offset:19456
	ds_read_b128 v[204:207], v17 offset:20480
	ds_read_b128 v[208:211], v17 offset:21504
	ds_read_b128 v[212:215], v17 offset:22528
	ds_read_b128 v[216:219], v17 offset:23552
	global_load_lds_dwordx4 v[220:221], off
	v_lshl_add_u64 v[222:223], s[0:1], 0, v[2:3]
	s_mov_b32 m0, s15
	s_addc_u32 s29, s1, 0
	global_load_lds_dwordx4 v[222:223], off
	v_lshl_add_u64 v[224:225], s[28:29], 0, v[0:1]
	s_mov_b32 m0, s16
	v_lshl_add_u64 v[226:227], s[40:41], 0, v[4:5]
	global_load_lds_dwordx4 v[224:225], off
	v_lshl_add_u64 v[224:225], s[28:29], 0, v[2:3]
	s_mov_b32 m0, s17
	s_nop 0
	global_load_lds_dwordx4 v[224:225], off
	v_lshl_add_u64 v[224:225], s[40:41], 0, v[6:7]
	s_mov_b32 m0, s8
	s_nop 0
	global_load_lds_dwordx4 v[224:225], off
	s_mov_b32 m0, s18
	s_nop 0
	global_load_lds_dwordx4 v[226:227], off
	s_waitcnt vmcnt(8)
	s_waitcnt lgkmcnt(0)
	s_barrier
	s_setprio 1
	s_waitcnt lgkmcnt(0)
	v_mfma_f32_16x16x32_bf16 v[8:11], v[140:143], v[188:191], v[8:11]
	v_mfma_f32_16x16x32_bf16 v[12:15], v[148:151], v[188:191], v[12:15]
	v_mfma_f32_16x16x32_bf16 v[156:159], v[140:143], v[196:199], v[156:159]
	v_mfma_f32_16x16x32_bf16 v[160:163], v[148:151], v[196:199], v[160:163]
	v_mfma_f32_16x16x32_bf16 v[164:167], v[140:143], v[204:207], v[164:167]
	v_mfma_f32_16x16x32_bf16 v[168:171], v[148:151], v[204:207], v[168:171]
	v_mfma_f32_16x16x32_bf16 v[52:55], v[140:143], v[212:215], v[52:55]
	v_mfma_f32_16x16x32_bf16 v[36:39], v[148:151], v[212:215], v[36:39]
	v_mfma_f32_16x16x32_bf16 v[8:11], v[144:147], v[192:195], v[8:11]
	v_mfma_f32_16x16x32_bf16 v[12:15], v[20:23], v[192:195], v[12:15]
	v_mfma_f32_16x16x32_bf16 v[156:159], v[144:147], v[200:203], v[156:159]
	v_mfma_f32_16x16x32_bf16 v[160:163], v[20:23], v[200:203], v[160:163]
	v_mfma_f32_16x16x32_bf16 v[164:167], v[144:147], v[208:211], v[164:167]
	v_mfma_f32_16x16x32_bf16 v[168:171], v[20:23], v[208:211], v[168:171]
	v_mfma_f32_16x16x32_bf16 v[52:55], v[144:147], v[216:219], v[52:55]
	v_mfma_f32_16x16x32_bf16 v[20:23], v[20:23], v[216:219], v[36:39]
	v_mfma_f32_16x16x32_bf16 v[36:39], v[152:155], v[188:191], v[40:43]
	v_mfma_f32_16x16x32_bf16 v[40:43], v[182:185], v[188:191], v[56:59]
	v_mfma_f32_16x16x32_bf16 v[56:59], v[152:155], v[196:199], v[80:83]
	v_mfma_f32_16x16x32_bf16 v[80:83], v[182:185], v[196:199], v[128:131]
	v_mfma_f32_16x16x32_bf16 v[128:131], v[152:155], v[204:207], v[132:135]
	v_mfma_f32_16x16x32_bf16 v[132:135], v[182:185], v[204:207], v[136:139]
	v_mfma_f32_16x16x32_bf16 v[44:47], v[152:155], v[212:215], v[44:47]
	v_mfma_f32_16x16x32_bf16 v[48:51], v[182:185], v[212:215], v[48:51]
	v_mfma_f32_16x16x32_bf16 v[36:39], v[176:179], v[192:195], v[36:39]
	v_mfma_f32_16x16x32_bf16 v[40:43], v[24:27], v[192:195], v[40:43]
	v_mfma_f32_16x16x32_bf16 v[56:59], v[176:179], v[200:203], v[56:59]
	v_mfma_f32_16x16x32_bf16 v[80:83], v[24:27], v[200:203], v[80:83]
	v_mfma_f32_16x16x32_bf16 v[128:131], v[176:179], v[208:211], v[128:131]
	v_mfma_f32_16x16x32_bf16 v[132:135], v[24:27], v[208:211], v[132:135]
	v_mfma_f32_16x16x32_bf16 v[44:47], v[176:179], v[216:219], v[44:47]
	v_mfma_f32_16x16x32_bf16 v[24:27], v[24:27], v[216:219], v[48:51]
	s_setprio 0
	s_barrier
	s_nop 0
	ds_read_b128 v[48:51], v28
	ds_read_b128 v[136:139], v29
	ds_read_b128 v[140:143], v30
	ds_read_b128 v[28:31], v31
	ds_read_b128 v[144:147], v32
	ds_read_b128 v[148:151], v33
	ds_read_b128 v[152:155], v34
	ds_read_b128 v[32:35], v35
	s_add_u32 s28, s40, 0x70000
	s_addc_u32 s29, s41, 0
	s_mov_b32 m0, s19
	v_lshl_add_u64 v[212:213], s[28:29], 0, v[6:7]
	ds_read_b128 v[176:179], v17 offset:32768
	ds_read_b128 v[182:185], v17 offset:33792
	ds_read_b128 v[188:191], v17 offset:34816
	ds_read_b128 v[192:195], v17 offset:35840
	ds_read_b128 v[196:199], v17 offset:36864
	ds_read_b128 v[200:203], v17 offset:37888
	ds_read_b128 v[204:207], v17 offset:38912
	ds_read_b128 v[208:211], v17 offset:39936
	global_load_lds_dwordx4 v[212:213], off
	v_lshl_add_u64 v[212:213], s[28:29], 0, v[4:5]
	s_mov_b32 m0, s26
	s_nop 0
	global_load_lds_dwordx4 v[212:213], off
	s_waitcnt vmcnt(8)
	s_waitcnt lgkmcnt(0)
	s_barrier
	s_setprio 1
	s_waitcnt lgkmcnt(0)
	v_mfma_f32_16x16x32_bf16 v[84:87], v[48:51], v[176:179], v[84:87]
	v_mfma_f32_16x16x32_bf16 v[88:91], v[140:143], v[176:179], v[88:91]
	v_mfma_f32_16x16x32_bf16 v[92:95], v[48:51], v[188:191], v[92:95]
	v_mfma_f32_16x16x32_bf16 v[96:99], v[140:143], v[188:191], v[96:99]
	v_mfma_f32_16x16x32_bf16 v[100:103], v[48:51], v[196:199], v[100:103]
	v_mfma_f32_16x16x32_bf16 v[104:107], v[140:143], v[196:199], v[104:107]
	v_mfma_f32_16x16x32_bf16 v[108:111], v[48:51], v[204:207], v[108:111]
	v_mfma_f32_16x16x32_bf16 v[112:115], v[140:143], v[204:207], v[112:115]
	v_mfma_f32_16x16x32_bf16 v[84:87], v[136:139], v[182:185], v[84:87]
	v_mfma_f32_16x16x32_bf16 v[88:91], v[28:31], v[182:185], v[88:91]
	v_mfma_f32_16x16x32_bf16 v[92:95], v[136:139], v[192:195], v[92:95]
	v_mfma_f32_16x16x32_bf16 v[96:99], v[28:31], v[192:195], v[96:99]
	v_mfma_f32_16x16x32_bf16 v[100:103], v[136:139], v[200:203], v[100:103]
	v_mfma_f32_16x16x32_bf16 v[104:107], v[28:31], v[200:203], v[104:107]
	v_mfma_f32_16x16x32_bf16 v[108:111], v[136:139], v[208:211], v[108:111]
	v_mfma_f32_16x16x32_bf16 v[112:115], v[28:31], v[208:211], v[112:115]
	v_mfma_f32_16x16x32_bf16 v[116:119], v[144:147], v[176:179], v[116:119]
	v_mfma_f32_16x16x32_bf16 v[120:123], v[152:155], v[176:179], v[120:123]
	v_mfma_f32_16x16x32_bf16 v[124:127], v[144:147], v[188:191], v[124:127]
	v_mfma_f32_16x16x32_bf16 v[60:63], v[152:155], v[188:191], v[60:63]
	v_mfma_f32_16x16x32_bf16 v[64:67], v[144:147], v[196:199], v[64:67]
	v_mfma_f32_16x16x32_bf16 v[68:71], v[152:155], v[196:199], v[68:71]
	v_mfma_f32_16x16x32_bf16 v[72:75], v[144:147], v[204:207], v[72:75]
	v_mfma_f32_16x16x32_bf16 v[76:79], v[152:155], v[204:207], v[76:79]
	v_mfma_f32_16x16x32_bf16 v[116:119], v[148:151], v[182:185], v[116:119]
	v_mfma_f32_16x16x32_bf16 v[120:123], v[32:35], v[182:185], v[120:123]
	v_mfma_f32_16x16x32_bf16 v[124:127], v[148:151], v[192:195], v[124:127]
	v_mfma_f32_16x16x32_bf16 v[60:63], v[32:35], v[192:195], v[60:63]
	v_mfma_f32_16x16x32_bf16 v[64:67], v[148:151], v[200:203], v[64:67]
	v_mfma_f32_16x16x32_bf16 v[68:71], v[32:35], v[200:203], v[68:71]
	v_mfma_f32_16x16x32_bf16 v[72:75], v[148:151], v[208:211], v[72:75]
	v_mfma_f32_16x16x32_bf16 v[76:79], v[32:35], v[208:211], v[76:79]
	s_setprio 0
	s_barrier
; #define G_STAGE(bufoff, gbase, voff) do { _Pragma("unroll") for (int _i = 0; _i < 2; ++_i) \
;         __builtin_amdgcn_global_load_lds((const unsigned*)((const char*)(gbase) + (voff)[_i]), (LAS unsigned*)(lds + (bufoff) + ldsw + _i * 8192), 16, 0, 0); } while (0)
; #define G_LDA(dst, b, h) do { _Pragma("unroll") for (int m = 0; m < 4; ++m) _Pragma("unroll") for (int k = 0; k < 2; ++k) dst[m][k] = *(const LAS bf16x8*)(lds + G_SA(b, h) + aoff + m * 2048 + k * 1024); } while (0)
; #define G_MMA(ai, bj, At, Bt_) do { __builtin_amdgcn_s_setprio(1); _Pragma("unroll") for (int m = 0; m < 4; ++m) _Pragma("unroll") for (int n = 0; n < 2; ++n) _Pragma("unroll") for (int k = 0; k < 2; ++k) \
;         acc[ai][bj][m][n] = __builtin_amdgcn_mfma_f32_16x16x32_bf16(Bt_[n][k], At[m][k], acc[ai][bj][m][n], 0, 0, 0); __builtin_amdgcn_s_setprio(0); } while (0)
; #define G_WAIT_V(n) asm volatile("s_waitcnt vmcnt(" #n ")" ::: "memory")
; #define G_WAIT_L(n) asm volatile("s_waitcnt lgkmcnt(" #n ")" ::: "memory")
; #define G_BAR __builtin_amdgcn_s_barrier()
; #define G_SCHED __builtin_amdgcn_sched_barrier(0)
; template <int NSTORE, class TF, class F>
; DEVI void gemm_run(const bf16_t* __restrict__ A, int lda, const bf16_t* __restrict__ Bt, int ldb, int K, bf16_t* shm, TF&& tile, F&& emit) {
;     ...
;             G_LDA(At, 1, 1); G_STAGE(G_SB(1, 0), b3, voffB); G_STAGE(G_SB(1, 1), b3 + hstepB, voffB); G_STAGE(G_SA(1, 0), a3, voffA);
;             G_WAIT_V(8); G_WAIT_L(0); G_BAR; G_MMA(1, 0, At, B0); G_MMA(1, 1, At, B1); G_BAR; G_SCHED;
	s_mov_b32 m0, s27
	v_lshl_add_u64 v[212:213], v[220:221], 0, s[30:31]
	s_add_u32 s28, s0, 0x18080
	ds_read_b128 v[176:179], v17 offset:49152
	ds_read_b128 v[182:185], v17 offset:50176
	ds_read_b128 v[188:191], v17 offset:51200
	ds_read_b128 v[192:195], v17 offset:52224
	ds_read_b128 v[196:199], v17 offset:53248
	ds_read_b128 v[200:203], v17 offset:54272
	ds_read_b128 v[204:207], v17 offset:55296
	ds_read_b128 v[208:211], v17 offset:56320
	global_load_lds_dwordx4 v[212:213], off
	v_lshl_add_u64 v[212:213], v[222:223], 0, s[30:31]
	s_mov_b32 m0, s46
	s_addc_u32 s29, s1, 0
	global_load_lds_dwordx4 v[212:213], off
	v_lshl_add_u64 v[212:213], s[28:29], 0, v[0:1]
	s_mov_b32 m0, s49
	s_nop 0
	global_load_lds_dwordx4 v[212:213], off
	v_lshl_add_u64 v[212:213], s[28:29], 0, v[2:3]
	s_mov_b32 m0, s68
	s_nop 0
	global_load_lds_dwordx4 v[212:213], off
	v_lshl_add_u64 v[212:213], v[224:225], 0, s[30:31]
	s_mov_b32 m0, s47
	s_nop 0
	global_load_lds_dwordx4 v[212:213], off
	v_lshl_add_u64 v[212:213], v[226:227], 0, s[30:31]
	s_mov_b32 m0, s48
	s_nop 0
	global_load_lds_dwordx4 v[212:213], off
	s_waitcnt vmcnt(8)
	s_waitcnt lgkmcnt(0)
	s_barrier
	s_setprio 1
	s_waitcnt lgkmcnt(0)
	v_mfma_f32_16x16x32_bf16 v[8:11], v[48:51], v[176:179], v[8:11]
	v_mfma_f32_16x16x32_bf16 v[12:15], v[140:143], v[176:179], v[12:15]
	v_mfma_f32_16x16x32_bf16 v[156:159], v[48:51], v[188:191], v[156:159]
	v_mfma_f32_16x16x32_bf16 v[160:163], v[140:143], v[188:191], v[160:163]
	v_mfma_f32_16x16x32_bf16 v[164:167], v[48:51], v[196:199], v[164:167]
	v_mfma_f32_16x16x32_bf16 v[168:171], v[140:143], v[196:199], v[168:171]
	v_mfma_f32_16x16x32_bf16 v[48:51], v[48:51], v[204:207], v[52:55]
	v_mfma_f32_16x16x32_bf16 v[20:23], v[140:143], v[204:207], v[20:23]
	v_mfma_f32_16x16x32_bf16 v[8:11], v[136:139], v[182:185], v[8:11]
	v_mfma_f32_16x16x32_bf16 v[12:15], v[28:31], v[182:185], v[12:15]
	v_mfma_f32_16x16x32_bf16 v[156:159], v[136:139], v[192:195], v[156:159]
	v_mfma_f32_16x16x32_bf16 v[160:163], v[28:31], v[192:195], v[160:163]
	v_mfma_f32_16x16x32_bf16 v[164:167], v[136:139], v[200:203], v[164:167]
	v_mfma_f32_16x16x32_bf16 v[168:171], v[28:31], v[200:203], v[168:171]
	v_mfma_f32_16x16x32_bf16 v[48:51], v[136:139], v[208:211], v[48:51]
	v_mfma_f32_16x16x32_bf16 v[20:23], v[28:31], v[208:211], v[20:23]
	v_mfma_f32_16x16x32_bf16 v[28:31], v[144:147], v[176:179], v[36:39]
	v_mfma_f32_16x16x32_bf16 v[36:39], v[152:155], v[176:179], v[40:43]
	v_mfma_f32_16x16x32_bf16 v[40:43], v[144:147], v[188:191], v[56:59]
	v_mfma_f32_16x16x32_bf16 v[52:55], v[152:155], v[188:191], v[80:83]
	v_mfma_f32_16x16x32_bf16 v[56:59], v[144:147], v[196:199], v[128:131]
	v_mfma_f32_16x16x32_bf16 v[80:83], v[152:155], v[196:199], v[132:135]
	v_mfma_f32_16x16x32_bf16 v[44:47], v[144:147], v[204:207], v[44:47]
	v_mfma_f32_16x16x32_bf16 v[24:27], v[152:155], v[204:207], v[24:27]
	v_mfma_f32_16x16x32_bf16 v[28:31], v[148:151], v[182:185], v[28:31]
	v_mfma_f32_16x16x32_bf16 v[36:39], v[32:35], v[182:185], v[36:39]
	v_mfma_f32_16x16x32_bf16 v[40:43], v[148:151], v[192:195], v[40:43]
	v_mfma_f32_16x16x32_bf16 v[52:55], v[32:35], v[192:195], v[52:55]
	v_mfma_f32_16x16x32_bf16 v[56:59], v[148:151], v[200:203], v[56:59]
	v_mfma_f32_16x16x32_bf16 v[80:83], v[32:35], v[200:203], v[80:83]
	v_mfma_f32_16x16x32_bf16 v[44:47], v[148:151], v[208:211], v[44:47]
	v_mfma_f32_16x16x32_bf16 v[24:27], v[32:35], v[208:211], v[24:27]
	s_setprio 0
	s_barrier
; #define G_BAR __builtin_amdgcn_s_barrier()
; template <int NSTORE, class TF, class F>
; DEVI void gemm_run(const bf16_t* __restrict__ A, int lda, const bf16_t* __restrict__ Bt, int ldb, int K, bf16_t* shm, TF&& tile, F&& emit) {
;     ...
;         if (NSTORE != 0 && wr == 0) G_BAR;
; #pragma unroll
;         for (int ai = 0; ai < 2; ++ai)
; #pragma unroll
;             for (int m = 0; m < 4; ++m)
; #pragma unroll
;                 for (int bj = 0; bj < 2; ++bj)
;                     emit(brow + ai * HALF + wr * 64 + m * 16 + fr, bcol + bj * HALF + wc * 32 + fq * 8, acc[ai][bj][m][0], acc[ai][bj][m][1]);
;         if (!has_next) break;
; #pragma unroll
;         for (int a = 0; a < 2; ++a)
; #pragma unroll
;             for (int b = 0; b < 2; ++b)
; #pragma unroll
;                 for (int m = 0; m < 4; ++m)
; #pragma unroll
;                     for (int n = 0; n < 2; ++n) acc[a][b][m][n] = (f32x4){0.f, 0.f, 0.f, 0.f};
;         brow = nrow; bcol = ncol; cA = nA; cB = nB; ++ui;
	v_readlane_b32 s28, v252, 8
	v_add_u32_e32 v32, s3, v19
	v_readlane_b32 s29, v252, 9
	v_add_u32_e32 v134, s33, v16
	s_movk_i32 s3, 0x600
	v_mov_b64_e32 v[128:129], s[28:29]
	v_ashrrev_i32_e32 v33, 31, v32
	v_mad_i64_i32 v[34:35], s[28:29], v134, s3, v[128:129]
	v_lshlrev_b64 v[130:131], 1, v[32:33]
	v_lshl_add_u64 v[132:133], v[34:35], 0, v[130:131]
	v_cvt_pk_bf16_f32 v32, v84, v85
	v_cvt_pk_bf16_f32 v33, v86, v87
	v_cvt_pk_bf16_f32 v34, v88, v89
	v_cvt_pk_bf16_f32 v35, v90, v91
	global_store_dwordx4 v[132:133], v[32:35], off
	v_cvt_pk_bf16_f32 v8, v8, v9
	v_cvt_pk_bf16_f32 v9, v10, v11
	v_cvt_pk_bf16_f32 v32, v116, v117
	v_cvt_pk_bf16_f32 v33, v118, v119
	v_cvt_pk_bf16_f32 v34, v120, v121
	v_cvt_pk_bf16_f32 v35, v122, v123
	global_store_dwordx4 v[132:133], v[32:35], off offset:256
	v_cvt_pk_bf16_f32 v10, v12, v13
	v_cvt_pk_bf16_f32 v11, v14, v15
	v_add_u32_e32 v32, 16, v134
	v_mad_i64_i32 v[32:33], s[28:29], v32, s3, v[128:129]
	v_lshl_add_u64 v[84:85], v[32:33], 0, v[130:131]
	v_cvt_pk_bf16_f32 v32, v92, v93
	v_cvt_pk_bf16_f32 v33, v94, v95
	v_cvt_pk_bf16_f32 v34, v96, v97
	v_cvt_pk_bf16_f32 v35, v98, v99
	global_store_dwordx4 v[84:85], v[32:35], off
	v_readlane_b32 s72, v255, 16
	s_andn2_b64 vcc, exec, s[38:39]
	v_cvt_pk_bf16_f32 v32, v124, v125
	v_cvt_pk_bf16_f32 v33, v126, v127
	v_cvt_pk_bf16_f32 v34, v60, v61
	v_cvt_pk_bf16_f32 v35, v62, v63
	global_store_dwordx4 v[84:85], v[32:35], off offset:256
	s_mov_b32 s33, s70
	s_mov_b64 s[44:45], s[0:1]
	v_add_u32_e32 v32, 32, v134
	v_mad_i64_i32 v[32:33], s[28:29], v32, s3, v[128:129]
	v_lshl_add_u64 v[60:61], v[32:33], 0, v[130:131]
	v_cvt_pk_bf16_f32 v32, v100, v101
	v_cvt_pk_bf16_f32 v33, v102, v103
	v_cvt_pk_bf16_f32 v34, v104, v105
	v_cvt_pk_bf16_f32 v35, v106, v107
	global_store_dwordx4 v[60:61], v[32:35], off
	s_mov_b64 s[42:43], s[40:41]
	v_readlane_b32 s73, v255, 17
	v_cvt_pk_bf16_f32 v32, v64, v65
	v_cvt_pk_bf16_f32 v33, v66, v67
	v_cvt_pk_bf16_f32 v34, v68, v69
	v_cvt_pk_bf16_f32 v35, v70, v71
	global_store_dwordx4 v[60:61], v[32:35], off offset:256
	v_readlane_b32 s74, v255, 18
	v_readlane_b32 s75, v255, 19
	v_add_u32_e32 v32, 48, v134
	v_mad_i64_i32 v[32:33], s[28:29], v32, s3, v[128:129]
	v_lshl_add_u64 v[60:61], v[32:33], 0, v[130:131]
	v_cvt_pk_bf16_f32 v32, v108, v109
	v_cvt_pk_bf16_f32 v33, v110, v111
	v_cvt_pk_bf16_f32 v34, v112, v113
	v_cvt_pk_bf16_f32 v35, v114, v115
	global_store_dwordx4 v[60:61], v[32:35], off
	s_nop 1
	v_cvt_pk_bf16_f32 v32, v72, v73
	v_cvt_pk_bf16_f32 v33, v74, v75
	v_cvt_pk_bf16_f32 v34, v76, v77
	v_cvt_pk_bf16_f32 v35, v78, v79
	global_store_dwordx4 v[60:61], v[32:35], off offset:256
	s_nop 1
	v_add_u32_e32 v32, 0x80, v134
	v_mad_i64_i32 v[32:33], s[28:29], v32, s3, v[128:129]
	v_lshl_add_u64 v[32:33], v[32:33], 0, v[130:131]
	global_store_dwordx4 v[32:33], v[8:11], off
	s_nop 1
	v_cvt_pk_bf16_f32 v8, v28, v29
	v_cvt_pk_bf16_f32 v9, v30, v31
	v_cvt_pk_bf16_f32 v10, v36, v37
	v_cvt_pk_bf16_f32 v11, v38, v39
	global_store_dwordx4 v[32:33], v[8:11], off offset:256
	s_nop 1
	v_add_u32_e32 v8, 0x90, v134
	v_mad_i64_i32 v[8:9], s[28:29], v8, s3, v[128:129]
	v_lshl_add_u64 v[12:13], v[8:9], 0, v[130:131]
	v_cvt_pk_bf16_f32 v8, v156, v157
	v_cvt_pk_bf16_f32 v9, v158, v159
	v_cvt_pk_bf16_f32 v10, v160, v161
	v_cvt_pk_bf16_f32 v11, v162, v163
	global_store_dwordx4 v[12:13], v[8:11], off
	s_nop 1
	v_cvt_pk_bf16_f32 v8, v40, v41
	v_cvt_pk_bf16_f32 v9, v42, v43
	v_cvt_pk_bf16_f32 v10, v52, v53
	v_cvt_pk_bf16_f32 v11, v54, v55
	global_store_dwordx4 v[12:13], v[8:11], off offset:256
	s_nop 1
	v_add_u32_e32 v8, 0xa0, v134
	v_mad_i64_i32 v[8:9], s[28:29], v8, s3, v[128:129]
	v_lshl_add_u64 v[12:13], v[8:9], 0, v[130:131]
	v_cvt_pk_bf16_f32 v8, v164, v165
	v_cvt_pk_bf16_f32 v9, v166, v167
	v_cvt_pk_bf16_f32 v10, v168, v169
	v_cvt_pk_bf16_f32 v11, v170, v171
	global_store_dwordx4 v[12:13], v[8:11], off
	s_nop 1
	v_cvt_pk_bf16_f32 v8, v56, v57
	v_cvt_pk_bf16_f32 v9, v58, v59
	v_cvt_pk_bf16_f32 v10, v80, v81
	v_cvt_pk_bf16_f32 v11, v82, v83
	global_store_dwordx4 v[12:13], v[8:11], off offset:256
	s_nop 1
	v_add_u32_e32 v8, 0xb0, v134
	v_mad_i64_i32 v[8:9], s[28:29], v8, s3, v[128:129]
	v_lshl_add_u64 v[12:13], v[8:9], 0, v[130:131]
	v_cvt_pk_bf16_f32 v8, v48, v49
	v_cvt_pk_bf16_f32 v9, v50, v51
	v_cvt_pk_bf16_f32 v10, v20, v21
	v_cvt_pk_bf16_f32 v11, v22, v23
	global_store_dwordx4 v[12:13], v[8:11], off
	s_mov_b32 s3, s71
	s_nop 0
	v_cvt_pk_bf16_f32 v8, v44, v45
	v_cvt_pk_bf16_f32 v9, v46, v47
	v_cvt_pk_bf16_f32 v10, v24, v25
	v_cvt_pk_bf16_f32 v11, v26, v27
	global_store_dwordx4 v[12:13], v[8:11], off offset:256
	s_cbranch_vccz .LBB0_357

; #define G_STAGE(bufoff, gbase, voff) do { _Pragma("unroll") for (int _i = 0; _i < 2; ++_i) \
;         __builtin_amdgcn_global_load_lds((const unsigned*)((const char*)(gbase) + (voff)[_i]), (LAS unsigned*)(lds + (bufoff) + ldsw + _i * 8192), 16, 0, 0); } while (0)
; #define G_LDA(dst, b, h) do { _Pragma("unroll") for (int m = 0; m < 4; ++m) _Pragma("unroll") for (int k = 0; k < 2; ++k) dst[m][k] = *(const LAS bf16x8*)(lds + G_SA(b, h) + aoff + m * 2048 + k * 1024); } while (0)
; #define G_LDB(dst, b, h) do { _Pragma("unroll") for (int n = 0; n < 2; ++n) _Pragma("unroll") for (int k = 0; k < 2; ++k) dst[n][k] = *(const LAS bf16x8*)(lds + G_SB(b, h) + boff + n * 2048 + k * 1024); } while (0)
; #define G_MMA(ai, bj, At, Bt_) do { __builtin_amdgcn_s_setprio(1); _Pragma("unroll") for (int m = 0; m < 4; ++m) _Pragma("unroll") for (int n = 0; n < 2; ++n) _Pragma("unroll") for (int k = 0; k < 2; ++k) \
;         acc[ai][bj][m][n] = __builtin_amdgcn_mfma_f32_16x16x32_bf16(Bt_[n][k], At[m][k], acc[ai][bj][m][n], 0, 0, 0); __builtin_amdgcn_s_setprio(0); } while (0)
; #define G_WAIT_V(n) asm volatile("s_waitcnt vmcnt(" #n ")" ::: "memory")
; #define G_WAIT_L(n) asm volatile("s_waitcnt lgkmcnt(" #n ")" ::: "memory")
; #define G_BAR __builtin_amdgcn_s_barrier()
; #define G_SCHED __builtin_amdgcn_sched_barrier(0)
; template <int NSTORE, class TF, class F>
; DEVI void gemm_run(const bf16_t* __restrict__ A, int lda, const bf16_t* __restrict__ Bt, int ldb, int K, bf16_t* shm, TF&& tile, F&& emit) {
;     ...
;         for (int t = 0; t < nt; t += 2) {
;             const bool last = (t == nt - 2);
;             const char* a1 = cA + (size_t)(t + 1) * kstep;
;             const char* a2 = last ? nA : cA + (size_t)(t + 2) * kstep; const char* b2 = last ? nB : cB + (size_t)(t + 2) * kstep;
;             const char* a3 = a2 + kstep; const char* b3 = b2 + kstep;
;             G_LDB(B0, 0, 0); G_LDB(B1, 0, 1); G_SCHED; G_LDA(At, 0, 0); G_STAGE(G_SA(1, 1), a1 + hstepA, voffA);
;             G_WAIT_V(8); G_WAIT_L(0); G_BAR; G_MMA(0, 0, At, B0); G_MMA(0, 1, At, B1); G_BAR; G_SCHED;
;             G_LDA(At, 0, 1); G_STAGE(G_SB(0, 0), b2, voffB); G_STAGE(G_SB(0, 1), b2 + hstepB, voffB); G_STAGE(G_SA(0, 0), a2, voffA);
;             G_WAIT_V(8); G_WAIT_L(0); G_BAR; G_MMA(1, 0, At, B0); G_MMA(1, 1, At, B1); G_BAR; G_SCHED;
.LBB0_452:
	v_or_b32_e32 v144, 0x10000, v142
	v_add_u32_e32 v148, 0x10400, v142
	v_add_u32_e32 v152, 0x10800, v142
	v_add_u32_e32 v156, 0x10c00, v142
	v_or_b32_e32 v160, 0x14000, v142
	v_add_u32_e32 v164, 0x14400, v142
	v_add_u32_e32 v168, 0x14800, v142
	v_add_u32_e32 v176, 0x14c00, v142
	ds_read_b128 v[144:147], v144
	ds_read_b128 v[148:151], v148
	ds_read_b128 v[152:155], v152
	ds_read_b128 v[156:159], v156
	ds_read_b128 v[160:163], v160
	ds_read_b128 v[164:167], v164
	ds_read_b128 v[168:171], v168
	ds_read_b128 v[176:179], v176
	s_add_u32 s28, s70, 0xfffc0080
	s_addc_u32 s29, s71, -1
	s_cmp_eq_u32 s82, 12
	s_cselect_b32 s75, s41, s29
	s_cselect_b32 s74, s94, s28
	s_cselect_b32 s73, s43, s3
	s_cselect_b32 s72, s95, s33
	v_lshl_add_u64 v[216:217], s[70:71], 0, v[136:137]
	s_add_i32 m0, s14, 0xc000
	ds_read_b128 v[182:185], v141
	ds_read_b128 v[188:191], v141 offset:1024
	ds_read_b128 v[192:195], v141 offset:2048
	ds_read_b128 v[196:199], v141 offset:3072
	ds_read_b128 v[200:203], v141 offset:4096
	ds_read_b128 v[204:207], v141 offset:5120
	ds_read_b128 v[208:211], v141 offset:6144
	ds_read_b128 v[212:215], v141 offset:7168
	global_load_lds_dwordx4 v[216:217], off
	v_lshl_add_u64 v[216:217], s[70:71], 0, v[138:139]
	s_add_i32 m0, s14, 0xe000
	s_nop 0
	global_load_lds_dwordx4 v[216:217], off
	s_waitcnt vmcnt(8)
	s_waitcnt lgkmcnt(0)
	s_barrier
	s_setprio 1
	s_waitcnt lgkmcnt(0)
	v_mfma_f32_16x16x32_bf16 v[126:129], v[144:147], v[182:185], v[126:129]
	v_mfma_f32_16x16x32_bf16 v[122:125], v[152:155], v[182:185], v[122:125]
	v_mfma_f32_16x16x32_bf16 v[118:121], v[144:147], v[192:195], v[118:121]
	v_mfma_f32_16x16x32_bf16 v[114:117], v[152:155], v[192:195], v[114:117]
	v_mfma_f32_16x16x32_bf16 v[102:105], v[144:147], v[200:203], v[102:105]
	v_mfma_f32_16x16x32_bf16 v[98:101], v[152:155], v[200:203], v[98:101]
	v_mfma_f32_16x16x32_bf16 v[86:89], v[144:147], v[208:211], v[86:89]
	v_mfma_f32_16x16x32_bf16 v[82:85], v[152:155], v[208:211], v[82:85]
	v_mfma_f32_16x16x32_bf16 v[126:129], v[148:151], v[188:191], v[126:129]
	v_mfma_f32_16x16x32_bf16 v[122:125], v[156:159], v[188:191], v[122:125]
	v_mfma_f32_16x16x32_bf16 v[118:121], v[148:151], v[196:199], v[118:121]
	v_mfma_f32_16x16x32_bf16 v[114:117], v[156:159], v[196:199], v[114:117]
	v_mfma_f32_16x16x32_bf16 v[102:105], v[148:151], v[204:207], v[102:105]
	v_mfma_f32_16x16x32_bf16 v[98:101], v[156:159], v[204:207], v[98:101]
	v_mfma_f32_16x16x32_bf16 v[86:89], v[148:151], v[212:215], v[86:89]
	v_mfma_f32_16x16x32_bf16 v[82:85], v[156:159], v[212:215], v[82:85]
	v_mfma_f32_16x16x32_bf16 v[110:113], v[160:163], v[182:185], v[110:113]
	v_mfma_f32_16x16x32_bf16 v[106:109], v[168:171], v[182:185], v[106:109]
	v_mfma_f32_16x16x32_bf16 v[94:97], v[160:163], v[192:195], v[94:97]
	v_mfma_f32_16x16x32_bf16 v[90:93], v[168:171], v[192:195], v[90:93]
	v_mfma_f32_16x16x32_bf16 v[78:81], v[160:163], v[200:203], v[78:81]
	v_mfma_f32_16x16x32_bf16 v[74:77], v[168:171], v[200:203], v[74:77]
	v_mfma_f32_16x16x32_bf16 v[70:73], v[160:163], v[208:211], v[70:73]
	v_mfma_f32_16x16x32_bf16 v[66:69], v[168:171], v[208:211], v[66:69]
	v_mfma_f32_16x16x32_bf16 v[110:113], v[164:167], v[188:191], v[110:113]
	v_mfma_f32_16x16x32_bf16 v[106:109], v[176:179], v[188:191], v[106:109]
	v_mfma_f32_16x16x32_bf16 v[94:97], v[164:167], v[196:199], v[94:97]
	v_mfma_f32_16x16x32_bf16 v[90:93], v[176:179], v[196:199], v[90:93]
	v_mfma_f32_16x16x32_bf16 v[78:81], v[164:167], v[204:207], v[78:81]
	v_mfma_f32_16x16x32_bf16 v[74:77], v[176:179], v[204:207], v[74:77]
	v_mfma_f32_16x16x32_bf16 v[70:73], v[164:167], v[212:215], v[70:73]
	v_mfma_f32_16x16x32_bf16 v[66:69], v[176:179], v[212:215], v[66:69]
	s_setprio 0
	s_barrier
	s_mov_b32 m0, s15
	v_lshl_add_u64 v[216:217], s[72:73], 0, v[0:1]
	s_add_u32 s28, s72, 0x40000
	ds_read_b128 v[182:185], v141 offset:16384
	ds_read_b128 v[188:191], v141 offset:17408
	ds_read_b128 v[192:195], v141 offset:18432
	ds_read_b128 v[196:199], v141 offset:19456
	ds_read_b128 v[200:203], v141 offset:20480
	ds_read_b128 v[204:207], v141 offset:21504
	ds_read_b128 v[208:211], v141 offset:22528
	ds_read_b128 v[212:215], v141 offset:23552
	global_load_lds_dwordx4 v[216:217], off
	v_lshl_add_u64 v[218:219], s[72:73], 0, v[130:131]
	s_mov_b32 m0, s16
	s_addc_u32 s29, s73, 0
	global_load_lds_dwordx4 v[218:219], off
	v_lshl_add_u64 v[220:221], s[28:29], 0, v[0:1]
	s_mov_b32 m0, s17
	v_lshl_add_u64 v[222:223], s[74:75], 0, v[132:133]
	global_load_lds_dwordx4 v[220:221], off
	v_lshl_add_u64 v[220:221], s[28:29], 0, v[130:131]
	s_mov_b32 m0, s18
	s_nop 0
	global_load_lds_dwordx4 v[220:221], off
	v_lshl_add_u64 v[220:221], s[74:75], 0, v[134:135]
	s_mov_b32 m0, s14
	s_nop 0
	global_load_lds_dwordx4 v[220:221], off
	s_mov_b32 m0, s19
	s_nop 0
	global_load_lds_dwordx4 v[222:223], off
	s_waitcnt vmcnt(8)
	s_waitcnt lgkmcnt(0)
	s_barrier
; #define G_STAGE(bufoff, gbase, voff) do { _Pragma("unroll") for (int _i = 0; _i < 2; ++_i) \
;         __builtin_amdgcn_global_load_lds((const unsigned*)((const char*)(gbase) + (voff)[_i]), (LAS unsigned*)(lds + (bufoff) + ldsw + _i * 8192), 16, 0, 0); } while (0)
; #define G_LDA(dst, b, h) do { _Pragma("unroll") for (int m = 0; m < 4; ++m) _Pragma("unroll") for (int k = 0; k < 2; ++k) dst[m][k] = *(const LAS bf16x8*)(lds + G_SA(b, h) + aoff + m * 2048 + k * 1024); } while (0)
; #define G_LDB(dst, b, h) do { _Pragma("unroll") for (int n = 0; n < 2; ++n) _Pragma("unroll") for (int k = 0; k < 2; ++k) dst[n][k] = *(const LAS bf16x8*)(lds + G_SB(b, h) + boff + n * 2048 + k * 1024); } while (0)
; #define G_MMA(ai, bj, At, Bt_) do { __builtin_amdgcn_s_setprio(1); _Pragma("unroll") for (int m = 0; m < 4; ++m) _Pragma("unroll") for (int n = 0; n < 2; ++n) _Pragma("unroll") for (int k = 0; k < 2; ++k) \
;         acc[ai][bj][m][n] = __builtin_amdgcn_mfma_f32_16x16x32_bf16(Bt_[n][k], At[m][k], acc[ai][bj][m][n], 0, 0, 0); __builtin_amdgcn_s_setprio(0); } while (0)
; #define G_WAIT_V(n) asm volatile("s_waitcnt vmcnt(" #n ")" ::: "memory")
; #define G_WAIT_L(n) asm volatile("s_waitcnt lgkmcnt(" #n ")" ::: "memory")
; #define G_BAR __builtin_amdgcn_s_barrier()
; #define G_SCHED __builtin_amdgcn_sched_barrier(0)
; template <int NSTORE, class TF, class F>
; DEVI void gemm_run(const bf16_t* __restrict__ A, int lda, const bf16_t* __restrict__ Bt, int ldb, int K, bf16_t* shm, TF&& tile, F&& emit) {
;     ...
;             G_WAIT_V(8); G_WAIT_L(0); G_BAR; G_MMA(1, 0, At, B0); G_MMA(1, 1, At, B1); G_BAR; G_SCHED;
;             G_LDB(B0, 1, 0); G_LDB(B1, 1, 1); G_SCHED; G_LDA(At, 1, 0); G_STAGE(G_SA(0, 1), a2 + hstepA, voffA);
;             G_WAIT_V(8); G_WAIT_L(0); G_BAR; G_MMA(0, 0, At, B0); G_MMA(0, 1, At, B1); G_BAR; G_SCHED;
	s_setprio 1
	s_waitcnt lgkmcnt(0)
	v_mfma_f32_16x16x32_bf16 v[62:65], v[144:147], v[182:185], v[62:65]
	v_mfma_f32_16x16x32_bf16 v[58:61], v[152:155], v[182:185], v[58:61]
	v_mfma_f32_16x16x32_bf16 v[54:57], v[144:147], v[192:195], v[54:57]
	v_mfma_f32_16x16x32_bf16 v[50:53], v[152:155], v[192:195], v[50:53]
	v_mfma_f32_16x16x32_bf16 v[38:41], v[144:147], v[200:203], v[38:41]
	v_mfma_f32_16x16x32_bf16 v[34:37], v[152:155], v[200:203], v[34:37]
	v_mfma_f32_16x16x32_bf16 v[22:25], v[144:147], v[208:211], v[22:25]
	v_mfma_f32_16x16x32_bf16 v[18:21], v[152:155], v[208:211], v[18:21]
	v_mfma_f32_16x16x32_bf16 v[62:65], v[148:151], v[188:191], v[62:65]
	v_mfma_f32_16x16x32_bf16 v[58:61], v[156:159], v[188:191], v[58:61]
	v_mfma_f32_16x16x32_bf16 v[54:57], v[148:151], v[196:199], v[54:57]
	v_mfma_f32_16x16x32_bf16 v[50:53], v[156:159], v[196:199], v[50:53]
	v_mfma_f32_16x16x32_bf16 v[38:41], v[148:151], v[204:207], v[38:41]
	v_mfma_f32_16x16x32_bf16 v[34:37], v[156:159], v[204:207], v[34:37]
	v_mfma_f32_16x16x32_bf16 v[22:25], v[148:151], v[212:215], v[22:25]
	v_mfma_f32_16x16x32_bf16 v[18:21], v[156:159], v[212:215], v[18:21]
	v_mfma_f32_16x16x32_bf16 v[46:49], v[160:163], v[182:185], v[46:49]
	v_mfma_f32_16x16x32_bf16 v[42:45], v[168:171], v[182:185], v[42:45]
	v_mfma_f32_16x16x32_bf16 v[30:33], v[160:163], v[192:195], v[30:33]
	v_mfma_f32_16x16x32_bf16 v[26:29], v[168:171], v[192:195], v[26:29]
	v_mfma_f32_16x16x32_bf16 v[14:17], v[160:163], v[200:203], v[14:17]
	v_mfma_f32_16x16x32_bf16 v[10:13], v[168:171], v[200:203], v[10:13]
	v_mfma_f32_16x16x32_bf16 v[6:9], v[160:163], v[208:211], v[6:9]
	v_mfma_f32_16x16x32_bf16 v[2:5], v[168:171], v[208:211], v[2:5]
	v_mfma_f32_16x16x32_bf16 v[46:49], v[164:167], v[188:191], v[46:49]
	v_mfma_f32_16x16x32_bf16 v[42:45], v[176:179], v[188:191], v[42:45]
	v_mfma_f32_16x16x32_bf16 v[30:33], v[164:167], v[196:199], v[30:33]
	v_mfma_f32_16x16x32_bf16 v[26:29], v[176:179], v[196:199], v[26:29]
	v_mfma_f32_16x16x32_bf16 v[14:17], v[164:167], v[204:207], v[14:17]
	v_mfma_f32_16x16x32_bf16 v[10:13], v[176:179], v[204:207], v[10:13]
	v_mfma_f32_16x16x32_bf16 v[6:9], v[164:167], v[212:215], v[6:9]
	v_mfma_f32_16x16x32_bf16 v[2:5], v[176:179], v[212:215], v[2:5]
	s_setprio 0
	s_barrier
	v_or_b32_e32 v144, 0x18000, v142
	v_add_u32_e32 v148, 0x18400, v142
	v_add_u32_e32 v152, 0x18800, v142
	v_add_u32_e32 v156, 0x18c00, v142
	v_or_b32_e32 v160, 0x1c000, v142
	v_add_u32_e32 v164, 0x1c400, v142
	v_add_u32_e32 v168, 0x1c800, v142
	v_add_u32_e32 v176, 0x1cc00, v142
	ds_read_b128 v[144:147], v144
	ds_read_b128 v[148:151], v148
	ds_read_b128 v[152:155], v152
	ds_read_b128 v[156:159], v156
	ds_read_b128 v[160:163], v160
	ds_read_b128 v[164:167], v164
	ds_read_b128 v[168:171], v168
	ds_read_b128 v[176:179], v176
	s_add_u32 s28, s74, 0x40000
	s_addc_u32 s29, s75, 0
	s_mov_b32 m0, s76
	v_lshl_add_u64 v[224:225], s[28:29], 0, v[134:135]
	ds_read_b128 v[182:185], v141 offset:32768
	ds_read_b128 v[188:191], v141 offset:33792
	ds_read_b128 v[192:195], v141 offset:34816
	ds_read_b128 v[196:199], v141 offset:35840
	ds_read_b128 v[200:203], v141 offset:36864
	ds_read_b128 v[204:207], v141 offset:37888
	ds_read_b128 v[208:211], v141 offset:38912
	ds_read_b128 v[212:215], v141 offset:39936
	global_load_lds_dwordx4 v[224:225], off
	v_lshl_add_u64 v[224:225], s[28:29], 0, v[132:133]
	s_mov_b32 m0, s77
	s_nop 0
	global_load_lds_dwordx4 v[224:225], off
	s_waitcnt vmcnt(8)
	s_waitcnt lgkmcnt(0)
	s_barrier
	s_setprio 1
	s_waitcnt lgkmcnt(0)
	v_mfma_f32_16x16x32_bf16 v[126:129], v[144:147], v[182:185], v[126:129]
	v_mfma_f32_16x16x32_bf16 v[122:125], v[152:155], v[182:185], v[122:125]
	v_mfma_f32_16x16x32_bf16 v[118:121], v[144:147], v[192:195], v[118:121]
	v_mfma_f32_16x16x32_bf16 v[114:117], v[152:155], v[192:195], v[114:117]
	v_mfma_f32_16x16x32_bf16 v[102:105], v[144:147], v[200:203], v[102:105]
	v_mfma_f32_16x16x32_bf16 v[98:101], v[152:155], v[200:203], v[98:101]
	v_mfma_f32_16x16x32_bf16 v[86:89], v[144:147], v[208:211], v[86:89]
	v_mfma_f32_16x16x32_bf16 v[82:85], v[152:155], v[208:211], v[82:85]
	v_mfma_f32_16x16x32_bf16 v[126:129], v[148:151], v[188:191], v[126:129]
	v_mfma_f32_16x16x32_bf16 v[122:125], v[156:159], v[188:191], v[122:125]
	v_mfma_f32_16x16x32_bf16 v[118:121], v[148:151], v[196:199], v[118:121]
	v_mfma_f32_16x16x32_bf16 v[114:117], v[156:159], v[196:199], v[114:117]
	v_mfma_f32_16x16x32_bf16 v[102:105], v[148:151], v[204:207], v[102:105]
	v_mfma_f32_16x16x32_bf16 v[98:101], v[156:159], v[204:207], v[98:101]
	v_mfma_f32_16x16x32_bf16 v[86:89], v[148:151], v[212:215], v[86:89]
	v_mfma_f32_16x16x32_bf16 v[82:85], v[156:159], v[212:215], v[82:85]
	v_mfma_f32_16x16x32_bf16 v[110:113], v[160:163], v[182:185], v[110:113]
	v_mfma_f32_16x16x32_bf16 v[106:109], v[168:171], v[182:185], v[106:109]
	v_mfma_f32_16x16x32_bf16 v[94:97], v[160:163], v[192:195], v[94:97]
	v_mfma_f32_16x16x32_bf16 v[90:93], v[168:171], v[192:195], v[90:93]
	v_mfma_f32_16x16x32_bf16 v[78:81], v[160:163], v[200:203], v[78:81]
	v_mfma_f32_16x16x32_bf16 v[74:77], v[168:171], v[200:203], v[74:77]
	v_mfma_f32_16x16x32_bf16 v[70:73], v[160:163], v[208:211], v[70:73]
	v_mfma_f32_16x16x32_bf16 v[66:69], v[168:171], v[208:211], v[66:69]
	v_mfma_f32_16x16x32_bf16 v[110:113], v[164:167], v[188:191], v[110:113]
	v_mfma_f32_16x16x32_bf16 v[106:109], v[176:179], v[188:191], v[106:109]
	v_mfma_f32_16x16x32_bf16 v[94:97], v[164:167], v[196:199], v[94:97]
	v_mfma_f32_16x16x32_bf16 v[90:93], v[176:179], v[196:199], v[90:93]
	v_mfma_f32_16x16x32_bf16 v[78:81], v[164:167], v[204:207], v[78:81]
	v_mfma_f32_16x16x32_bf16 v[74:77], v[176:179], v[204:207], v[74:77]
	v_mfma_f32_16x16x32_bf16 v[70:73], v[164:167], v[212:215], v[70:73]
	v_mfma_f32_16x16x32_bf16 v[66:69], v[176:179], v[212:215], v[66:69]
	s_setprio 0
	s_barrier
; #define G_STAGE(bufoff, gbase, voff) do { _Pragma("unroll") for (int _i = 0; _i < 2; ++_i) \
;         __builtin_amdgcn_global_load_lds((const unsigned*)((const char*)(gbase) + (voff)[_i]), (LAS unsigned*)(lds + (bufoff) + ldsw + _i * 8192), 16, 0, 0); } while (0)
; #define G_LDA(dst, b, h) do { _Pragma("unroll") for (int m = 0; m < 4; ++m) _Pragma("unroll") for (int k = 0; k < 2; ++k) dst[m][k] = *(const LAS bf16x8*)(lds + G_SA(b, h) + aoff + m * 2048 + k * 1024); } while (0)
; #define G_MMA(ai, bj, At, Bt_) do { __builtin_amdgcn_s_setprio(1); _Pragma("unroll") for (int m = 0; m < 4; ++m) _Pragma("unroll") for (int n = 0; n < 2; ++n) _Pragma("unroll") for (int k = 0; k < 2; ++k) \
;         acc[ai][bj][m][n] = __builtin_amdgcn_mfma_f32_16x16x32_bf16(Bt_[n][k], At[m][k], acc[ai][bj][m][n], 0, 0, 0); __builtin_amdgcn_s_setprio(0); } while (0)
; #define G_WAIT_V(n) asm volatile("s_waitcnt vmcnt(" #n ")" ::: "memory")
; #define G_WAIT_L(n) asm volatile("s_waitcnt lgkmcnt(" #n ")" ::: "memory")
; #define G_BAR __builtin_amdgcn_s_barrier()
; #define G_SCHED __builtin_amdgcn_sched_barrier(0)
; template <int NSTORE, class TF, class F>
; DEVI void gemm_run(const bf16_t* __restrict__ A, int lda, const bf16_t* __restrict__ Bt, int ldb, int K, bf16_t* shm, TF&& tile, F&& emit) {
;     ...
;             G_LDA(At, 1, 1); G_STAGE(G_SB(1, 0), b3, voffB); G_STAGE(G_SB(1, 1), b3 + hstepB, voffB); G_STAGE(G_SA(1, 0), a3, voffA);
;             G_WAIT_V(8); G_WAIT_L(0); G_BAR; G_MMA(1, 0, At, B0); G_MMA(1, 1, At, B1); G_BAR; G_SCHED;
;         }
;         if (NSTORE != 0 && wr == 0) G_BAR;
	s_mov_b32 m0, s8
	v_lshl_add_u64 v[216:217], v[216:217], 0, s[30:31]
	s_add_u32 s28, s72, 0x40080
	ds_read_b128 v[182:185], v141 offset:49152
	ds_read_b128 v[188:191], v141 offset:50176
	ds_read_b128 v[192:195], v141 offset:51200
	ds_read_b128 v[196:199], v141 offset:52224
	ds_read_b128 v[200:203], v141 offset:53248
	ds_read_b128 v[204:207], v141 offset:54272
	ds_read_b128 v[208:211], v141 offset:55296
	ds_read_b128 v[212:215], v141 offset:56320
	global_load_lds_dwordx4 v[216:217], off
	v_lshl_add_u64 v[216:217], v[218:219], 0, s[30:31]
	s_mov_b32 m0, s9
	s_addc_u32 s29, s73, 0
	global_load_lds_dwordx4 v[216:217], off
	v_lshl_add_u64 v[216:217], s[28:29], 0, v[0:1]
	s_mov_b32 m0, s78
	s_nop 0
	global_load_lds_dwordx4 v[216:217], off
	v_lshl_add_u64 v[216:217], s[28:29], 0, v[130:131]
	s_mov_b32 m0, s79
	s_nop 0
	global_load_lds_dwordx4 v[216:217], off
	v_lshl_add_u64 v[216:217], v[220:221], 0, s[30:31]
	s_mov_b32 m0, s26
	s_nop 0
	global_load_lds_dwordx4 v[216:217], off
	v_lshl_add_u64 v[216:217], v[222:223], 0, s[30:31]
	s_mov_b32 m0, s27
	s_nop 0
	global_load_lds_dwordx4 v[216:217], off
	s_waitcnt vmcnt(8)
	s_waitcnt lgkmcnt(0)
	s_barrier
	s_setprio 1
	s_waitcnt lgkmcnt(0)
	v_mfma_f32_16x16x32_bf16 v[62:65], v[144:147], v[182:185], v[62:65]
	v_mfma_f32_16x16x32_bf16 v[58:61], v[152:155], v[182:185], v[58:61]
	v_mfma_f32_16x16x32_bf16 v[54:57], v[144:147], v[192:195], v[54:57]
	v_mfma_f32_16x16x32_bf16 v[50:53], v[152:155], v[192:195], v[50:53]
	v_mfma_f32_16x16x32_bf16 v[38:41], v[144:147], v[200:203], v[38:41]
	v_mfma_f32_16x16x32_bf16 v[34:37], v[152:155], v[200:203], v[34:37]
	v_mfma_f32_16x16x32_bf16 v[22:25], v[144:147], v[208:211], v[22:25]
	v_mfma_f32_16x16x32_bf16 v[18:21], v[152:155], v[208:211], v[18:21]
	v_mfma_f32_16x16x32_bf16 v[62:65], v[148:151], v[188:191], v[62:65]
	v_mfma_f32_16x16x32_bf16 v[58:61], v[156:159], v[188:191], v[58:61]
	v_mfma_f32_16x16x32_bf16 v[54:57], v[148:151], v[196:199], v[54:57]
	v_mfma_f32_16x16x32_bf16 v[50:53], v[156:159], v[196:199], v[50:53]
	v_mfma_f32_16x16x32_bf16 v[38:41], v[148:151], v[204:207], v[38:41]
	v_mfma_f32_16x16x32_bf16 v[34:37], v[156:159], v[204:207], v[34:37]
	v_mfma_f32_16x16x32_bf16 v[22:25], v[148:151], v[212:215], v[22:25]
	v_mfma_f32_16x16x32_bf16 v[18:21], v[156:159], v[212:215], v[18:21]
	v_mfma_f32_16x16x32_bf16 v[46:49], v[160:163], v[182:185], v[46:49]
	v_mfma_f32_16x16x32_bf16 v[42:45], v[168:171], v[182:185], v[42:45]
	v_mfma_f32_16x16x32_bf16 v[30:33], v[160:163], v[192:195], v[30:33]
	v_mfma_f32_16x16x32_bf16 v[26:29], v[168:171], v[192:195], v[26:29]
	v_mfma_f32_16x16x32_bf16 v[14:17], v[160:163], v[200:203], v[14:17]
	s_add_i32 s82, s82, 2
	v_mfma_f32_16x16x32_bf16 v[10:13], v[168:171], v[200:203], v[10:13]
	v_mfma_f32_16x16x32_bf16 v[6:9], v[160:163], v[208:211], v[6:9]
	s_add_u32 s70, s70, 0x100
	v_mfma_f32_16x16x32_bf16 v[2:5], v[168:171], v[208:211], v[2:5]
	v_mfma_f32_16x16x32_bf16 v[46:49], v[164:167], v[188:191], v[46:49]
	s_addc_u32 s71, s71, 0
	v_mfma_f32_16x16x32_bf16 v[42:45], v[176:179], v[188:191], v[42:45]
	v_mfma_f32_16x16x32_bf16 v[30:33], v[164:167], v[196:199], v[30:33]
	s_add_u32 s33, s33, 0x100
	v_mfma_f32_16x16x32_bf16 v[26:29], v[176:179], v[196:199], v[26:29]
	v_mfma_f32_16x16x32_bf16 v[14:17], v[164:167], v[204:207], v[14:17]
	s_addc_u32 s3, s3, 0
	v_mfma_f32_16x16x32_bf16 v[10:13], v[176:179], v[204:207], v[10:13]
	v_mfma_f32_16x16x32_bf16 v[6:9], v[164:167], v[212:215], v[6:9]
	s_cmp_gt_u32 s82, 13
	v_mfma_f32_16x16x32_bf16 v[2:5], v[176:179], v[212:215], v[2:5]
	s_setprio 0
	s_barrier
	s_cbranch_scc0 .LBB0_452
	s_and_b64 vcc, exec, s[38:39]
	s_cbranch_vccz .LBB0_455
	s_barrier

; #define G_STAGE(bufoff, gbase, voff) do { _Pragma("unroll") for (int _i = 0; _i < 2; ++_i) \
;         __builtin_amdgcn_global_load_lds((const unsigned*)((const char*)(gbase) + (voff)[_i]), (LAS unsigned*)(lds + (bufoff) + ldsw + _i * 8192), 16, 0, 0); } while (0)
; #define G_LDA(dst, b, h) do { _Pragma("unroll") for (int m = 0; m < 4; ++m) _Pragma("unroll") for (int k = 0; k < 2; ++k) dst[m][k] = *(const LAS bf16x8*)(lds + G_SA(b, h) + aoff + m * 2048 + k * 1024); } while (0)
; #define G_LDB(dst, b, h) do { _Pragma("unroll") for (int n = 0; n < 2; ++n) _Pragma("unroll") for (int k = 0; k < 2; ++k) dst[n][k] = *(const LAS bf16x8*)(lds + G_SB(b, h) + boff + n * 2048 + k * 1024); } while (0)
; #define G_MMA(ai, bj, At, Bt_) do { __builtin_amdgcn_s_setprio(1); _Pragma("unroll") for (int m = 0; m < 4; ++m) _Pragma("unroll") for (int n = 0; n < 2; ++n) _Pragma("unroll") for (int k = 0; k < 2; ++k) \
;         acc[ai][bj][m][n] = __builtin_amdgcn_mfma_f32_16x16x32_bf16(Bt_[n][k], At[m][k], acc[ai][bj][m][n], 0, 0, 0); __builtin_amdgcn_s_setprio(0); } while (0)
; #define G_WAIT_V(n) asm volatile("s_waitcnt vmcnt(" #n ")" ::: "memory")
; #define G_WAIT_L(n) asm volatile("s_waitcnt lgkmcnt(" #n ")" ::: "memory")
; #define G_BAR __builtin_amdgcn_s_barrier()
; #define G_SCHED __builtin_amdgcn_sched_barrier(0)
; template <int NSTORE, class TF, class F>
; DEVI void gemm_run(const bf16_t* __restrict__ A, int lda, const bf16_t* __restrict__ Bt, int ldb, int K, bf16_t* shm, TF&& tile, F&& emit) {
;     ...
;         for (int t = 0; t < nt; t += 2) {
;             const bool last = (t == nt - 2);
;             const char* a1 = cA + (size_t)(t + 1) * kstep;
;             const char* a2 = last ? nA : cA + (size_t)(t + 2) * kstep; const char* b2 = last ? nB : cB + (size_t)(t + 2) * kstep;
;             const char* a3 = a2 + kstep; const char* b3 = b2 + kstep;
;             G_LDB(B0, 0, 0); G_LDB(B1, 0, 1); G_SCHED; G_LDA(At, 0, 0); G_STAGE(G_SA(1, 1), a1 + hstepA, voffA);
;             G_WAIT_V(8); G_WAIT_L(0); G_BAR; G_MMA(0, 0, At, B0); G_MMA(0, 1, At, B1); G_BAR; G_SCHED;
;             G_LDA(At, 0, 1); G_STAGE(G_SB(0, 0), b2, voffB); G_STAGE(G_SB(0, 1), b2 + hstepB, voffB); G_STAGE(G_SA(0, 0), a2, voffA);
;             G_WAIT_V(8); G_WAIT_L(0); G_BAR; G_MMA(1, 0, At, B0); G_MMA(1, 1, At, B1); G_BAR; G_SCHED;
.LBB0_488:
	v_or_b32_e32 v144, 0x10000, v141
	v_add_u32_e32 v148, 0x10400, v141
	v_add_u32_e32 v152, 0x10800, v141
	v_add_u32_e32 v156, 0x10c00, v141
	v_or_b32_e32 v160, 0x14000, v141
	v_add_u32_e32 v164, 0x14400, v141
	v_add_u32_e32 v168, 0x14800, v141
	v_add_u32_e32 v176, 0x14c00, v141
	ds_read_b128 v[144:147], v144
	ds_read_b128 v[148:151], v148
	ds_read_b128 v[152:155], v152
	ds_read_b128 v[156:159], v156
	ds_read_b128 v[160:163], v160
	ds_read_b128 v[164:167], v164
	ds_read_b128 v[168:171], v168
	ds_read_b128 v[176:179], v176
	s_add_u32 s28, s74, 0xfff00080
	s_addc_u32 s29, s75, -1
	s_cmp_eq_u32 s82, 60
	s_cselect_b32 s79, s43, s29
	s_cselect_b32 s78, s47, s28
	s_cselect_b32 s77, s49, s3
	s_cselect_b32 s76, s69, s33
	v_lshl_add_u64 v[216:217], s[74:75], 0, v[136:137]
	s_add_i32 m0, s14, 0xc000
	ds_read_b128 v[182:185], v142
	ds_read_b128 v[188:191], v142 offset:1024
	ds_read_b128 v[192:195], v142 offset:2048
	ds_read_b128 v[196:199], v142 offset:3072
	ds_read_b128 v[200:203], v142 offset:4096
	ds_read_b128 v[204:207], v142 offset:5120
	ds_read_b128 v[208:211], v142 offset:6144
	ds_read_b128 v[212:215], v142 offset:7168
	global_load_lds_dwordx4 v[216:217], off
	v_lshl_add_u64 v[216:217], s[74:75], 0, v[138:139]
	s_add_i32 m0, s14, 0xe000
	s_nop 0
	global_load_lds_dwordx4 v[216:217], off
	s_waitcnt vmcnt(8)
	s_waitcnt lgkmcnt(0)
	s_barrier
	s_setprio 1
	s_waitcnt lgkmcnt(0)
	v_mfma_f32_16x16x32_bf16 v[126:129], v[144:147], v[182:185], v[126:129]
	v_mfma_f32_16x16x32_bf16 v[122:125], v[152:155], v[182:185], v[122:125]
	v_mfma_f32_16x16x32_bf16 v[118:121], v[144:147], v[192:195], v[118:121]
	v_mfma_f32_16x16x32_bf16 v[114:117], v[152:155], v[192:195], v[114:117]
	v_mfma_f32_16x16x32_bf16 v[102:105], v[144:147], v[200:203], v[102:105]
	v_mfma_f32_16x16x32_bf16 v[98:101], v[152:155], v[200:203], v[98:101]
	v_mfma_f32_16x16x32_bf16 v[86:89], v[144:147], v[208:211], v[86:89]
	v_mfma_f32_16x16x32_bf16 v[82:85], v[152:155], v[208:211], v[82:85]
	v_mfma_f32_16x16x32_bf16 v[126:129], v[148:151], v[188:191], v[126:129]
	v_mfma_f32_16x16x32_bf16 v[122:125], v[156:159], v[188:191], v[122:125]
	v_mfma_f32_16x16x32_bf16 v[118:121], v[148:151], v[196:199], v[118:121]
	v_mfma_f32_16x16x32_bf16 v[114:117], v[156:159], v[196:199], v[114:117]
	v_mfma_f32_16x16x32_bf16 v[102:105], v[148:151], v[204:207], v[102:105]
	v_mfma_f32_16x16x32_bf16 v[98:101], v[156:159], v[204:207], v[98:101]
	v_mfma_f32_16x16x32_bf16 v[86:89], v[148:151], v[212:215], v[86:89]
	v_mfma_f32_16x16x32_bf16 v[82:85], v[156:159], v[212:215], v[82:85]
	v_mfma_f32_16x16x32_bf16 v[110:113], v[160:163], v[182:185], v[110:113]
	v_mfma_f32_16x16x32_bf16 v[106:109], v[168:171], v[182:185], v[106:109]
	v_mfma_f32_16x16x32_bf16 v[94:97], v[160:163], v[192:195], v[94:97]
	v_mfma_f32_16x16x32_bf16 v[90:93], v[168:171], v[192:195], v[90:93]
	v_mfma_f32_16x16x32_bf16 v[78:81], v[160:163], v[200:203], v[78:81]
	v_mfma_f32_16x16x32_bf16 v[74:77], v[168:171], v[200:203], v[74:77]
	v_mfma_f32_16x16x32_bf16 v[70:73], v[160:163], v[208:211], v[70:73]
	v_mfma_f32_16x16x32_bf16 v[66:69], v[168:171], v[208:211], v[66:69]
	v_mfma_f32_16x16x32_bf16 v[110:113], v[164:167], v[188:191], v[110:113]
	v_mfma_f32_16x16x32_bf16 v[106:109], v[176:179], v[188:191], v[106:109]
	v_mfma_f32_16x16x32_bf16 v[94:97], v[164:167], v[196:199], v[94:97]
	v_mfma_f32_16x16x32_bf16 v[90:93], v[176:179], v[196:199], v[90:93]
	v_mfma_f32_16x16x32_bf16 v[78:81], v[164:167], v[204:207], v[78:81]
	v_mfma_f32_16x16x32_bf16 v[74:77], v[176:179], v[204:207], v[74:77]
	v_mfma_f32_16x16x32_bf16 v[70:73], v[164:167], v[212:215], v[70:73]
	v_mfma_f32_16x16x32_bf16 v[66:69], v[176:179], v[212:215], v[66:69]
	s_setprio 0
	s_barrier
	s_mov_b32 m0, s15
	v_lshl_add_u64 v[216:217], s[76:77], 0, v[0:1]
	s_add_u32 s28, s76, 0x100000
	ds_read_b128 v[182:185], v142 offset:16384
	ds_read_b128 v[188:191], v142 offset:17408
	ds_read_b128 v[192:195], v142 offset:18432
	ds_read_b128 v[196:199], v142 offset:19456
	ds_read_b128 v[200:203], v142 offset:20480
	ds_read_b128 v[204:207], v142 offset:21504
	ds_read_b128 v[208:211], v142 offset:22528
	ds_read_b128 v[212:215], v142 offset:23552
	global_load_lds_dwordx4 v[216:217], off
	v_lshl_add_u64 v[218:219], s[76:77], 0, v[134:135]
	s_mov_b32 m0, s16
	s_addc_u32 s29, s77, 0
	global_load_lds_dwordx4 v[218:219], off
	v_lshl_add_u64 v[220:221], s[28:29], 0, v[0:1]
	s_mov_b32 m0, s17
	v_lshl_add_u64 v[222:223], s[78:79], 0, v[132:133]
	global_load_lds_dwordx4 v[220:221], off
	v_lshl_add_u64 v[220:221], s[28:29], 0, v[134:135]
	s_mov_b32 m0, s18
	s_nop 0
	global_load_lds_dwordx4 v[220:221], off
	v_lshl_add_u64 v[220:221], s[78:79], 0, v[130:131]
	s_mov_b32 m0, s14
	s_nop 0
	global_load_lds_dwordx4 v[220:221], off
	s_mov_b32 m0, s19
	s_nop 0
	global_load_lds_dwordx4 v[222:223], off
	s_waitcnt vmcnt(8)
	s_waitcnt lgkmcnt(0)
	s_barrier
; #define G_STAGE(bufoff, gbase, voff) do { _Pragma("unroll") for (int _i = 0; _i < 2; ++_i) \
;         __builtin_amdgcn_global_load_lds((const unsigned*)((const char*)(gbase) + (voff)[_i]), (LAS unsigned*)(lds + (bufoff) + ldsw + _i * 8192), 16, 0, 0); } while (0)
; #define G_LDA(dst, b, h) do { _Pragma("unroll") for (int m = 0; m < 4; ++m) _Pragma("unroll") for (int k = 0; k < 2; ++k) dst[m][k] = *(const LAS bf16x8*)(lds + G_SA(b, h) + aoff + m * 2048 + k * 1024); } while (0)
; #define G_LDB(dst, b, h) do { _Pragma("unroll") for (int n = 0; n < 2; ++n) _Pragma("unroll") for (int k = 0; k < 2; ++k) dst[n][k] = *(const LAS bf16x8*)(lds + G_SB(b, h) + boff + n * 2048 + k * 1024); } while (0)
; #define G_MMA(ai, bj, At, Bt_) do { __builtin_amdgcn_s_setprio(1); _Pragma("unroll") for (int m = 0; m < 4; ++m) _Pragma("unroll") for (int n = 0; n < 2; ++n) _Pragma("unroll") for (int k = 0; k < 2; ++k) \
;         acc[ai][bj][m][n] = __builtin_amdgcn_mfma_f32_16x16x32_bf16(Bt_[n][k], At[m][k], acc[ai][bj][m][n], 0, 0, 0); __builtin_amdgcn_s_setprio(0); } while (0)
; #define G_WAIT_V(n) asm volatile("s_waitcnt vmcnt(" #n ")" ::: "memory")
; #define G_WAIT_L(n) asm volatile("s_waitcnt lgkmcnt(" #n ")" ::: "memory")
; #define G_BAR __builtin_amdgcn_s_barrier()
; #define G_SCHED __builtin_amdgcn_sched_barrier(0)
; template <int NSTORE, class TF, class F>
; DEVI void gemm_run(const bf16_t* __restrict__ A, int lda, const bf16_t* __restrict__ Bt, int ldb, int K, bf16_t* shm, TF&& tile, F&& emit) {
;     ...
;             G_WAIT_V(8); G_WAIT_L(0); G_BAR; G_MMA(1, 0, At, B0); G_MMA(1, 1, At, B1); G_BAR; G_SCHED;
;             G_LDB(B0, 1, 0); G_LDB(B1, 1, 1); G_SCHED; G_LDA(At, 1, 0); G_STAGE(G_SA(0, 1), a2 + hstepA, voffA);
;             G_WAIT_V(8); G_WAIT_L(0); G_BAR; G_MMA(0, 0, At, B0); G_MMA(0, 1, At, B1); G_BAR; G_SCHED;
	s_setprio 1
	s_waitcnt lgkmcnt(0)
	v_mfma_f32_16x16x32_bf16 v[62:65], v[144:147], v[182:185], v[62:65]
	v_mfma_f32_16x16x32_bf16 v[58:61], v[152:155], v[182:185], v[58:61]
	v_mfma_f32_16x16x32_bf16 v[54:57], v[144:147], v[192:195], v[54:57]
	v_mfma_f32_16x16x32_bf16 v[50:53], v[152:155], v[192:195], v[50:53]
	v_mfma_f32_16x16x32_bf16 v[38:41], v[144:147], v[200:203], v[38:41]
	v_mfma_f32_16x16x32_bf16 v[34:37], v[152:155], v[200:203], v[34:37]
	v_mfma_f32_16x16x32_bf16 v[22:25], v[144:147], v[208:211], v[22:25]
	v_mfma_f32_16x16x32_bf16 v[18:21], v[152:155], v[208:211], v[18:21]
	v_mfma_f32_16x16x32_bf16 v[62:65], v[148:151], v[188:191], v[62:65]
	v_mfma_f32_16x16x32_bf16 v[58:61], v[156:159], v[188:191], v[58:61]
	v_mfma_f32_16x16x32_bf16 v[54:57], v[148:151], v[196:199], v[54:57]
	v_mfma_f32_16x16x32_bf16 v[50:53], v[156:159], v[196:199], v[50:53]
	v_mfma_f32_16x16x32_bf16 v[38:41], v[148:151], v[204:207], v[38:41]
	v_mfma_f32_16x16x32_bf16 v[34:37], v[156:159], v[204:207], v[34:37]
	v_mfma_f32_16x16x32_bf16 v[22:25], v[148:151], v[212:215], v[22:25]
	v_mfma_f32_16x16x32_bf16 v[18:21], v[156:159], v[212:215], v[18:21]
	v_mfma_f32_16x16x32_bf16 v[46:49], v[160:163], v[182:185], v[46:49]
	v_mfma_f32_16x16x32_bf16 v[42:45], v[168:171], v[182:185], v[42:45]
	v_mfma_f32_16x16x32_bf16 v[30:33], v[160:163], v[192:195], v[30:33]
	v_mfma_f32_16x16x32_bf16 v[26:29], v[168:171], v[192:195], v[26:29]
	v_mfma_f32_16x16x32_bf16 v[14:17], v[160:163], v[200:203], v[14:17]
	v_mfma_f32_16x16x32_bf16 v[10:13], v[168:171], v[200:203], v[10:13]
	v_mfma_f32_16x16x32_bf16 v[6:9], v[160:163], v[208:211], v[6:9]
	v_mfma_f32_16x16x32_bf16 v[2:5], v[168:171], v[208:211], v[2:5]
	v_mfma_f32_16x16x32_bf16 v[46:49], v[164:167], v[188:191], v[46:49]
	v_mfma_f32_16x16x32_bf16 v[42:45], v[176:179], v[188:191], v[42:45]
	v_mfma_f32_16x16x32_bf16 v[30:33], v[164:167], v[196:199], v[30:33]
	v_mfma_f32_16x16x32_bf16 v[26:29], v[176:179], v[196:199], v[26:29]
	v_mfma_f32_16x16x32_bf16 v[14:17], v[164:167], v[204:207], v[14:17]
	v_mfma_f32_16x16x32_bf16 v[10:13], v[176:179], v[204:207], v[10:13]
	v_mfma_f32_16x16x32_bf16 v[6:9], v[164:167], v[212:215], v[6:9]
	v_mfma_f32_16x16x32_bf16 v[2:5], v[176:179], v[212:215], v[2:5]
	s_setprio 0
	s_barrier
	v_or_b32_e32 v144, 0x18000, v141
	v_add_u32_e32 v148, 0x18400, v141
	v_add_u32_e32 v152, 0x18800, v141
	v_add_u32_e32 v156, 0x18c00, v141
	v_or_b32_e32 v160, 0x1c000, v141
	v_add_u32_e32 v164, 0x1c400, v141
	v_add_u32_e32 v168, 0x1c800, v141
	v_add_u32_e32 v176, 0x1cc00, v141
	ds_read_b128 v[144:147], v144
	ds_read_b128 v[148:151], v148
	ds_read_b128 v[152:155], v152
	ds_read_b128 v[156:159], v156
	ds_read_b128 v[160:163], v160
	ds_read_b128 v[164:167], v164
	ds_read_b128 v[168:171], v168
	ds_read_b128 v[176:179], v176
	s_add_u32 s28, s78, 0x100000
	s_addc_u32 s29, s79, 0
	s_mov_b32 m0, s45
	v_lshl_add_u64 v[224:225], s[28:29], 0, v[130:131]
	ds_read_b128 v[182:185], v142 offset:32768
	ds_read_b128 v[188:191], v142 offset:33792
	ds_read_b128 v[192:195], v142 offset:34816
	ds_read_b128 v[196:199], v142 offset:35840
	ds_read_b128 v[200:203], v142 offset:36864
	ds_read_b128 v[204:207], v142 offset:37888
	ds_read_b128 v[208:211], v142 offset:38912
	ds_read_b128 v[212:215], v142 offset:39936
	global_load_lds_dwordx4 v[224:225], off
	v_lshl_add_u64 v[224:225], s[28:29], 0, v[132:133]
	s_mov_b32 m0, s83
	s_nop 0
	global_load_lds_dwordx4 v[224:225], off
	s_waitcnt vmcnt(8)
	s_waitcnt lgkmcnt(0)
	s_barrier
	s_setprio 1
	s_waitcnt lgkmcnt(0)
	v_mfma_f32_16x16x32_bf16 v[126:129], v[144:147], v[182:185], v[126:129]
	v_mfma_f32_16x16x32_bf16 v[122:125], v[152:155], v[182:185], v[122:125]
	v_mfma_f32_16x16x32_bf16 v[118:121], v[144:147], v[192:195], v[118:121]
	v_mfma_f32_16x16x32_bf16 v[114:117], v[152:155], v[192:195], v[114:117]
	v_mfma_f32_16x16x32_bf16 v[102:105], v[144:147], v[200:203], v[102:105]
	v_mfma_f32_16x16x32_bf16 v[98:101], v[152:155], v[200:203], v[98:101]
	v_mfma_f32_16x16x32_bf16 v[86:89], v[144:147], v[208:211], v[86:89]
	v_mfma_f32_16x16x32_bf16 v[82:85], v[152:155], v[208:211], v[82:85]
	v_mfma_f32_16x16x32_bf16 v[126:129], v[148:151], v[188:191], v[126:129]
	v_mfma_f32_16x16x32_bf16 v[122:125], v[156:159], v[188:191], v[122:125]
	v_mfma_f32_16x16x32_bf16 v[118:121], v[148:151], v[196:199], v[118:121]
	v_mfma_f32_16x16x32_bf16 v[114:117], v[156:159], v[196:199], v[114:117]
	v_mfma_f32_16x16x32_bf16 v[102:105], v[148:151], v[204:207], v[102:105]
	v_mfma_f32_16x16x32_bf16 v[98:101], v[156:159], v[204:207], v[98:101]
	v_mfma_f32_16x16x32_bf16 v[86:89], v[148:151], v[212:215], v[86:89]
	v_mfma_f32_16x16x32_bf16 v[82:85], v[156:159], v[212:215], v[82:85]
	v_mfma_f32_16x16x32_bf16 v[110:113], v[160:163], v[182:185], v[110:113]
	v_mfma_f32_16x16x32_bf16 v[106:109], v[168:171], v[182:185], v[106:109]
	v_mfma_f32_16x16x32_bf16 v[94:97], v[160:163], v[192:195], v[94:97]
	v_mfma_f32_16x16x32_bf16 v[90:93], v[168:171], v[192:195], v[90:93]
	v_mfma_f32_16x16x32_bf16 v[78:81], v[160:163], v[200:203], v[78:81]
	v_mfma_f32_16x16x32_bf16 v[74:77], v[168:171], v[200:203], v[74:77]
	v_mfma_f32_16x16x32_bf16 v[70:73], v[160:163], v[208:211], v[70:73]
	v_mfma_f32_16x16x32_bf16 v[66:69], v[168:171], v[208:211], v[66:69]
	v_mfma_f32_16x16x32_bf16 v[110:113], v[164:167], v[188:191], v[110:113]
	v_mfma_f32_16x16x32_bf16 v[106:109], v[176:179], v[188:191], v[106:109]
	v_mfma_f32_16x16x32_bf16 v[94:97], v[164:167], v[196:199], v[94:97]
	v_mfma_f32_16x16x32_bf16 v[90:93], v[176:179], v[196:199], v[90:93]
	v_mfma_f32_16x16x32_bf16 v[78:81], v[164:167], v[204:207], v[78:81]
	v_mfma_f32_16x16x32_bf16 v[74:77], v[176:179], v[204:207], v[74:77]
	v_mfma_f32_16x16x32_bf16 v[70:73], v[164:167], v[212:215], v[70:73]
	v_mfma_f32_16x16x32_bf16 v[66:69], v[176:179], v[212:215], v[66:69]
	s_setprio 0
	s_barrier
; #define G_STAGE(bufoff, gbase, voff) do { _Pragma("unroll") for (int _i = 0; _i < 2; ++_i) \
;         __builtin_amdgcn_global_load_lds((const unsigned*)((const char*)(gbase) + (voff)[_i]), (LAS unsigned*)(lds + (bufoff) + ldsw + _i * 8192), 16, 0, 0); } while (0)
; #define G_LDA(dst, b, h) do { _Pragma("unroll") for (int m = 0; m < 4; ++m) _Pragma("unroll") for (int k = 0; k < 2; ++k) dst[m][k] = *(const LAS bf16x8*)(lds + G_SA(b, h) + aoff + m * 2048 + k * 1024); } while (0)
; #define G_MMA(ai, bj, At, Bt_) do { __builtin_amdgcn_s_setprio(1); _Pragma("unroll") for (int m = 0; m < 4; ++m) _Pragma("unroll") for (int n = 0; n < 2; ++n) _Pragma("unroll") for (int k = 0; k < 2; ++k) \
;         acc[ai][bj][m][n] = __builtin_amdgcn_mfma_f32_16x16x32_bf16(Bt_[n][k], At[m][k], acc[ai][bj][m][n], 0, 0, 0); __builtin_amdgcn_s_setprio(0); } while (0)
; #define G_WAIT_V(n) asm volatile("s_waitcnt vmcnt(" #n ")" ::: "memory")
; #define G_WAIT_L(n) asm volatile("s_waitcnt lgkmcnt(" #n ")" ::: "memory")
; #define G_BAR __builtin_amdgcn_s_barrier()
; #define G_SCHED __builtin_amdgcn_sched_barrier(0)
; template <int NSTORE, class TF, class F>
; DEVI void gemm_run(const bf16_t* __restrict__ A, int lda, const bf16_t* __restrict__ Bt, int ldb, int K, bf16_t* shm, TF&& tile, F&& emit) {
;     ...
;             G_LDA(At, 1, 1); G_STAGE(G_SB(1, 0), b3, voffB); G_STAGE(G_SB(1, 1), b3 + hstepB, voffB); G_STAGE(G_SA(1, 0), a3, voffA);
;             G_WAIT_V(8); G_WAIT_L(0); G_BAR; G_MMA(1, 0, At, B0); G_MMA(1, 1, At, B1); G_BAR; G_SCHED;
;         }
;         if (NSTORE != 0 && wr == 0) G_BAR;
	s_mov_b32 m0, s94
	v_lshl_add_u64 v[216:217], v[216:217], 0, s[30:31]
	s_add_u32 s28, s76, 0x100080
	ds_read_b128 v[182:185], v142 offset:49152
	ds_read_b128 v[188:191], v142 offset:50176
	ds_read_b128 v[192:195], v142 offset:51200
	ds_read_b128 v[196:199], v142 offset:52224
	ds_read_b128 v[200:203], v142 offset:53248
	ds_read_b128 v[204:207], v142 offset:54272
	ds_read_b128 v[208:211], v142 offset:55296
	ds_read_b128 v[212:215], v142 offset:56320
	global_load_lds_dwordx4 v[216:217], off
	v_lshl_add_u64 v[216:217], v[218:219], 0, s[30:31]
	s_mov_b32 m0, s95
	s_addc_u32 s29, s77, 0
	global_load_lds_dwordx4 v[216:217], off
	v_lshl_add_u64 v[216:217], s[28:29], 0, v[0:1]
	s_mov_b32 m0, s26
	s_nop 0
	global_load_lds_dwordx4 v[216:217], off
	v_lshl_add_u64 v[216:217], s[28:29], 0, v[134:135]
	s_mov_b32 m0, s27
	s_nop 0
	global_load_lds_dwordx4 v[216:217], off
	v_lshl_add_u64 v[216:217], v[220:221], 0, s[30:31]
	s_mov_b32 m0, s8
	s_nop 0
	global_load_lds_dwordx4 v[216:217], off
	v_lshl_add_u64 v[216:217], v[222:223], 0, s[30:31]
	s_mov_b32 m0, s9
	s_nop 0
	global_load_lds_dwordx4 v[216:217], off
	s_waitcnt vmcnt(8)
	s_waitcnt lgkmcnt(0)
	s_barrier
	s_setprio 1
	s_waitcnt lgkmcnt(0)
	v_mfma_f32_16x16x32_bf16 v[62:65], v[144:147], v[182:185], v[62:65]
	v_mfma_f32_16x16x32_bf16 v[58:61], v[152:155], v[182:185], v[58:61]
	v_mfma_f32_16x16x32_bf16 v[54:57], v[144:147], v[192:195], v[54:57]
	v_mfma_f32_16x16x32_bf16 v[50:53], v[152:155], v[192:195], v[50:53]
	v_mfma_f32_16x16x32_bf16 v[38:41], v[144:147], v[200:203], v[38:41]
	v_mfma_f32_16x16x32_bf16 v[34:37], v[152:155], v[200:203], v[34:37]
	v_mfma_f32_16x16x32_bf16 v[22:25], v[144:147], v[208:211], v[22:25]
	v_mfma_f32_16x16x32_bf16 v[18:21], v[152:155], v[208:211], v[18:21]
	v_mfma_f32_16x16x32_bf16 v[62:65], v[148:151], v[188:191], v[62:65]
	v_mfma_f32_16x16x32_bf16 v[58:61], v[156:159], v[188:191], v[58:61]
	v_mfma_f32_16x16x32_bf16 v[54:57], v[148:151], v[196:199], v[54:57]
	v_mfma_f32_16x16x32_bf16 v[50:53], v[156:159], v[196:199], v[50:53]
	v_mfma_f32_16x16x32_bf16 v[38:41], v[148:151], v[204:207], v[38:41]
	v_mfma_f32_16x16x32_bf16 v[34:37], v[156:159], v[204:207], v[34:37]
	v_mfma_f32_16x16x32_bf16 v[22:25], v[148:151], v[212:215], v[22:25]
	v_mfma_f32_16x16x32_bf16 v[18:21], v[156:159], v[212:215], v[18:21]
	v_mfma_f32_16x16x32_bf16 v[46:49], v[160:163], v[182:185], v[46:49]
	v_mfma_f32_16x16x32_bf16 v[42:45], v[168:171], v[182:185], v[42:45]
	v_mfma_f32_16x16x32_bf16 v[30:33], v[160:163], v[192:195], v[30:33]
	v_mfma_f32_16x16x32_bf16 v[26:29], v[168:171], v[192:195], v[26:29]
	v_mfma_f32_16x16x32_bf16 v[14:17], v[160:163], v[200:203], v[14:17]
	s_add_i32 s82, s82, 2
	v_mfma_f32_16x16x32_bf16 v[10:13], v[168:171], v[200:203], v[10:13]
	v_mfma_f32_16x16x32_bf16 v[6:9], v[160:163], v[208:211], v[6:9]
	s_add_u32 s74, s74, 0x100
	v_mfma_f32_16x16x32_bf16 v[2:5], v[168:171], v[208:211], v[2:5]
	v_mfma_f32_16x16x32_bf16 v[46:49], v[164:167], v[188:191], v[46:49]
	s_addc_u32 s75, s75, 0
	v_mfma_f32_16x16x32_bf16 v[42:45], v[176:179], v[188:191], v[42:45]
	v_mfma_f32_16x16x32_bf16 v[30:33], v[164:167], v[196:199], v[30:33]
	s_add_u32 s33, s33, 0x100
	v_mfma_f32_16x16x32_bf16 v[26:29], v[176:179], v[196:199], v[26:29]
	v_mfma_f32_16x16x32_bf16 v[14:17], v[164:167], v[204:207], v[14:17]
	s_addc_u32 s3, s3, 0
	v_mfma_f32_16x16x32_bf16 v[10:13], v[176:179], v[204:207], v[10:13]
	v_mfma_f32_16x16x32_bf16 v[6:9], v[164:167], v[212:215], v[6:9]
	s_cmp_gt_u32 s82, 61
	v_mfma_f32_16x16x32_bf16 v[2:5], v[176:179], v[212:215], v[2:5]
	s_setprio 0
	s_barrier
	s_cbranch_scc0 .LBB0_488
	s_and_b64 vcc, exec, s[40:41]
	s_cbranch_vccz .LBB0_491
	s_barrier

; #define G_STAGE(bufoff, gbase, voff) do { _Pragma("unroll") for (int _i = 0; _i < 2; ++_i) \
;         __builtin_amdgcn_global_load_lds((const unsigned*)((const char*)(gbase) + (voff)[_i]), (LAS unsigned*)(lds + (bufoff) + ldsw + _i * 8192), 16, 0, 0); } while (0)
; #define G_LDA(dst, b, h) do { _Pragma("unroll") for (int m = 0; m < 4; ++m) _Pragma("unroll") for (int k = 0; k < 2; ++k) dst[m][k] = *(const LAS bf16x8*)(lds + G_SA(b, h) + aoff + m * 2048 + k * 1024); } while (0)
; #define G_LDB(dst, b, h) do { _Pragma("unroll") for (int n = 0; n < 2; ++n) _Pragma("unroll") for (int k = 0; k < 2; ++k) dst[n][k] = *(const LAS bf16x8*)(lds + G_SB(b, h) + boff + n * 2048 + k * 1024); } while (0)
; #define G_MMA(ai, bj, At, Bt_) do { __builtin_amdgcn_s_setprio(1); _Pragma("unroll") for (int m = 0; m < 4; ++m) _Pragma("unroll") for (int n = 0; n < 2; ++n) _Pragma("unroll") for (int k = 0; k < 2; ++k) \
;         acc[ai][bj][m][n] = __builtin_amdgcn_mfma_f32_16x16x32_bf16(Bt_[n][k], At[m][k], acc[ai][bj][m][n], 0, 0, 0); __builtin_amdgcn_s_setprio(0); } while (0)
; #define G_WAIT_V(n) asm volatile("s_waitcnt vmcnt(" #n ")" ::: "memory")
; #define G_WAIT_L(n) asm volatile("s_waitcnt lgkmcnt(" #n ")" ::: "memory")
; #define G_BAR __builtin_amdgcn_s_barrier()
; #define G_SCHED __builtin_amdgcn_sched_barrier(0)
; template <int NSTORE, class TF, class F>
; DEVI void gemm_run(const bf16_t* __restrict__ A, int lda, const bf16_t* __restrict__ Bt, int ldb, int K, bf16_t* shm, TF&& tile, F&& emit) {
;     ...
;         for (int t = 0; t < nt; t += 2) {
;             const bool last = (t == nt - 2);
;             const char* a1 = cA + (size_t)(t + 1) * kstep;
;             const char* a2 = last ? nA : cA + (size_t)(t + 2) * kstep; const char* b2 = last ? nB : cB + (size_t)(t + 2) * kstep;
;             const char* a3 = a2 + kstep; const char* b3 = b2 + kstep;
;             G_LDB(B0, 0, 0); G_LDB(B1, 0, 1); G_SCHED; G_LDA(At, 0, 0); G_STAGE(G_SA(1, 1), a1 + hstepA, voffA);
;             G_WAIT_V(8); G_WAIT_L(0); G_BAR; G_MMA(0, 0, At, B0); G_MMA(0, 1, At, B1); G_BAR; G_SCHED;
;             G_LDA(At, 0, 1); G_STAGE(G_SB(0, 0), b2, voffB); G_STAGE(G_SB(0, 1), b2 + hstepB, voffB); G_STAGE(G_SA(0, 0), a2, voffA);
;             G_WAIT_V(8); G_WAIT_L(0); G_BAR; G_MMA(1, 0, At, B0); G_MMA(1, 1, At, B1); G_BAR; G_SCHED;
.LBB0_512:
	v_or_b32_e32 v140, 0x10000, v144
	v_add_u32_e32 v141, 0x10400, v144
	ds_read_b128 v[146:149], v140
	ds_read_b128 v[150:153], v141
	v_add_u32_e32 v140, 0x10800, v144
	v_add_u32_e32 v141, 0x10c00, v144
	ds_read_b128 v[154:157], v140
	ds_read_b128 v[158:161], v141
	v_or_b32_e32 v140, 0x14000, v144
	v_add_u32_e32 v141, 0x14400, v144
	ds_read_b128 v[162:165], v140
	ds_read_b128 v[166:169], v141
	v_add_u32_e32 v140, 0x14800, v144
	v_add_u32_e32 v141, 0x14c00, v144
	ds_read_b128 v[176:179], v140
	ds_read_b128 v[182:185], v141
	s_add_u32 s28, s68, 0xfffc0080
	s_addc_u32 s29, s69, -1
	s_cmp_eq_u32 s82, 12
	s_cselect_b32 s73, s39, s29
	s_cselect_b32 s72, s48, s28
	s_cselect_b32 s71, s41, s3
	s_cselect_b32 s70, s49, s33
	v_lshl_add_u64 v[140:141], s[68:69], 0, v[136:137]
	s_add_i32 m0, s74, 0xc000
	ds_read_b128 v[188:191], v143
	ds_read_b128 v[192:195], v143 offset:1024
	ds_read_b128 v[196:199], v143 offset:2048
	ds_read_b128 v[200:203], v143 offset:3072
	ds_read_b128 v[204:207], v143 offset:4096
	ds_read_b128 v[208:211], v143 offset:5120
	ds_read_b128 v[212:215], v143 offset:6144
	ds_read_b128 v[216:219], v143 offset:7168
	global_load_lds_dwordx4 v[140:141], off
	v_lshl_add_u64 v[140:141], s[68:69], 0, v[138:139]
	s_add_i32 m0, s74, 0xe000
	s_nop 0
	global_load_lds_dwordx4 v[140:141], off
	s_waitcnt vmcnt(8)
	s_waitcnt lgkmcnt(0)
	s_barrier
	s_setprio 1
	s_waitcnt lgkmcnt(0)
	v_mfma_f32_16x16x32_bf16 v[126:129], v[146:149], v[188:191], v[126:129]
	v_mfma_f32_16x16x32_bf16 v[122:125], v[154:157], v[188:191], v[122:125]
	v_mfma_f32_16x16x32_bf16 v[110:113], v[146:149], v[196:199], v[110:113]
	v_mfma_f32_16x16x32_bf16 v[106:109], v[154:157], v[196:199], v[106:109]
	v_mfma_f32_16x16x32_bf16 v[94:97], v[146:149], v[204:207], v[94:97]
	v_mfma_f32_16x16x32_bf16 v[90:93], v[154:157], v[204:207], v[90:93]
	v_mfma_f32_16x16x32_bf16 v[78:81], v[146:149], v[212:215], v[78:81]
	v_mfma_f32_16x16x32_bf16 v[74:77], v[154:157], v[212:215], v[74:77]
	v_mfma_f32_16x16x32_bf16 v[126:129], v[150:153], v[192:195], v[126:129]
	v_mfma_f32_16x16x32_bf16 v[122:125], v[158:161], v[192:195], v[122:125]
	v_mfma_f32_16x16x32_bf16 v[110:113], v[150:153], v[200:203], v[110:113]
	v_mfma_f32_16x16x32_bf16 v[106:109], v[158:161], v[200:203], v[106:109]
	v_mfma_f32_16x16x32_bf16 v[94:97], v[150:153], v[208:211], v[94:97]
	v_mfma_f32_16x16x32_bf16 v[90:93], v[158:161], v[208:211], v[90:93]
	v_mfma_f32_16x16x32_bf16 v[78:81], v[150:153], v[216:219], v[78:81]
	v_mfma_f32_16x16x32_bf16 v[74:77], v[158:161], v[216:219], v[74:77]
	v_mfma_f32_16x16x32_bf16 v[118:121], v[162:165], v[188:191], v[118:121]
	v_mfma_f32_16x16x32_bf16 v[114:117], v[176:179], v[188:191], v[114:117]
	v_mfma_f32_16x16x32_bf16 v[102:105], v[162:165], v[196:199], v[102:105]
	v_mfma_f32_16x16x32_bf16 v[98:101], v[176:179], v[196:199], v[98:101]
	v_mfma_f32_16x16x32_bf16 v[86:89], v[162:165], v[204:207], v[86:89]
	v_mfma_f32_16x16x32_bf16 v[82:85], v[176:179], v[204:207], v[82:85]
	v_mfma_f32_16x16x32_bf16 v[70:73], v[162:165], v[212:215], v[70:73]
	v_mfma_f32_16x16x32_bf16 v[66:69], v[176:179], v[212:215], v[66:69]
	v_mfma_f32_16x16x32_bf16 v[118:121], v[166:169], v[192:195], v[118:121]
	v_mfma_f32_16x16x32_bf16 v[114:117], v[182:185], v[192:195], v[114:117]
	v_mfma_f32_16x16x32_bf16 v[102:105], v[166:169], v[200:203], v[102:105]
	v_mfma_f32_16x16x32_bf16 v[98:101], v[182:185], v[200:203], v[98:101]
	v_mfma_f32_16x16x32_bf16 v[86:89], v[166:169], v[208:211], v[86:89]
	v_mfma_f32_16x16x32_bf16 v[82:85], v[182:185], v[208:211], v[82:85]
	v_mfma_f32_16x16x32_bf16 v[70:73], v[166:169], v[216:219], v[70:73]
	v_mfma_f32_16x16x32_bf16 v[66:69], v[182:185], v[216:219], v[66:69]
	s_setprio 0
	s_barrier
	s_mov_b32 m0, s75
	v_lshl_add_u64 v[140:141], s[70:71], 0, v[0:1]
	s_add_u32 s28, s70, 0x40000
	ds_read_b128 v[188:191], v143 offset:16384
	ds_read_b128 v[192:195], v143 offset:17408
	ds_read_b128 v[196:199], v143 offset:18432
	ds_read_b128 v[200:203], v143 offset:19456
	ds_read_b128 v[204:207], v143 offset:20480
	ds_read_b128 v[208:211], v143 offset:21504
	ds_read_b128 v[212:215], v143 offset:22528
	ds_read_b128 v[216:219], v143 offset:23552
	global_load_lds_dwordx4 v[140:141], off
	v_lshl_add_u64 v[170:171], s[70:71], 0, v[130:131]
	s_mov_b32 m0, s76
	s_addc_u32 s29, s71, 0
	global_load_lds_dwordx4 v[170:171], off
	v_lshl_add_u64 v[220:221], s[28:29], 0, v[0:1]
	s_mov_b32 m0, s77
	v_lshl_add_u64 v[222:223], s[72:73], 0, v[132:133]
	global_load_lds_dwordx4 v[220:221], off
	v_lshl_add_u64 v[220:221], s[28:29], 0, v[130:131]
	s_mov_b32 m0, s78
	s_nop 0
	global_load_lds_dwordx4 v[220:221], off
	v_lshl_add_u64 v[220:221], s[72:73], 0, v[134:135]
	s_mov_b32 m0, s74
	s_nop 0
	global_load_lds_dwordx4 v[220:221], off
	s_mov_b32 m0, s79
	s_nop 0
	global_load_lds_dwordx4 v[222:223], off
	s_waitcnt vmcnt(8)
	s_waitcnt lgkmcnt(0)
	s_barrier
; #define G_STAGE(bufoff, gbase, voff) do { _Pragma("unroll") for (int _i = 0; _i < 2; ++_i) \
;         __builtin_amdgcn_global_load_lds((const unsigned*)((const char*)(gbase) + (voff)[_i]), (LAS unsigned*)(lds + (bufoff) + ldsw + _i * 8192), 16, 0, 0); } while (0)
; #define G_LDA(dst, b, h) do { _Pragma("unroll") for (int m = 0; m < 4; ++m) _Pragma("unroll") for (int k = 0; k < 2; ++k) dst[m][k] = *(const LAS bf16x8*)(lds + G_SA(b, h) + aoff + m * 2048 + k * 1024); } while (0)
; #define G_LDB(dst, b, h) do { _Pragma("unroll") for (int n = 0; n < 2; ++n) _Pragma("unroll") for (int k = 0; k < 2; ++k) dst[n][k] = *(const LAS bf16x8*)(lds + G_SB(b, h) + boff + n * 2048 + k * 1024); } while (0)
; #define G_MMA(ai, bj, At, Bt_) do { __builtin_amdgcn_s_setprio(1); _Pragma("unroll") for (int m = 0; m < 4; ++m) _Pragma("unroll") for (int n = 0; n < 2; ++n) _Pragma("unroll") for (int k = 0; k < 2; ++k) \
;         acc[ai][bj][m][n] = __builtin_amdgcn_mfma_f32_16x16x32_bf16(Bt_[n][k], At[m][k], acc[ai][bj][m][n], 0, 0, 0); __builtin_amdgcn_s_setprio(0); } while (0)
; #define G_WAIT_V(n) asm volatile("s_waitcnt vmcnt(" #n ")" ::: "memory")
; #define G_WAIT_L(n) asm volatile("s_waitcnt lgkmcnt(" #n ")" ::: "memory")
; #define G_BAR __builtin_amdgcn_s_barrier()
; #define G_SCHED __builtin_amdgcn_sched_barrier(0)
; template <int NSTORE, class TF, class F>
; DEVI void gemm_run(const bf16_t* __restrict__ A, int lda, const bf16_t* __restrict__ Bt, int ldb, int K, bf16_t* shm, TF&& tile, F&& emit) {
;     ...
;             G_WAIT_V(8); G_WAIT_L(0); G_BAR; G_MMA(1, 0, At, B0); G_MMA(1, 1, At, B1); G_BAR; G_SCHED;
;             G_LDB(B0, 1, 0); G_LDB(B1, 1, 1); G_SCHED; G_LDA(At, 1, 0); G_STAGE(G_SA(0, 1), a2 + hstepA, voffA);
;             G_WAIT_V(8); G_WAIT_L(0); G_BAR; G_MMA(0, 0, At, B0); G_MMA(0, 1, At, B1); G_BAR; G_SCHED;
	s_setprio 1
	s_waitcnt lgkmcnt(0)
	v_mfma_f32_16x16x32_bf16 v[62:65], v[146:149], v[188:191], v[62:65]
	v_mfma_f32_16x16x32_bf16 v[58:61], v[154:157], v[188:191], v[58:61]
	v_mfma_f32_16x16x32_bf16 v[46:49], v[146:149], v[196:199], v[46:49]
	v_mfma_f32_16x16x32_bf16 v[42:45], v[154:157], v[196:199], v[42:45]
	v_mfma_f32_16x16x32_bf16 v[30:33], v[146:149], v[204:207], v[30:33]
	v_mfma_f32_16x16x32_bf16 v[26:29], v[154:157], v[204:207], v[26:29]
	v_mfma_f32_16x16x32_bf16 v[14:17], v[146:149], v[212:215], v[14:17]
	v_mfma_f32_16x16x32_bf16 v[10:13], v[154:157], v[212:215], v[10:13]
	v_mfma_f32_16x16x32_bf16 v[62:65], v[150:153], v[192:195], v[62:65]
	v_mfma_f32_16x16x32_bf16 v[58:61], v[158:161], v[192:195], v[58:61]
	v_mfma_f32_16x16x32_bf16 v[46:49], v[150:153], v[200:203], v[46:49]
	v_mfma_f32_16x16x32_bf16 v[42:45], v[158:161], v[200:203], v[42:45]
	v_mfma_f32_16x16x32_bf16 v[30:33], v[150:153], v[208:211], v[30:33]
	v_mfma_f32_16x16x32_bf16 v[26:29], v[158:161], v[208:211], v[26:29]
	v_mfma_f32_16x16x32_bf16 v[14:17], v[150:153], v[216:219], v[14:17]
	v_mfma_f32_16x16x32_bf16 v[10:13], v[158:161], v[216:219], v[10:13]
	v_mfma_f32_16x16x32_bf16 v[54:57], v[162:165], v[188:191], v[54:57]
	v_mfma_f32_16x16x32_bf16 v[50:53], v[176:179], v[188:191], v[50:53]
	v_mfma_f32_16x16x32_bf16 v[38:41], v[162:165], v[196:199], v[38:41]
	v_mfma_f32_16x16x32_bf16 v[34:37], v[176:179], v[196:199], v[34:37]
	v_mfma_f32_16x16x32_bf16 v[22:25], v[162:165], v[204:207], v[22:25]
	v_mfma_f32_16x16x32_bf16 v[18:21], v[176:179], v[204:207], v[18:21]
	v_mfma_f32_16x16x32_bf16 v[6:9], v[162:165], v[212:215], v[6:9]
	v_mfma_f32_16x16x32_bf16 v[2:5], v[176:179], v[212:215], v[2:5]
	v_mfma_f32_16x16x32_bf16 v[54:57], v[166:169], v[192:195], v[54:57]
	v_mfma_f32_16x16x32_bf16 v[50:53], v[182:185], v[192:195], v[50:53]
	v_mfma_f32_16x16x32_bf16 v[38:41], v[166:169], v[200:203], v[38:41]
	v_mfma_f32_16x16x32_bf16 v[34:37], v[182:185], v[200:203], v[34:37]
	v_mfma_f32_16x16x32_bf16 v[22:25], v[166:169], v[208:211], v[22:25]
	v_mfma_f32_16x16x32_bf16 v[18:21], v[182:185], v[208:211], v[18:21]
	v_mfma_f32_16x16x32_bf16 v[6:9], v[166:169], v[216:219], v[6:9]
	v_mfma_f32_16x16x32_bf16 v[2:5], v[182:185], v[216:219], v[2:5]
	s_setprio 0
	s_barrier
	v_or_b32_e32 v146, 0x18000, v144
	v_add_u32_e32 v150, 0x18400, v144
	v_add_u32_e32 v154, 0x18800, v144
	v_add_u32_e32 v158, 0x18c00, v144
	v_or_b32_e32 v162, 0x1c000, v144
	v_add_u32_e32 v166, 0x1c400, v144
	v_add_u32_e32 v176, 0x1c800, v144
	v_add_u32_e32 v182, 0x1cc00, v144
	ds_read_b128 v[146:149], v146
	ds_read_b128 v[150:153], v150
	ds_read_b128 v[154:157], v154
	ds_read_b128 v[158:161], v158
	ds_read_b128 v[162:165], v162
	ds_read_b128 v[166:169], v166
	ds_read_b128 v[176:179], v176
	ds_read_b128 v[182:185], v182
	s_add_u32 s28, s72, 0x40000
	s_addc_u32 s29, s73, 0
	s_mov_b32 m0, s95
	v_lshl_add_u64 v[224:225], s[28:29], 0, v[134:135]
	ds_read_b128 v[188:191], v143 offset:32768
	ds_read_b128 v[192:195], v143 offset:33792
	ds_read_b128 v[196:199], v143 offset:34816
	ds_read_b128 v[200:203], v143 offset:35840
	ds_read_b128 v[204:207], v143 offset:36864
	ds_read_b128 v[208:211], v143 offset:37888
	ds_read_b128 v[212:215], v143 offset:38912
	ds_read_b128 v[216:219], v143 offset:39936
	global_load_lds_dwordx4 v[224:225], off
	v_lshl_add_u64 v[224:225], s[28:29], 0, v[132:133]
	s_mov_b32 m0, s18
	s_nop 0
	global_load_lds_dwordx4 v[224:225], off
	s_waitcnt vmcnt(8)
	s_waitcnt lgkmcnt(0)
	s_barrier
	s_setprio 1
	s_waitcnt lgkmcnt(0)
	v_mfma_f32_16x16x32_bf16 v[126:129], v[146:149], v[188:191], v[126:129]
	v_mfma_f32_16x16x32_bf16 v[122:125], v[154:157], v[188:191], v[122:125]
	v_mfma_f32_16x16x32_bf16 v[110:113], v[146:149], v[196:199], v[110:113]
	v_mfma_f32_16x16x32_bf16 v[106:109], v[154:157], v[196:199], v[106:109]
	v_mfma_f32_16x16x32_bf16 v[94:97], v[146:149], v[204:207], v[94:97]
	v_mfma_f32_16x16x32_bf16 v[90:93], v[154:157], v[204:207], v[90:93]
	v_mfma_f32_16x16x32_bf16 v[78:81], v[146:149], v[212:215], v[78:81]
	v_mfma_f32_16x16x32_bf16 v[74:77], v[154:157], v[212:215], v[74:77]
	v_mfma_f32_16x16x32_bf16 v[126:129], v[150:153], v[192:195], v[126:129]
	v_mfma_f32_16x16x32_bf16 v[122:125], v[158:161], v[192:195], v[122:125]
	v_mfma_f32_16x16x32_bf16 v[110:113], v[150:153], v[200:203], v[110:113]
	v_mfma_f32_16x16x32_bf16 v[106:109], v[158:161], v[200:203], v[106:109]
	v_mfma_f32_16x16x32_bf16 v[94:97], v[150:153], v[208:211], v[94:97]
	v_mfma_f32_16x16x32_bf16 v[90:93], v[158:161], v[208:211], v[90:93]
	v_mfma_f32_16x16x32_bf16 v[78:81], v[150:153], v[216:219], v[78:81]
	v_mfma_f32_16x16x32_bf16 v[74:77], v[158:161], v[216:219], v[74:77]
	v_mfma_f32_16x16x32_bf16 v[118:121], v[162:165], v[188:191], v[118:121]
	v_mfma_f32_16x16x32_bf16 v[114:117], v[176:179], v[188:191], v[114:117]
	v_mfma_f32_16x16x32_bf16 v[102:105], v[162:165], v[196:199], v[102:105]
	v_mfma_f32_16x16x32_bf16 v[98:101], v[176:179], v[196:199], v[98:101]
	v_mfma_f32_16x16x32_bf16 v[86:89], v[162:165], v[204:207], v[86:89]
	v_mfma_f32_16x16x32_bf16 v[82:85], v[176:179], v[204:207], v[82:85]
	v_mfma_f32_16x16x32_bf16 v[70:73], v[162:165], v[212:215], v[70:73]
	v_mfma_f32_16x16x32_bf16 v[66:69], v[176:179], v[212:215], v[66:69]
	v_mfma_f32_16x16x32_bf16 v[118:121], v[166:169], v[192:195], v[118:121]
	v_mfma_f32_16x16x32_bf16 v[114:117], v[182:185], v[192:195], v[114:117]
	v_mfma_f32_16x16x32_bf16 v[102:105], v[166:169], v[200:203], v[102:105]
	v_mfma_f32_16x16x32_bf16 v[98:101], v[182:185], v[200:203], v[98:101]
	v_mfma_f32_16x16x32_bf16 v[86:89], v[166:169], v[208:211], v[86:89]
	v_mfma_f32_16x16x32_bf16 v[82:85], v[182:185], v[208:211], v[82:85]
	v_mfma_f32_16x16x32_bf16 v[70:73], v[166:169], v[216:219], v[70:73]
	v_mfma_f32_16x16x32_bf16 v[66:69], v[182:185], v[216:219], v[66:69]
	s_setprio 0
	s_barrier
; #define G_STAGE(bufoff, gbase, voff) do { _Pragma("unroll") for (int _i = 0; _i < 2; ++_i) \
;         __builtin_amdgcn_global_load_lds((const unsigned*)((const char*)(gbase) + (voff)[_i]), (LAS unsigned*)(lds + (bufoff) + ldsw + _i * 8192), 16, 0, 0); } while (0)
; #define G_LDA(dst, b, h) do { _Pragma("unroll") for (int m = 0; m < 4; ++m) _Pragma("unroll") for (int k = 0; k < 2; ++k) dst[m][k] = *(const LAS bf16x8*)(lds + G_SA(b, h) + aoff + m * 2048 + k * 1024); } while (0)
; #define G_MMA(ai, bj, At, Bt_) do { __builtin_amdgcn_s_setprio(1); _Pragma("unroll") for (int m = 0; m < 4; ++m) _Pragma("unroll") for (int n = 0; n < 2; ++n) _Pragma("unroll") for (int k = 0; k < 2; ++k) \
;         acc[ai][bj][m][n] = __builtin_amdgcn_mfma_f32_16x16x32_bf16(Bt_[n][k], At[m][k], acc[ai][bj][m][n], 0, 0, 0); __builtin_amdgcn_s_setprio(0); } while (0)
; #define G_WAIT_V(n) asm volatile("s_waitcnt vmcnt(" #n ")" ::: "memory")
; #define G_WAIT_L(n) asm volatile("s_waitcnt lgkmcnt(" #n ")" ::: "memory")
; #define G_BAR __builtin_amdgcn_s_barrier()
; #define G_SCHED __builtin_amdgcn_sched_barrier(0)
; template <int NSTORE, class TF, class F>
; DEVI void gemm_run(const bf16_t* __restrict__ A, int lda, const bf16_t* __restrict__ Bt, int ldb, int K, bf16_t* shm, TF&& tile, F&& emit) {
;     ...
;             G_LDA(At, 1, 1); G_STAGE(G_SB(1, 0), b3, voffB); G_STAGE(G_SB(1, 1), b3 + hstepB, voffB); G_STAGE(G_SA(1, 0), a3, voffA);
;             G_WAIT_V(8); G_WAIT_L(0); G_BAR; G_MMA(1, 0, At, B0); G_MMA(1, 1, At, B1); G_BAR; G_SCHED;
;         }
;         if (NSTORE != 0 && wr == 0) G_BAR;
	s_mov_b32 m0, s19
	v_lshl_add_u64 v[140:141], v[140:141], 0, s[30:31]
	s_add_u32 s28, s70, 0x40080
	ds_read_b128 v[188:191], v143 offset:49152
	ds_read_b128 v[192:195], v143 offset:50176
	ds_read_b128 v[196:199], v143 offset:51200
	ds_read_b128 v[200:203], v143 offset:52224
	ds_read_b128 v[204:207], v143 offset:53248
	ds_read_b128 v[208:211], v143 offset:54272
	ds_read_b128 v[212:215], v143 offset:55296
	ds_read_b128 v[216:219], v143 offset:56320
	global_load_lds_dwordx4 v[140:141], off
	v_lshl_add_u64 v[140:141], v[170:171], 0, s[30:31]
	s_mov_b32 m0, s14
	s_addc_u32 s29, s71, 0
	global_load_lds_dwordx4 v[140:141], off
	v_lshl_add_u64 v[140:141], s[28:29], 0, v[0:1]
	s_mov_b32 m0, s17
	s_nop 0
	global_load_lds_dwordx4 v[140:141], off
	v_lshl_add_u64 v[140:141], s[28:29], 0, v[130:131]
	s_mov_b32 m0, s94
	s_nop 0
	global_load_lds_dwordx4 v[140:141], off
	v_lshl_add_u64 v[140:141], v[220:221], 0, s[30:31]
	s_mov_b32 m0, s15
	s_nop 0
	global_load_lds_dwordx4 v[140:141], off
	v_lshl_add_u64 v[140:141], v[222:223], 0, s[30:31]
	s_mov_b32 m0, s16
	s_nop 0
	global_load_lds_dwordx4 v[140:141], off
	s_waitcnt vmcnt(8)
	s_waitcnt lgkmcnt(0)
	s_barrier
	s_setprio 1
	s_waitcnt lgkmcnt(0)
	v_mfma_f32_16x16x32_bf16 v[62:65], v[146:149], v[188:191], v[62:65]
	v_mfma_f32_16x16x32_bf16 v[58:61], v[154:157], v[188:191], v[58:61]
	v_mfma_f32_16x16x32_bf16 v[46:49], v[146:149], v[196:199], v[46:49]
	v_mfma_f32_16x16x32_bf16 v[42:45], v[154:157], v[196:199], v[42:45]
	v_mfma_f32_16x16x32_bf16 v[30:33], v[146:149], v[204:207], v[30:33]
	v_mfma_f32_16x16x32_bf16 v[26:29], v[154:157], v[204:207], v[26:29]
	v_mfma_f32_16x16x32_bf16 v[14:17], v[146:149], v[212:215], v[14:17]
	v_mfma_f32_16x16x32_bf16 v[10:13], v[154:157], v[212:215], v[10:13]
	v_mfma_f32_16x16x32_bf16 v[62:65], v[150:153], v[192:195], v[62:65]
	v_mfma_f32_16x16x32_bf16 v[58:61], v[158:161], v[192:195], v[58:61]
	v_mfma_f32_16x16x32_bf16 v[46:49], v[150:153], v[200:203], v[46:49]
	v_mfma_f32_16x16x32_bf16 v[42:45], v[158:161], v[200:203], v[42:45]
	v_mfma_f32_16x16x32_bf16 v[30:33], v[150:153], v[208:211], v[30:33]
	v_mfma_f32_16x16x32_bf16 v[26:29], v[158:161], v[208:211], v[26:29]
	v_mfma_f32_16x16x32_bf16 v[14:17], v[150:153], v[216:219], v[14:17]
	v_mfma_f32_16x16x32_bf16 v[10:13], v[158:161], v[216:219], v[10:13]
	v_mfma_f32_16x16x32_bf16 v[54:57], v[162:165], v[188:191], v[54:57]
	v_mfma_f32_16x16x32_bf16 v[50:53], v[176:179], v[188:191], v[50:53]
	v_mfma_f32_16x16x32_bf16 v[38:41], v[162:165], v[196:199], v[38:41]
	v_mfma_f32_16x16x32_bf16 v[34:37], v[176:179], v[196:199], v[34:37]
	v_mfma_f32_16x16x32_bf16 v[22:25], v[162:165], v[204:207], v[22:25]
	s_add_i32 s82, s82, 2
	v_mfma_f32_16x16x32_bf16 v[18:21], v[176:179], v[204:207], v[18:21]
	v_mfma_f32_16x16x32_bf16 v[6:9], v[162:165], v[212:215], v[6:9]
	s_add_u32 s68, s68, 0x100
	v_mfma_f32_16x16x32_bf16 v[2:5], v[176:179], v[212:215], v[2:5]
	v_mfma_f32_16x16x32_bf16 v[54:57], v[166:169], v[192:195], v[54:57]
	s_addc_u32 s69, s69, 0
	v_mfma_f32_16x16x32_bf16 v[50:53], v[182:185], v[192:195], v[50:53]
	v_mfma_f32_16x16x32_bf16 v[38:41], v[166:169], v[200:203], v[38:41]
	s_add_u32 s33, s33, 0x100
	v_mfma_f32_16x16x32_bf16 v[34:37], v[182:185], v[200:203], v[34:37]
	v_mfma_f32_16x16x32_bf16 v[22:25], v[166:169], v[208:211], v[22:25]
	s_addc_u32 s3, s3, 0
	v_mfma_f32_16x16x32_bf16 v[18:21], v[182:185], v[208:211], v[18:21]
	v_mfma_f32_16x16x32_bf16 v[6:9], v[166:169], v[216:219], v[6:9]
	s_cmp_gt_u32 s82, 13
	v_mfma_f32_16x16x32_bf16 v[2:5], v[182:185], v[216:219], v[2:5]
	s_setprio 0
	s_barrier
	s_cbranch_scc0 .LBB0_512
	s_and_b64 vcc, exec, s[8:9]
	s_cbranch_vccz .LBB0_515
	s_barrier

; #define G_STAGE(bufoff, gbase, voff) do { _Pragma("unroll") for (int _i = 0; _i < 2; ++_i) \
;         __builtin_amdgcn_global_load_lds((const unsigned*)((const char*)(gbase) + (voff)[_i]), (LAS unsigned*)(lds + (bufoff) + ldsw + _i * 8192), 16, 0, 0); } while (0)
; #define G_LDA(dst, b, h) do { _Pragma("unroll") for (int m = 0; m < 4; ++m) _Pragma("unroll") for (int k = 0; k < 2; ++k) dst[m][k] = *(const LAS bf16x8*)(lds + G_SA(b, h) + aoff + m * 2048 + k * 1024); } while (0)
; #define G_LDB(dst, b, h) do { _Pragma("unroll") for (int n = 0; n < 2; ++n) _Pragma("unroll") for (int k = 0; k < 2; ++k) dst[n][k] = *(const LAS bf16x8*)(lds + G_SB(b, h) + boff + n * 2048 + k * 1024); } while (0)
; #define G_MMA(ai, bj, At, Bt_) do { __builtin_amdgcn_s_setprio(1); _Pragma("unroll") for (int m = 0; m < 4; ++m) _Pragma("unroll") for (int n = 0; n < 2; ++n) _Pragma("unroll") for (int k = 0; k < 2; ++k) \
;         acc[ai][bj][m][n] = __builtin_amdgcn_mfma_f32_16x16x32_bf16(Bt_[n][k], At[m][k], acc[ai][bj][m][n], 0, 0, 0); __builtin_amdgcn_s_setprio(0); } while (0)
; #define G_WAIT_V(n) asm volatile("s_waitcnt vmcnt(" #n ")" ::: "memory")
; #define G_WAIT_L(n) asm volatile("s_waitcnt lgkmcnt(" #n ")" ::: "memory")
; #define G_BAR __builtin_amdgcn_s_barrier()
; #define G_SCHED __builtin_amdgcn_sched_barrier(0)
; template <int NSTORE, class TF, class F>
; DEVI void gemm_run(const bf16_t* __restrict__ A, int lda, const bf16_t* __restrict__ Bt, int ldb, int K, bf16_t* shm, TF&& tile, F&& emit) {
;     ...
;         for (int t = 0; t < nt; t += 2) {
;             const bool last = (t == nt - 2);
;             const char* a1 = cA + (size_t)(t + 1) * kstep;
;             const char* a2 = last ? nA : cA + (size_t)(t + 2) * kstep; const char* b2 = last ? nB : cB + (size_t)(t + 2) * kstep;
;             const char* a3 = a2 + kstep; const char* b3 = b2 + kstep;
;             G_LDB(B0, 0, 0); G_LDB(B1, 0, 1); G_SCHED; G_LDA(At, 0, 0); G_STAGE(G_SA(1, 1), a1 + hstepA, voffA);
;             G_WAIT_V(8); G_WAIT_L(0); G_BAR; G_MMA(0, 0, At, B0); G_MMA(0, 1, At, B1); G_BAR; G_SCHED;
;             G_LDA(At, 0, 1); G_STAGE(G_SB(0, 0), b2, voffB); G_STAGE(G_SB(0, 1), b2 + hstepB, voffB); G_STAGE(G_SA(0, 0), a2, voffA);
;             G_WAIT_V(8); G_WAIT_L(0); G_BAR; G_MMA(1, 0, At, B0); G_MMA(1, 1, At, B1); G_BAR; G_SCHED;
.LBB0_545:
	v_or_b32_e32 v144, 0x10000, v142
	v_add_u32_e32 v148, 0x10400, v142
	v_add_u32_e32 v152, 0x10800, v142
	v_add_u32_e32 v156, 0x10c00, v142
	v_or_b32_e32 v160, 0x14000, v142
	v_add_u32_e32 v164, 0x14400, v142
	v_add_u32_e32 v168, 0x14800, v142
	v_add_u32_e32 v176, 0x14c00, v142
	ds_read_b128 v[144:147], v144
	ds_read_b128 v[148:151], v148
	ds_read_b128 v[152:155], v152
	ds_read_b128 v[156:159], v156
	ds_read_b128 v[160:163], v160
	ds_read_b128 v[164:167], v164
	ds_read_b128 v[168:171], v168
	ds_read_b128 v[176:179], v176
	s_add_u32 s28, s44, 0xfffc0080
	s_addc_u32 s29, s45, -1
	s_cmp_eq_u32 s82, 12
	s_cselect_b32 s69, s17, s29
	s_cselect_b32 s68, vcc_lo, s28
	s_cselect_b32 s47, s19, s3
	s_cselect_b32 s46, vcc_hi, s33
	v_lshl_add_u64 v[216:217], s[44:45], 0, v[136:137]
	s_add_i32 m0, s70, 0xc000
	ds_read_b128 v[182:185], v141
	ds_read_b128 v[188:191], v141 offset:1024
	ds_read_b128 v[192:195], v141 offset:2048
	ds_read_b128 v[196:199], v141 offset:3072
	ds_read_b128 v[200:203], v141 offset:4096
	ds_read_b128 v[204:207], v141 offset:5120
	ds_read_b128 v[208:211], v141 offset:6144
	ds_read_b128 v[212:215], v141 offset:7168
	global_load_lds_dwordx4 v[216:217], off
	v_lshl_add_u64 v[216:217], s[44:45], 0, v[138:139]
	s_add_i32 m0, s70, 0xe000
	s_nop 0
	global_load_lds_dwordx4 v[216:217], off
	s_waitcnt vmcnt(8)
	s_waitcnt lgkmcnt(0)
	s_barrier
	s_setprio 1
	s_waitcnt lgkmcnt(0)
	v_mfma_f32_16x16x32_bf16 v[126:129], v[144:147], v[182:185], v[126:129]
	v_mfma_f32_16x16x32_bf16 v[122:125], v[152:155], v[182:185], v[122:125]
	v_mfma_f32_16x16x32_bf16 v[118:121], v[144:147], v[192:195], v[118:121]
	v_mfma_f32_16x16x32_bf16 v[114:117], v[152:155], v[192:195], v[114:117]
	v_mfma_f32_16x16x32_bf16 v[102:105], v[144:147], v[200:203], v[102:105]
	v_mfma_f32_16x16x32_bf16 v[98:101], v[152:155], v[200:203], v[98:101]
	v_mfma_f32_16x16x32_bf16 v[86:89], v[144:147], v[208:211], v[86:89]
	v_mfma_f32_16x16x32_bf16 v[82:85], v[152:155], v[208:211], v[82:85]
	v_mfma_f32_16x16x32_bf16 v[126:129], v[148:151], v[188:191], v[126:129]
	v_mfma_f32_16x16x32_bf16 v[122:125], v[156:159], v[188:191], v[122:125]
	v_mfma_f32_16x16x32_bf16 v[118:121], v[148:151], v[196:199], v[118:121]
	v_mfma_f32_16x16x32_bf16 v[114:117], v[156:159], v[196:199], v[114:117]
	v_mfma_f32_16x16x32_bf16 v[102:105], v[148:151], v[204:207], v[102:105]
	v_mfma_f32_16x16x32_bf16 v[98:101], v[156:159], v[204:207], v[98:101]
	v_mfma_f32_16x16x32_bf16 v[86:89], v[148:151], v[212:215], v[86:89]
	v_mfma_f32_16x16x32_bf16 v[82:85], v[156:159], v[212:215], v[82:85]
	v_mfma_f32_16x16x32_bf16 v[110:113], v[160:163], v[182:185], v[110:113]
	v_mfma_f32_16x16x32_bf16 v[106:109], v[168:171], v[182:185], v[106:109]
	v_mfma_f32_16x16x32_bf16 v[94:97], v[160:163], v[192:195], v[94:97]
	v_mfma_f32_16x16x32_bf16 v[90:93], v[168:171], v[192:195], v[90:93]
	v_mfma_f32_16x16x32_bf16 v[78:81], v[160:163], v[200:203], v[78:81]
	v_mfma_f32_16x16x32_bf16 v[74:77], v[168:171], v[200:203], v[74:77]
	v_mfma_f32_16x16x32_bf16 v[70:73], v[160:163], v[208:211], v[70:73]
	v_mfma_f32_16x16x32_bf16 v[66:69], v[168:171], v[208:211], v[66:69]
	v_mfma_f32_16x16x32_bf16 v[110:113], v[164:167], v[188:191], v[110:113]
	v_mfma_f32_16x16x32_bf16 v[106:109], v[176:179], v[188:191], v[106:109]
	v_mfma_f32_16x16x32_bf16 v[94:97], v[164:167], v[196:199], v[94:97]
	v_mfma_f32_16x16x32_bf16 v[90:93], v[176:179], v[196:199], v[90:93]
	v_mfma_f32_16x16x32_bf16 v[78:81], v[164:167], v[204:207], v[78:81]
	v_mfma_f32_16x16x32_bf16 v[74:77], v[176:179], v[204:207], v[74:77]
	v_mfma_f32_16x16x32_bf16 v[70:73], v[164:167], v[212:215], v[70:73]
	v_mfma_f32_16x16x32_bf16 v[66:69], v[176:179], v[212:215], v[66:69]
	s_setprio 0
	s_barrier
	s_mov_b32 m0, s71
	v_lshl_add_u64 v[216:217], s[46:47], 0, v[0:1]
	s_add_u32 s28, s46, 0x40000
	ds_read_b128 v[182:185], v141 offset:16384
	ds_read_b128 v[188:191], v141 offset:17408
	ds_read_b128 v[192:195], v141 offset:18432
	ds_read_b128 v[196:199], v141 offset:19456
	ds_read_b128 v[200:203], v141 offset:20480
	ds_read_b128 v[204:207], v141 offset:21504
	ds_read_b128 v[208:211], v141 offset:22528
	ds_read_b128 v[212:215], v141 offset:23552
	global_load_lds_dwordx4 v[216:217], off
	v_lshl_add_u64 v[218:219], s[46:47], 0, v[130:131]
	s_mov_b32 m0, s72
	s_addc_u32 s29, s47, 0
	global_load_lds_dwordx4 v[218:219], off
	v_lshl_add_u64 v[220:221], s[28:29], 0, v[0:1]
	s_mov_b32 m0, s73
	v_lshl_add_u64 v[222:223], s[68:69], 0, v[132:133]
	global_load_lds_dwordx4 v[220:221], off
	v_lshl_add_u64 v[220:221], s[28:29], 0, v[130:131]
	s_mov_b32 m0, s74
	s_nop 0
	global_load_lds_dwordx4 v[220:221], off
	v_lshl_add_u64 v[220:221], s[68:69], 0, v[134:135]
	s_mov_b32 m0, s70
	s_nop 0
	global_load_lds_dwordx4 v[220:221], off
	s_mov_b32 m0, s75
	s_nop 0
	global_load_lds_dwordx4 v[222:223], off
	s_waitcnt vmcnt(8)
	s_waitcnt lgkmcnt(0)
	s_barrier
; #define G_STAGE(bufoff, gbase, voff) do { _Pragma("unroll") for (int _i = 0; _i < 2; ++_i) \
;         __builtin_amdgcn_global_load_lds((const unsigned*)((const char*)(gbase) + (voff)[_i]), (LAS unsigned*)(lds + (bufoff) + ldsw + _i * 8192), 16, 0, 0); } while (0)
; #define G_LDA(dst, b, h) do { _Pragma("unroll") for (int m = 0; m < 4; ++m) _Pragma("unroll") for (int k = 0; k < 2; ++k) dst[m][k] = *(const LAS bf16x8*)(lds + G_SA(b, h) + aoff + m * 2048 + k * 1024); } while (0)
; #define G_LDB(dst, b, h) do { _Pragma("unroll") for (int n = 0; n < 2; ++n) _Pragma("unroll") for (int k = 0; k < 2; ++k) dst[n][k] = *(const LAS bf16x8*)(lds + G_SB(b, h) + boff + n * 2048 + k * 1024); } while (0)
; #define G_MMA(ai, bj, At, Bt_) do { __builtin_amdgcn_s_setprio(1); _Pragma("unroll") for (int m = 0; m < 4; ++m) _Pragma("unroll") for (int n = 0; n < 2; ++n) _Pragma("unroll") for (int k = 0; k < 2; ++k) \
;         acc[ai][bj][m][n] = __builtin_amdgcn_mfma_f32_16x16x32_bf16(Bt_[n][k], At[m][k], acc[ai][bj][m][n], 0, 0, 0); __builtin_amdgcn_s_setprio(0); } while (0)
; #define G_WAIT_V(n) asm volatile("s_waitcnt vmcnt(" #n ")" ::: "memory")
; #define G_WAIT_L(n) asm volatile("s_waitcnt lgkmcnt(" #n ")" ::: "memory")
; #define G_BAR __builtin_amdgcn_s_barrier()
; #define G_SCHED __builtin_amdgcn_sched_barrier(0)
; template <int NSTORE, class TF, class F>
; DEVI void gemm_run(const bf16_t* __restrict__ A, int lda, const bf16_t* __restrict__ Bt, int ldb, int K, bf16_t* shm, TF&& tile, F&& emit) {
;     ...
;             G_WAIT_V(8); G_WAIT_L(0); G_BAR; G_MMA(1, 0, At, B0); G_MMA(1, 1, At, B1); G_BAR; G_SCHED;
;             G_LDB(B0, 1, 0); G_LDB(B1, 1, 1); G_SCHED; G_LDA(At, 1, 0); G_STAGE(G_SA(0, 1), a2 + hstepA, voffA);
;             G_WAIT_V(8); G_WAIT_L(0); G_BAR; G_MMA(0, 0, At, B0); G_MMA(0, 1, At, B1); G_BAR; G_SCHED;
	s_setprio 1
	s_waitcnt lgkmcnt(0)
	v_mfma_f32_16x16x32_bf16 v[62:65], v[144:147], v[182:185], v[62:65]
	v_mfma_f32_16x16x32_bf16 v[58:61], v[152:155], v[182:185], v[58:61]
	v_mfma_f32_16x16x32_bf16 v[54:57], v[144:147], v[192:195], v[54:57]
	v_mfma_f32_16x16x32_bf16 v[50:53], v[152:155], v[192:195], v[50:53]
	v_mfma_f32_16x16x32_bf16 v[38:41], v[144:147], v[200:203], v[38:41]
	v_mfma_f32_16x16x32_bf16 v[34:37], v[152:155], v[200:203], v[34:37]
	v_mfma_f32_16x16x32_bf16 v[22:25], v[144:147], v[208:211], v[22:25]
	v_mfma_f32_16x16x32_bf16 v[18:21], v[152:155], v[208:211], v[18:21]
	v_mfma_f32_16x16x32_bf16 v[62:65], v[148:151], v[188:191], v[62:65]
	v_mfma_f32_16x16x32_bf16 v[58:61], v[156:159], v[188:191], v[58:61]
	v_mfma_f32_16x16x32_bf16 v[54:57], v[148:151], v[196:199], v[54:57]
	v_mfma_f32_16x16x32_bf16 v[50:53], v[156:159], v[196:199], v[50:53]
	v_mfma_f32_16x16x32_bf16 v[38:41], v[148:151], v[204:207], v[38:41]
	v_mfma_f32_16x16x32_bf16 v[34:37], v[156:159], v[204:207], v[34:37]
	v_mfma_f32_16x16x32_bf16 v[22:25], v[148:151], v[212:215], v[22:25]
	v_mfma_f32_16x16x32_bf16 v[18:21], v[156:159], v[212:215], v[18:21]
	v_mfma_f32_16x16x32_bf16 v[46:49], v[160:163], v[182:185], v[46:49]
	v_mfma_f32_16x16x32_bf16 v[42:45], v[168:171], v[182:185], v[42:45]
	v_mfma_f32_16x16x32_bf16 v[30:33], v[160:163], v[192:195], v[30:33]
	v_mfma_f32_16x16x32_bf16 v[26:29], v[168:171], v[192:195], v[26:29]
	v_mfma_f32_16x16x32_bf16 v[14:17], v[160:163], v[200:203], v[14:17]
	v_mfma_f32_16x16x32_bf16 v[10:13], v[168:171], v[200:203], v[10:13]
	v_mfma_f32_16x16x32_bf16 v[6:9], v[160:163], v[208:211], v[6:9]
	v_mfma_f32_16x16x32_bf16 v[2:5], v[168:171], v[208:211], v[2:5]
	v_mfma_f32_16x16x32_bf16 v[46:49], v[164:167], v[188:191], v[46:49]
	v_mfma_f32_16x16x32_bf16 v[42:45], v[176:179], v[188:191], v[42:45]
	v_mfma_f32_16x16x32_bf16 v[30:33], v[164:167], v[196:199], v[30:33]
	v_mfma_f32_16x16x32_bf16 v[26:29], v[176:179], v[196:199], v[26:29]
	v_mfma_f32_16x16x32_bf16 v[14:17], v[164:167], v[204:207], v[14:17]
	v_mfma_f32_16x16x32_bf16 v[10:13], v[176:179], v[204:207], v[10:13]
	v_mfma_f32_16x16x32_bf16 v[6:9], v[164:167], v[212:215], v[6:9]
	v_mfma_f32_16x16x32_bf16 v[2:5], v[176:179], v[212:215], v[2:5]
	s_setprio 0
	s_barrier
	v_or_b32_e32 v144, 0x18000, v142
	v_add_u32_e32 v148, 0x18400, v142
	v_add_u32_e32 v152, 0x18800, v142
	v_add_u32_e32 v156, 0x18c00, v142
	v_or_b32_e32 v160, 0x1c000, v142
	v_add_u32_e32 v164, 0x1c400, v142
	v_add_u32_e32 v168, 0x1c800, v142
	v_add_u32_e32 v176, 0x1cc00, v142
	ds_read_b128 v[144:147], v144
	ds_read_b128 v[148:151], v148
	ds_read_b128 v[152:155], v152
	ds_read_b128 v[156:159], v156
	ds_read_b128 v[160:163], v160
	ds_read_b128 v[164:167], v164
	ds_read_b128 v[168:171], v168
	ds_read_b128 v[176:179], v176
	s_add_u32 s28, s68, 0x40000
	s_addc_u32 s29, s69, 0
	s_mov_b32 m0, s76
	v_lshl_add_u64 v[224:225], s[28:29], 0, v[134:135]
	ds_read_b128 v[182:185], v141 offset:32768
	ds_read_b128 v[188:191], v141 offset:33792
	ds_read_b128 v[192:195], v141 offset:34816
	ds_read_b128 v[196:199], v141 offset:35840
	ds_read_b128 v[200:203], v141 offset:36864
	ds_read_b128 v[204:207], v141 offset:37888
	ds_read_b128 v[208:211], v141 offset:38912
	ds_read_b128 v[212:215], v141 offset:39936
	global_load_lds_dwordx4 v[224:225], off
	v_lshl_add_u64 v[224:225], s[28:29], 0, v[132:133]
	s_mov_b32 m0, s77
	s_nop 0
	global_load_lds_dwordx4 v[224:225], off
	s_waitcnt vmcnt(8)
	s_waitcnt lgkmcnt(0)
	s_barrier
	s_setprio 1
	s_waitcnt lgkmcnt(0)
	v_mfma_f32_16x16x32_bf16 v[126:129], v[144:147], v[182:185], v[126:129]
	v_mfma_f32_16x16x32_bf16 v[122:125], v[152:155], v[182:185], v[122:125]
	v_mfma_f32_16x16x32_bf16 v[118:121], v[144:147], v[192:195], v[118:121]
	v_mfma_f32_16x16x32_bf16 v[114:117], v[152:155], v[192:195], v[114:117]
	v_mfma_f32_16x16x32_bf16 v[102:105], v[144:147], v[200:203], v[102:105]
	v_mfma_f32_16x16x32_bf16 v[98:101], v[152:155], v[200:203], v[98:101]
	v_mfma_f32_16x16x32_bf16 v[86:89], v[144:147], v[208:211], v[86:89]
	v_mfma_f32_16x16x32_bf16 v[82:85], v[152:155], v[208:211], v[82:85]
	v_mfma_f32_16x16x32_bf16 v[126:129], v[148:151], v[188:191], v[126:129]
	v_mfma_f32_16x16x32_bf16 v[122:125], v[156:159], v[188:191], v[122:125]
	v_mfma_f32_16x16x32_bf16 v[118:121], v[148:151], v[196:199], v[118:121]
	v_mfma_f32_16x16x32_bf16 v[114:117], v[156:159], v[196:199], v[114:117]
	v_mfma_f32_16x16x32_bf16 v[102:105], v[148:151], v[204:207], v[102:105]
	v_mfma_f32_16x16x32_bf16 v[98:101], v[156:159], v[204:207], v[98:101]
	v_mfma_f32_16x16x32_bf16 v[86:89], v[148:151], v[212:215], v[86:89]
	v_mfma_f32_16x16x32_bf16 v[82:85], v[156:159], v[212:215], v[82:85]
	v_mfma_f32_16x16x32_bf16 v[110:113], v[160:163], v[182:185], v[110:113]
	v_mfma_f32_16x16x32_bf16 v[106:109], v[168:171], v[182:185], v[106:109]
	v_mfma_f32_16x16x32_bf16 v[94:97], v[160:163], v[192:195], v[94:97]
	v_mfma_f32_16x16x32_bf16 v[90:93], v[168:171], v[192:195], v[90:93]
	v_mfma_f32_16x16x32_bf16 v[78:81], v[160:163], v[200:203], v[78:81]
	v_mfma_f32_16x16x32_bf16 v[74:77], v[168:171], v[200:203], v[74:77]
	v_mfma_f32_16x16x32_bf16 v[70:73], v[160:163], v[208:211], v[70:73]
	v_mfma_f32_16x16x32_bf16 v[66:69], v[168:171], v[208:211], v[66:69]
	v_mfma_f32_16x16x32_bf16 v[110:113], v[164:167], v[188:191], v[110:113]
	v_mfma_f32_16x16x32_bf16 v[106:109], v[176:179], v[188:191], v[106:109]
	v_mfma_f32_16x16x32_bf16 v[94:97], v[164:167], v[196:199], v[94:97]
	v_mfma_f32_16x16x32_bf16 v[90:93], v[176:179], v[196:199], v[90:93]
	v_mfma_f32_16x16x32_bf16 v[78:81], v[164:167], v[204:207], v[78:81]
	v_mfma_f32_16x16x32_bf16 v[74:77], v[176:179], v[204:207], v[74:77]
	v_mfma_f32_16x16x32_bf16 v[70:73], v[164:167], v[212:215], v[70:73]
	v_mfma_f32_16x16x32_bf16 v[66:69], v[176:179], v[212:215], v[66:69]
	s_setprio 0
	s_barrier
; #define G_STAGE(bufoff, gbase, voff) do { _Pragma("unroll") for (int _i = 0; _i < 2; ++_i) \
;         __builtin_amdgcn_global_load_lds((const unsigned*)((const char*)(gbase) + (voff)[_i]), (LAS unsigned*)(lds + (bufoff) + ldsw + _i * 8192), 16, 0, 0); } while (0)
; #define G_LDA(dst, b, h) do { _Pragma("unroll") for (int m = 0; m < 4; ++m) _Pragma("unroll") for (int k = 0; k < 2; ++k) dst[m][k] = *(const LAS bf16x8*)(lds + G_SA(b, h) + aoff + m * 2048 + k * 1024); } while (0)
; #define G_MMA(ai, bj, At, Bt_) do { __builtin_amdgcn_s_setprio(1); _Pragma("unroll") for (int m = 0; m < 4; ++m) _Pragma("unroll") for (int n = 0; n < 2; ++n) _Pragma("unroll") for (int k = 0; k < 2; ++k) \
;         acc[ai][bj][m][n] = __builtin_amdgcn_mfma_f32_16x16x32_bf16(Bt_[n][k], At[m][k], acc[ai][bj][m][n], 0, 0, 0); __builtin_amdgcn_s_setprio(0); } while (0)
; #define G_WAIT_V(n) asm volatile("s_waitcnt vmcnt(" #n ")" ::: "memory")
; #define G_WAIT_L(n) asm volatile("s_waitcnt lgkmcnt(" #n ")" ::: "memory")
; #define G_BAR __builtin_amdgcn_s_barrier()
; #define G_SCHED __builtin_amdgcn_sched_barrier(0)
; template <int NSTORE, class TF, class F>
; DEVI void gemm_run(const bf16_t* __restrict__ A, int lda, const bf16_t* __restrict__ Bt, int ldb, int K, bf16_t* shm, TF&& tile, F&& emit) {
;     ...
;             G_LDA(At, 1, 1); G_STAGE(G_SB(1, 0), b3, voffB); G_STAGE(G_SB(1, 1), b3 + hstepB, voffB); G_STAGE(G_SA(1, 0), a3, voffA);
;             G_WAIT_V(8); G_WAIT_L(0); G_BAR; G_MMA(1, 0, At, B0); G_MMA(1, 1, At, B1); G_BAR; G_SCHED;
;         }
;         if (NSTORE != 0 && wr == 0) G_BAR;
	s_mov_b32 m0, s78
	v_lshl_add_u64 v[216:217], v[216:217], 0, s[30:31]
	s_add_u32 s28, s46, 0x40080
	ds_read_b128 v[182:185], v141 offset:49152
	ds_read_b128 v[188:191], v141 offset:50176
	ds_read_b128 v[192:195], v141 offset:51200
	ds_read_b128 v[196:199], v141 offset:52224
	ds_read_b128 v[200:203], v141 offset:53248
	ds_read_b128 v[204:207], v141 offset:54272
	ds_read_b128 v[208:211], v141 offset:55296
	ds_read_b128 v[212:215], v141 offset:56320
	global_load_lds_dwordx4 v[216:217], off
	v_lshl_add_u64 v[216:217], v[218:219], 0, s[30:31]
	s_mov_b32 m0, s26
	s_addc_u32 s29, s47, 0
	global_load_lds_dwordx4 v[216:217], off
	v_lshl_add_u64 v[216:217], s[28:29], 0, v[0:1]
	s_mov_b32 m0, s83
	s_nop 0
	global_load_lds_dwordx4 v[216:217], off
	v_lshl_add_u64 v[216:217], s[28:29], 0, v[130:131]
	s_mov_b32 m0, s94
	s_nop 0
	global_load_lds_dwordx4 v[216:217], off
	v_lshl_add_u64 v[216:217], v[220:221], 0, s[30:31]
	s_mov_b32 m0, s27
	s_nop 0
	global_load_lds_dwordx4 v[216:217], off
	v_lshl_add_u64 v[216:217], v[222:223], 0, s[30:31]
	s_mov_b32 m0, s79
	s_nop 0
	global_load_lds_dwordx4 v[216:217], off
	s_waitcnt vmcnt(8)
	s_waitcnt lgkmcnt(0)
	s_barrier
	s_setprio 1
	s_waitcnt lgkmcnt(0)
	v_mfma_f32_16x16x32_bf16 v[62:65], v[144:147], v[182:185], v[62:65]
	v_mfma_f32_16x16x32_bf16 v[58:61], v[152:155], v[182:185], v[58:61]
	v_mfma_f32_16x16x32_bf16 v[54:57], v[144:147], v[192:195], v[54:57]
	v_mfma_f32_16x16x32_bf16 v[50:53], v[152:155], v[192:195], v[50:53]
	v_mfma_f32_16x16x32_bf16 v[38:41], v[144:147], v[200:203], v[38:41]
	v_mfma_f32_16x16x32_bf16 v[34:37], v[152:155], v[200:203], v[34:37]
	v_mfma_f32_16x16x32_bf16 v[22:25], v[144:147], v[208:211], v[22:25]
	v_mfma_f32_16x16x32_bf16 v[18:21], v[152:155], v[208:211], v[18:21]
	v_mfma_f32_16x16x32_bf16 v[62:65], v[148:151], v[188:191], v[62:65]
	v_mfma_f32_16x16x32_bf16 v[58:61], v[156:159], v[188:191], v[58:61]
	v_mfma_f32_16x16x32_bf16 v[54:57], v[148:151], v[196:199], v[54:57]
	v_mfma_f32_16x16x32_bf16 v[50:53], v[156:159], v[196:199], v[50:53]
	v_mfma_f32_16x16x32_bf16 v[38:41], v[148:151], v[204:207], v[38:41]
	v_mfma_f32_16x16x32_bf16 v[34:37], v[156:159], v[204:207], v[34:37]
	v_mfma_f32_16x16x32_bf16 v[22:25], v[148:151], v[212:215], v[22:25]
	v_mfma_f32_16x16x32_bf16 v[18:21], v[156:159], v[212:215], v[18:21]
	v_mfma_f32_16x16x32_bf16 v[46:49], v[160:163], v[182:185], v[46:49]
	v_mfma_f32_16x16x32_bf16 v[42:45], v[168:171], v[182:185], v[42:45]
	v_mfma_f32_16x16x32_bf16 v[30:33], v[160:163], v[192:195], v[30:33]
	v_mfma_f32_16x16x32_bf16 v[26:29], v[168:171], v[192:195], v[26:29]
	v_mfma_f32_16x16x32_bf16 v[14:17], v[160:163], v[200:203], v[14:17]
	s_add_i32 s82, s82, 2
	v_mfma_f32_16x16x32_bf16 v[10:13], v[168:171], v[200:203], v[10:13]
	v_mfma_f32_16x16x32_bf16 v[6:9], v[160:163], v[208:211], v[6:9]
	s_add_u32 s44, s44, 0x100
	v_mfma_f32_16x16x32_bf16 v[2:5], v[168:171], v[208:211], v[2:5]
	v_mfma_f32_16x16x32_bf16 v[46:49], v[164:167], v[188:191], v[46:49]
	s_addc_u32 s45, s45, 0
	v_mfma_f32_16x16x32_bf16 v[42:45], v[176:179], v[188:191], v[42:45]
	v_mfma_f32_16x16x32_bf16 v[30:33], v[164:167], v[196:199], v[30:33]
	s_add_u32 s33, s33, 0x100
	v_mfma_f32_16x16x32_bf16 v[26:29], v[176:179], v[196:199], v[26:29]
	v_mfma_f32_16x16x32_bf16 v[14:17], v[164:167], v[204:207], v[14:17]
	s_addc_u32 s3, s3, 0
	v_mfma_f32_16x16x32_bf16 v[10:13], v[176:179], v[204:207], v[10:13]
	v_mfma_f32_16x16x32_bf16 v[6:9], v[164:167], v[212:215], v[6:9]
	s_cmp_gt_u32 s82, 13
	v_mfma_f32_16x16x32_bf16 v[2:5], v[176:179], v[212:215], v[2:5]
	s_setprio 0
	s_barrier
	s_cbranch_scc0 .LBB0_545
	s_and_b64 vcc, exec, s[14:15]
	s_cbranch_vccz .LBB0_548
	s_barrier

; #define G_STAGE(bufoff, gbase, voff) do { _Pragma("unroll") for (int _i = 0; _i < 2; ++_i) \
;         __builtin_amdgcn_global_load_lds((const unsigned*)((const char*)(gbase) + (voff)[_i]), (LAS unsigned*)(lds + (bufoff) + ldsw + _i * 8192), 16, 0, 0); } while (0)
; #define G_LDA(dst, b, h) do { _Pragma("unroll") for (int m = 0; m < 4; ++m) _Pragma("unroll") for (int k = 0; k < 2; ++k) dst[m][k] = *(const LAS bf16x8*)(lds + G_SA(b, h) + aoff + m * 2048 + k * 1024); } while (0)
; #define G_LDB(dst, b, h) do { _Pragma("unroll") for (int n = 0; n < 2; ++n) _Pragma("unroll") for (int k = 0; k < 2; ++k) dst[n][k] = *(const LAS bf16x8*)(lds + G_SB(b, h) + boff + n * 2048 + k * 1024); } while (0)
; #define G_MMA(ai, bj, At, Bt_) do { __builtin_amdgcn_s_setprio(1); _Pragma("unroll") for (int m = 0; m < 4; ++m) _Pragma("unroll") for (int n = 0; n < 2; ++n) _Pragma("unroll") for (int k = 0; k < 2; ++k) \
;         acc[ai][bj][m][n] = __builtin_amdgcn_mfma_f32_16x16x32_bf16(Bt_[n][k], At[m][k], acc[ai][bj][m][n], 0, 0, 0); __builtin_amdgcn_s_setprio(0); } while (0)
; #define G_WAIT_V(n) asm volatile("s_waitcnt vmcnt(" #n ")" ::: "memory")
; #define G_WAIT_L(n) asm volatile("s_waitcnt lgkmcnt(" #n ")" ::: "memory")
; #define G_BAR __builtin_amdgcn_s_barrier()
; #define G_SCHED __builtin_amdgcn_sched_barrier(0)
; template <int NSTORE, class TF, class F>
; DEVI void gemm_run(const bf16_t* __restrict__ A, int lda, const bf16_t* __restrict__ Bt, int ldb, int K, bf16_t* shm, TF&& tile, F&& emit) {
;     ...
;         for (int t = 0; t < nt; t += 2) {
;             const bool last = (t == nt - 2);
;             const char* a1 = cA + (size_t)(t + 1) * kstep;
;             const char* a2 = last ? nA : cA + (size_t)(t + 2) * kstep; const char* b2 = last ? nB : cB + (size_t)(t + 2) * kstep;
;             const char* a3 = a2 + kstep; const char* b3 = b2 + kstep;
;             G_LDB(B0, 0, 0); G_LDB(B1, 0, 1); G_SCHED; G_LDA(At, 0, 0); G_STAGE(G_SA(1, 1), a1 + hstepA, voffA);
;             G_WAIT_V(8); G_WAIT_L(0); G_BAR; G_MMA(0, 0, At, B0); G_MMA(0, 1, At, B1); G_BAR; G_SCHED;
;             G_LDA(At, 0, 1); G_STAGE(G_SB(0, 0), b2, voffB); G_STAGE(G_SB(0, 1), b2 + hstepB, voffB); G_STAGE(G_SA(0, 0), a2, voffA);
;             G_WAIT_V(8); G_WAIT_L(0); G_BAR; G_MMA(1, 0, At, B0); G_MMA(1, 1, At, B1); G_BAR; G_SCHED;
.LBB0_803:
	v_or_b32_e32 v144, 0x10000, v142
	v_add_u32_e32 v148, 0x10400, v142
	ds_read_b128 v[144:147], v144
	ds_read_b128 v[150:153], v148
	v_add_u32_e32 v148, 0x10800, v142
	v_add_u32_e32 v149, 0x10c00, v142
	ds_read_b128 v[154:157], v148
	ds_read_b128 v[158:161], v149
	v_or_b32_e32 v148, 0x14000, v142
	v_add_u32_e32 v149, 0x14400, v142
	ds_read_b128 v[162:165], v148
	ds_read_b128 v[188:191], v149
	v_add_u32_e32 v148, 0x14800, v142
	v_add_u32_e32 v149, 0x14c00, v142
	ds_read_b128 v[192:195], v148
	ds_read_b128 v[196:199], v149
	s_add_u32 s28, s40, 0xfffc0080
	s_addc_u32 s29, s41, -1
	s_cmp_eq_u32 s3, 12
	s_cselect_b32 s45, s9, s29
	s_cselect_b32 s44, s79, s28
	s_cselect_b32 s43, s15, s33
	s_cselect_b32 s42, s83, s94
	v_lshl_add_u64 v[148:149], s[40:41], 0, v[136:137]
	s_add_i32 m0, s46, 0xc000
	ds_read_b128 v[200:203], v141
	ds_read_b128 v[204:207], v141 offset:1024
	ds_read_b128 v[208:211], v141 offset:2048
	ds_read_b128 v[212:215], v141 offset:3072
	ds_read_b128 v[216:219], v141 offset:4096
	ds_read_b128 v[220:223], v141 offset:5120
	ds_read_b128 v[224:227], v141 offset:6144
	ds_read_b128 v[228:231], v141 offset:7168
	global_load_lds_dwordx4 v[148:149], off
	v_lshl_add_u64 v[148:149], s[40:41], 0, v[138:139]
	s_add_i32 m0, s46, 0xe000
	s_nop 0
	global_load_lds_dwordx4 v[148:149], off
	s_waitcnt vmcnt(8)
	s_waitcnt lgkmcnt(0)
	s_barrier
	s_setprio 1
	s_waitcnt lgkmcnt(0)
	v_mfma_f32_16x16x32_bf16 v[126:129], v[144:147], v[200:203], v[126:129]
	v_mfma_f32_16x16x32_bf16 v[122:125], v[154:157], v[200:203], v[122:125]
	v_mfma_f32_16x16x32_bf16 v[118:121], v[144:147], v[208:211], v[118:121]
	v_mfma_f32_16x16x32_bf16 v[114:117], v[154:157], v[208:211], v[114:117]
	v_mfma_f32_16x16x32_bf16 v[102:105], v[144:147], v[216:219], v[102:105]
	v_mfma_f32_16x16x32_bf16 v[98:101], v[154:157], v[216:219], v[98:101]
	v_mfma_f32_16x16x32_bf16 v[86:89], v[144:147], v[224:227], v[86:89]
	v_mfma_f32_16x16x32_bf16 v[82:85], v[154:157], v[224:227], v[82:85]
	v_mfma_f32_16x16x32_bf16 v[126:129], v[150:153], v[204:207], v[126:129]
	v_mfma_f32_16x16x32_bf16 v[122:125], v[158:161], v[204:207], v[122:125]
	v_mfma_f32_16x16x32_bf16 v[118:121], v[150:153], v[212:215], v[118:121]
	v_mfma_f32_16x16x32_bf16 v[114:117], v[158:161], v[212:215], v[114:117]
	v_mfma_f32_16x16x32_bf16 v[102:105], v[150:153], v[220:223], v[102:105]
	v_mfma_f32_16x16x32_bf16 v[98:101], v[158:161], v[220:223], v[98:101]
	v_mfma_f32_16x16x32_bf16 v[86:89], v[150:153], v[228:231], v[86:89]
	v_mfma_f32_16x16x32_bf16 v[82:85], v[158:161], v[228:231], v[82:85]
	v_mfma_f32_16x16x32_bf16 v[110:113], v[162:165], v[200:203], v[110:113]
	v_mfma_f32_16x16x32_bf16 v[106:109], v[192:195], v[200:203], v[106:109]
	v_mfma_f32_16x16x32_bf16 v[94:97], v[162:165], v[208:211], v[94:97]
	v_mfma_f32_16x16x32_bf16 v[90:93], v[192:195], v[208:211], v[90:93]
	v_mfma_f32_16x16x32_bf16 v[78:81], v[162:165], v[216:219], v[78:81]
	v_mfma_f32_16x16x32_bf16 v[74:77], v[192:195], v[216:219], v[74:77]
	v_mfma_f32_16x16x32_bf16 v[70:73], v[162:165], v[224:227], v[70:73]
	v_mfma_f32_16x16x32_bf16 v[66:69], v[192:195], v[224:227], v[66:69]
	v_mfma_f32_16x16x32_bf16 v[110:113], v[188:191], v[204:207], v[110:113]
	v_mfma_f32_16x16x32_bf16 v[106:109], v[196:199], v[204:207], v[106:109]
	v_mfma_f32_16x16x32_bf16 v[94:97], v[188:191], v[212:215], v[94:97]
	v_mfma_f32_16x16x32_bf16 v[90:93], v[196:199], v[212:215], v[90:93]
	v_mfma_f32_16x16x32_bf16 v[78:81], v[188:191], v[220:223], v[78:81]
	v_mfma_f32_16x16x32_bf16 v[74:77], v[196:199], v[220:223], v[74:77]
	v_mfma_f32_16x16x32_bf16 v[70:73], v[188:191], v[228:231], v[70:73]
	v_mfma_f32_16x16x32_bf16 v[66:69], v[196:199], v[228:231], v[66:69]
	s_setprio 0
	s_barrier
	s_mov_b32 m0, s47
	v_lshl_add_u64 v[148:149], s[42:43], 0, v[0:1]
	s_add_u32 vcc_lo, s42, 0x40000
	ds_read_b128 v[200:203], v141 offset:16384
	ds_read_b128 v[204:207], v141 offset:17408
	ds_read_b128 v[208:211], v141 offset:18432
	ds_read_b128 v[212:215], v141 offset:19456
	ds_read_b128 v[216:219], v141 offset:20480
	ds_read_b128 v[220:223], v141 offset:21504
	ds_read_b128 v[224:227], v141 offset:22528
	ds_read_b128 v[228:231], v141 offset:23552
	global_load_lds_dwordx4 v[148:149], off
	v_lshl_add_u64 v[166:167], s[42:43], 0, v[130:131]
	s_mov_b32 m0, s68
	s_addc_u32 vcc_hi, s43, 0
	global_load_lds_dwordx4 v[166:167], off
	v_lshl_add_u64 v[168:169], vcc, 0, v[0:1]
	s_mov_b32 m0, s69
	v_lshl_add_u64 v[170:171], s[44:45], 0, v[132:133]
	global_load_lds_dwordx4 v[168:169], off
	v_lshl_add_u64 v[168:169], vcc, 0, v[130:131]
	s_mov_b32 m0, s70
	s_nop 0
	global_load_lds_dwordx4 v[168:169], off
	v_lshl_add_u64 v[168:169], s[44:45], 0, v[134:135]
	s_mov_b32 m0, s46
	s_nop 0
	global_load_lds_dwordx4 v[168:169], off
	s_mov_b32 m0, s71
	s_nop 0
	global_load_lds_dwordx4 v[170:171], off
	s_waitcnt vmcnt(8)
	s_waitcnt lgkmcnt(0)
	s_barrier
; #define G_STAGE(bufoff, gbase, voff) do { _Pragma("unroll") for (int _i = 0; _i < 2; ++_i) \
;         __builtin_amdgcn_global_load_lds((const unsigned*)((const char*)(gbase) + (voff)[_i]), (LAS unsigned*)(lds + (bufoff) + ldsw + _i * 8192), 16, 0, 0); } while (0)
; #define G_LDA(dst, b, h) do { _Pragma("unroll") for (int m = 0; m < 4; ++m) _Pragma("unroll") for (int k = 0; k < 2; ++k) dst[m][k] = *(const LAS bf16x8*)(lds + G_SA(b, h) + aoff + m * 2048 + k * 1024); } while (0)
; #define G_LDB(dst, b, h) do { _Pragma("unroll") for (int n = 0; n < 2; ++n) _Pragma("unroll") for (int k = 0; k < 2; ++k) dst[n][k] = *(const LAS bf16x8*)(lds + G_SB(b, h) + boff + n * 2048 + k * 1024); } while (0)
; #define G_MMA(ai, bj, At, Bt_) do { __builtin_amdgcn_s_setprio(1); _Pragma("unroll") for (int m = 0; m < 4; ++m) _Pragma("unroll") for (int n = 0; n < 2; ++n) _Pragma("unroll") for (int k = 0; k < 2; ++k) \
;         acc[ai][bj][m][n] = __builtin_amdgcn_mfma_f32_16x16x32_bf16(Bt_[n][k], At[m][k], acc[ai][bj][m][n], 0, 0, 0); __builtin_amdgcn_s_setprio(0); } while (0)
; #define G_WAIT_V(n) asm volatile("s_waitcnt vmcnt(" #n ")" ::: "memory")
; #define G_WAIT_L(n) asm volatile("s_waitcnt lgkmcnt(" #n ")" ::: "memory")
; #define G_BAR __builtin_amdgcn_s_barrier()
; #define G_SCHED __builtin_amdgcn_sched_barrier(0)
; template <int NSTORE, class TF, class F>
; DEVI void gemm_run(const bf16_t* __restrict__ A, int lda, const bf16_t* __restrict__ Bt, int ldb, int K, bf16_t* shm, TF&& tile, F&& emit) {
;     ...
;             G_WAIT_V(8); G_WAIT_L(0); G_BAR; G_MMA(1, 0, At, B0); G_MMA(1, 1, At, B1); G_BAR; G_SCHED;
;             G_LDB(B0, 1, 0); G_LDB(B1, 1, 1); G_SCHED; G_LDA(At, 1, 0); G_STAGE(G_SA(0, 1), a2 + hstepA, voffA);
;             G_WAIT_V(8); G_WAIT_L(0); G_BAR; G_MMA(0, 0, At, B0); G_MMA(0, 1, At, B1); G_BAR; G_SCHED;
	s_setprio 1
	s_waitcnt lgkmcnt(0)
	v_mfma_f32_16x16x32_bf16 v[62:65], v[144:147], v[200:203], v[62:65]
	v_mfma_f32_16x16x32_bf16 v[58:61], v[154:157], v[200:203], v[58:61]
	v_mfma_f32_16x16x32_bf16 v[54:57], v[144:147], v[208:211], v[54:57]
	v_mfma_f32_16x16x32_bf16 v[50:53], v[154:157], v[208:211], v[50:53]
	v_mfma_f32_16x16x32_bf16 v[38:41], v[144:147], v[216:219], v[38:41]
	v_mfma_f32_16x16x32_bf16 v[34:37], v[154:157], v[216:219], v[34:37]
	v_mfma_f32_16x16x32_bf16 v[22:25], v[144:147], v[224:227], v[22:25]
	v_mfma_f32_16x16x32_bf16 v[18:21], v[154:157], v[224:227], v[18:21]
	v_mfma_f32_16x16x32_bf16 v[62:65], v[150:153], v[204:207], v[62:65]
	v_mfma_f32_16x16x32_bf16 v[58:61], v[158:161], v[204:207], v[58:61]
	v_mfma_f32_16x16x32_bf16 v[54:57], v[150:153], v[212:215], v[54:57]
	v_mfma_f32_16x16x32_bf16 v[50:53], v[158:161], v[212:215], v[50:53]
	v_mfma_f32_16x16x32_bf16 v[38:41], v[150:153], v[220:223], v[38:41]
	v_mfma_f32_16x16x32_bf16 v[34:37], v[158:161], v[220:223], v[34:37]
	v_mfma_f32_16x16x32_bf16 v[22:25], v[150:153], v[228:231], v[22:25]
	v_mfma_f32_16x16x32_bf16 v[18:21], v[158:161], v[228:231], v[18:21]
	v_mfma_f32_16x16x32_bf16 v[46:49], v[162:165], v[200:203], v[46:49]
	v_mfma_f32_16x16x32_bf16 v[42:45], v[192:195], v[200:203], v[42:45]
	v_mfma_f32_16x16x32_bf16 v[30:33], v[162:165], v[208:211], v[30:33]
	v_mfma_f32_16x16x32_bf16 v[26:29], v[192:195], v[208:211], v[26:29]
	v_mfma_f32_16x16x32_bf16 v[14:17], v[162:165], v[216:219], v[14:17]
	v_mfma_f32_16x16x32_bf16 v[10:13], v[192:195], v[216:219], v[10:13]
	v_mfma_f32_16x16x32_bf16 v[6:9], v[162:165], v[224:227], v[6:9]
	v_mfma_f32_16x16x32_bf16 v[2:5], v[192:195], v[224:227], v[2:5]
	v_mfma_f32_16x16x32_bf16 v[46:49], v[188:191], v[204:207], v[46:49]
	v_mfma_f32_16x16x32_bf16 v[42:45], v[196:199], v[204:207], v[42:45]
	v_mfma_f32_16x16x32_bf16 v[30:33], v[188:191], v[212:215], v[30:33]
	v_mfma_f32_16x16x32_bf16 v[26:29], v[196:199], v[212:215], v[26:29]
	v_mfma_f32_16x16x32_bf16 v[14:17], v[188:191], v[220:223], v[14:17]
	v_mfma_f32_16x16x32_bf16 v[10:13], v[196:199], v[220:223], v[10:13]
	v_mfma_f32_16x16x32_bf16 v[6:9], v[188:191], v[228:231], v[6:9]
	v_mfma_f32_16x16x32_bf16 v[2:5], v[196:199], v[228:231], v[2:5]
	s_setprio 0
	s_barrier
	v_or_b32_e32 v144, 0x18000, v142
	v_add_u32_e32 v150, 0x18400, v142
	v_add_u32_e32 v154, 0x18800, v142
	v_add_u32_e32 v158, 0x18c00, v142
	v_or_b32_e32 v162, 0x1c000, v142
	v_add_u32_e32 v176, 0x1c400, v142
	ds_read_b128 v[144:147], v144
	ds_read_b128 v[150:153], v150
	ds_read_b128 v[154:157], v154
	ds_read_b128 v[158:161], v158
	ds_read_b128 v[162:165], v162
	ds_read_b128 v[188:191], v176
	v_add_u32_e32 v176, 0x1c800, v142
	v_add_u32_e32 v177, 0x1cc00, v142
	ds_read_b128 v[192:195], v176
	ds_read_b128 v[196:199], v177
	s_add_u32 s44, s44, 0x40000
	s_addc_u32 s45, s45, 0
	s_mov_b32 m0, s72
	v_lshl_add_u64 v[176:177], s[44:45], 0, v[134:135]
	ds_read_b128 v[200:203], v141 offset:32768
	ds_read_b128 v[204:207], v141 offset:33792
	ds_read_b128 v[208:211], v141 offset:34816
	ds_read_b128 v[212:215], v141 offset:35840
	ds_read_b128 v[216:219], v141 offset:36864
	ds_read_b128 v[220:223], v141 offset:37888
	ds_read_b128 v[224:227], v141 offset:38912
	ds_read_b128 v[228:231], v141 offset:39936
	global_load_lds_dwordx4 v[176:177], off
	v_lshl_add_u64 v[176:177], s[44:45], 0, v[132:133]
	s_mov_b32 m0, s73
	s_nop 0
	global_load_lds_dwordx4 v[176:177], off
	s_waitcnt vmcnt(8)
	s_waitcnt lgkmcnt(0)
	s_barrier
	s_setprio 1
	s_waitcnt lgkmcnt(0)
	v_mfma_f32_16x16x32_bf16 v[126:129], v[144:147], v[200:203], v[126:129]
	v_mfma_f32_16x16x32_bf16 v[122:125], v[154:157], v[200:203], v[122:125]
	v_mfma_f32_16x16x32_bf16 v[118:121], v[144:147], v[208:211], v[118:121]
	v_mfma_f32_16x16x32_bf16 v[114:117], v[154:157], v[208:211], v[114:117]
	v_mfma_f32_16x16x32_bf16 v[102:105], v[144:147], v[216:219], v[102:105]
	v_mfma_f32_16x16x32_bf16 v[98:101], v[154:157], v[216:219], v[98:101]
	v_mfma_f32_16x16x32_bf16 v[86:89], v[144:147], v[224:227], v[86:89]
	v_mfma_f32_16x16x32_bf16 v[82:85], v[154:157], v[224:227], v[82:85]
	v_mfma_f32_16x16x32_bf16 v[126:129], v[150:153], v[204:207], v[126:129]
	v_mfma_f32_16x16x32_bf16 v[122:125], v[158:161], v[204:207], v[122:125]
	v_mfma_f32_16x16x32_bf16 v[118:121], v[150:153], v[212:215], v[118:121]
	v_mfma_f32_16x16x32_bf16 v[114:117], v[158:161], v[212:215], v[114:117]
	v_mfma_f32_16x16x32_bf16 v[102:105], v[150:153], v[220:223], v[102:105]
	v_mfma_f32_16x16x32_bf16 v[98:101], v[158:161], v[220:223], v[98:101]
	v_mfma_f32_16x16x32_bf16 v[86:89], v[150:153], v[228:231], v[86:89]
	v_mfma_f32_16x16x32_bf16 v[82:85], v[158:161], v[228:231], v[82:85]
	v_mfma_f32_16x16x32_bf16 v[110:113], v[162:165], v[200:203], v[110:113]
	v_mfma_f32_16x16x32_bf16 v[106:109], v[192:195], v[200:203], v[106:109]
	v_mfma_f32_16x16x32_bf16 v[94:97], v[162:165], v[208:211], v[94:97]
	v_mfma_f32_16x16x32_bf16 v[90:93], v[192:195], v[208:211], v[90:93]
	v_mfma_f32_16x16x32_bf16 v[78:81], v[162:165], v[216:219], v[78:81]
	v_mfma_f32_16x16x32_bf16 v[74:77], v[192:195], v[216:219], v[74:77]
	v_mfma_f32_16x16x32_bf16 v[70:73], v[162:165], v[224:227], v[70:73]
	v_mfma_f32_16x16x32_bf16 v[66:69], v[192:195], v[224:227], v[66:69]
	v_mfma_f32_16x16x32_bf16 v[110:113], v[188:191], v[204:207], v[110:113]
	v_mfma_f32_16x16x32_bf16 v[106:109], v[196:199], v[204:207], v[106:109]
	v_mfma_f32_16x16x32_bf16 v[94:97], v[188:191], v[212:215], v[94:97]
	v_mfma_f32_16x16x32_bf16 v[90:93], v[196:199], v[212:215], v[90:93]
	v_mfma_f32_16x16x32_bf16 v[78:81], v[188:191], v[220:223], v[78:81]
	v_mfma_f32_16x16x32_bf16 v[74:77], v[196:199], v[220:223], v[74:77]
	v_mfma_f32_16x16x32_bf16 v[70:73], v[188:191], v[228:231], v[70:73]
	v_mfma_f32_16x16x32_bf16 v[66:69], v[196:199], v[228:231], v[66:69]
	s_setprio 0
	s_barrier
; #define G_STAGE(bufoff, gbase, voff) do { _Pragma("unroll") for (int _i = 0; _i < 2; ++_i) \
;         __builtin_amdgcn_global_load_lds((const unsigned*)((const char*)(gbase) + (voff)[_i]), (LAS unsigned*)(lds + (bufoff) + ldsw + _i * 8192), 16, 0, 0); } while (0)
; #define G_LDA(dst, b, h) do { _Pragma("unroll") for (int m = 0; m < 4; ++m) _Pragma("unroll") for (int k = 0; k < 2; ++k) dst[m][k] = *(const LAS bf16x8*)(lds + G_SA(b, h) + aoff + m * 2048 + k * 1024); } while (0)
; #define G_MMA(ai, bj, At, Bt_) do { __builtin_amdgcn_s_setprio(1); _Pragma("unroll") for (int m = 0; m < 4; ++m) _Pragma("unroll") for (int n = 0; n < 2; ++n) _Pragma("unroll") for (int k = 0; k < 2; ++k) \
;         acc[ai][bj][m][n] = __builtin_amdgcn_mfma_f32_16x16x32_bf16(Bt_[n][k], At[m][k], acc[ai][bj][m][n], 0, 0, 0); __builtin_amdgcn_s_setprio(0); } while (0)
; #define G_WAIT_V(n) asm volatile("s_waitcnt vmcnt(" #n ")" ::: "memory")
; #define G_WAIT_L(n) asm volatile("s_waitcnt lgkmcnt(" #n ")" ::: "memory")
; #define G_BAR __builtin_amdgcn_s_barrier()
; #define G_SCHED __builtin_amdgcn_sched_barrier(0)
; template <int NSTORE, class TF, class F>
; DEVI void gemm_run(const bf16_t* __restrict__ A, int lda, const bf16_t* __restrict__ Bt, int ldb, int K, bf16_t* shm, TF&& tile, F&& emit) {
;     ...
;             G_LDA(At, 1, 1); G_STAGE(G_SB(1, 0), b3, voffB); G_STAGE(G_SB(1, 1), b3 + hstepB, voffB); G_STAGE(G_SA(1, 0), a3, voffA);
;             G_WAIT_V(8); G_WAIT_L(0); G_BAR; G_MMA(1, 0, At, B0); G_MMA(1, 1, At, B1); G_BAR; G_SCHED;
;         }
;         if (NSTORE != 0 && wr == 0) G_BAR;
	s_mov_b32 m0, s26
	v_lshl_add_u64 v[148:149], v[148:149], 0, s[30:31]
	s_add_u32 s42, s42, 0x40080
	ds_read_b128 v[200:203], v141 offset:49152
	ds_read_b128 v[204:207], v141 offset:50176
	ds_read_b128 v[208:211], v141 offset:51200
	ds_read_b128 v[212:215], v141 offset:52224
	ds_read_b128 v[216:219], v141 offset:53248
	ds_read_b128 v[220:223], v141 offset:54272
	ds_read_b128 v[224:227], v141 offset:55296
	ds_read_b128 v[228:231], v141 offset:56320
	global_load_lds_dwordx4 v[148:149], off
	v_lshl_add_u64 v[148:149], v[166:167], 0, s[30:31]
	s_mov_b32 m0, s27
	s_addc_u32 s43, s43, 0
	global_load_lds_dwordx4 v[148:149], off
	v_lshl_add_u64 v[148:149], s[42:43], 0, v[0:1]
	s_mov_b32 m0, s76
	s_nop 0
	global_load_lds_dwordx4 v[148:149], off
	v_lshl_add_u64 v[148:149], s[42:43], 0, v[130:131]
	s_mov_b32 m0, s77
	s_nop 0
	global_load_lds_dwordx4 v[148:149], off
	v_lshl_add_u64 v[148:149], v[168:169], 0, s[30:31]
	s_mov_b32 m0, s74
	s_nop 0
	global_load_lds_dwordx4 v[148:149], off
	v_lshl_add_u64 v[148:149], v[170:171], 0, s[30:31]
	s_mov_b32 m0, s75
	s_nop 0
	global_load_lds_dwordx4 v[148:149], off
	s_waitcnt vmcnt(8)
	s_waitcnt lgkmcnt(0)
	s_barrier
	s_setprio 1
	s_waitcnt lgkmcnt(0)
	v_mfma_f32_16x16x32_bf16 v[62:65], v[144:147], v[200:203], v[62:65]
	v_mfma_f32_16x16x32_bf16 v[58:61], v[154:157], v[200:203], v[58:61]
	v_mfma_f32_16x16x32_bf16 v[54:57], v[144:147], v[208:211], v[54:57]
	v_mfma_f32_16x16x32_bf16 v[50:53], v[154:157], v[208:211], v[50:53]
	v_mfma_f32_16x16x32_bf16 v[38:41], v[144:147], v[216:219], v[38:41]
	v_mfma_f32_16x16x32_bf16 v[34:37], v[154:157], v[216:219], v[34:37]
	v_mfma_f32_16x16x32_bf16 v[22:25], v[144:147], v[224:227], v[22:25]
	v_mfma_f32_16x16x32_bf16 v[18:21], v[154:157], v[224:227], v[18:21]
	v_mfma_f32_16x16x32_bf16 v[62:65], v[150:153], v[204:207], v[62:65]
	v_mfma_f32_16x16x32_bf16 v[58:61], v[158:161], v[204:207], v[58:61]
	v_mfma_f32_16x16x32_bf16 v[54:57], v[150:153], v[212:215], v[54:57]
	v_mfma_f32_16x16x32_bf16 v[50:53], v[158:161], v[212:215], v[50:53]
	v_mfma_f32_16x16x32_bf16 v[38:41], v[150:153], v[220:223], v[38:41]
	v_mfma_f32_16x16x32_bf16 v[34:37], v[158:161], v[220:223], v[34:37]
	v_mfma_f32_16x16x32_bf16 v[22:25], v[150:153], v[228:231], v[22:25]
	v_mfma_f32_16x16x32_bf16 v[18:21], v[158:161], v[228:231], v[18:21]
	v_mfma_f32_16x16x32_bf16 v[46:49], v[162:165], v[200:203], v[46:49]
	v_mfma_f32_16x16x32_bf16 v[42:45], v[192:195], v[200:203], v[42:45]
	v_mfma_f32_16x16x32_bf16 v[30:33], v[162:165], v[208:211], v[30:33]
	v_mfma_f32_16x16x32_bf16 v[26:29], v[192:195], v[208:211], v[26:29]
	v_mfma_f32_16x16x32_bf16 v[14:17], v[162:165], v[216:219], v[14:17]
	s_add_i32 s3, s3, 2
	v_mfma_f32_16x16x32_bf16 v[10:13], v[192:195], v[216:219], v[10:13]
	v_mfma_f32_16x16x32_bf16 v[6:9], v[162:165], v[224:227], v[6:9]
	s_add_u32 s40, s40, 0x100
	v_mfma_f32_16x16x32_bf16 v[2:5], v[192:195], v[224:227], v[2:5]
	v_mfma_f32_16x16x32_bf16 v[46:49], v[188:191], v[204:207], v[46:49]
	s_addc_u32 s41, s41, 0
	v_mfma_f32_16x16x32_bf16 v[42:45], v[196:199], v[204:207], v[42:45]
	v_mfma_f32_16x16x32_bf16 v[30:33], v[188:191], v[212:215], v[30:33]
	s_add_u32 s94, s94, 0x100
	v_mfma_f32_16x16x32_bf16 v[26:29], v[196:199], v[212:215], v[26:29]
	v_mfma_f32_16x16x32_bf16 v[14:17], v[188:191], v[220:223], v[14:17]
	s_addc_u32 s33, s33, 0
	v_mfma_f32_16x16x32_bf16 v[10:13], v[196:199], v[220:223], v[10:13]
	v_mfma_f32_16x16x32_bf16 v[6:9], v[188:191], v[228:231], v[6:9]
	s_cmp_gt_u32 s3, 13
	v_mfma_f32_16x16x32_bf16 v[2:5], v[196:199], v[228:231], v[2:5]
	s_setprio 0
	s_barrier
	s_cbranch_scc0 .LBB0_803
	s_and_b64 vcc, exec, s[6:7]
	s_cbranch_vccz .LBB0_806
	s_barrier
